# GEMM load segments: six LDS-DMA loads per K-iteration use scalar base plus 32-bit lane offset, dropping their 64-bit VALU address adds
# speedup vs baseline: 1.0063x; 1.0029x over previous
; #define WAIT_V(n) asm volatile("s_waitcnt vmcnt(" #n ")" ::: "memory")
; #define WAIT_L(n) asm volatile("s_waitcnt lgkmcnt(" #n ")" ::: "memory")
; #define BAR __builtin_amdgcn_s_barrier()
; #define SCHED __builtin_amdgcn_sched_barrier(0)
; template <class Get, class Epi>
; DI void gemm_stream(LAS unsigned char* lds, const int K, const int ld, Get get, Epi epi) {
;     ...
;             LDB(B0, 0, 0); SCHED; LDA(At, 0, 0); STAGE(SAo(1, 1), a1 + hstep);
;             WAIT_L(8); BAR; WAIT_L(0); MMA(0, 0, At, B0); BAR; SCHED;
;             LDB(B1, 0, 1); STAGE(SBo(0, 0), b2);
;             BAR; WAIT_L(0); MMA(0, 1, At, B1); BAR;
;             LDA(At, 0, 1); STAGE(SAo(0, 0), a2);
;             BAR; WAIT_L(0); MMA(1, 0, At, B0); BAR; SCHED;
;             STAGE(SBo(0, 1), b2 + hstep);
;             WAIT_V(6); BAR; MMA(1, 1, At, B1); BAR;
.LBB0_726:
	ds_read_b128 v[128:131], v167
	ds_read_b128 v[132:135], v167 offset:1024
	ds_read_b128 v[136:139], v167 offset:2048
	ds_read_b128 v[154:157], v167 offset:3072
	s_add_u32 s6, s4, 0xfff80080
	s_addc_u32 s7, s5, -1
	s_cmp_eq_u32 vcc_lo, 28
	s_cselect_b32 s63, s59, s7
	s_cselect_b32 s62, s58, s6
	s_cselect_b32 s7, s61, s55
	s_cselect_b32 s6, s60, s29
	s_add_i32 m0, s74, 0xc000
	ds_read_b128 v[158:161], v168
	ds_read_b128 v[162:165], v168 offset:1024
	ds_read_b128 v[170:173], v168 offset:2048
	ds_read_b128 v[174:177], v168 offset:3072
	ds_read_b128 v[178:181], v168 offset:4096
	ds_read_b128 v[182:185], v168 offset:5120
	ds_read_b128 v[186:189], v168 offset:6144
	ds_read_b128 v[190:193], v168 offset:7168
	global_load_lds_dwordx4 v148, s[4:5]
	s_add_i32 m0, s74, 0xe000
	s_nop 0
	global_load_lds_dwordx4 v150, s[4:5]
	s_waitcnt lgkmcnt(8)
	s_barrier
	s_waitcnt lgkmcnt(0)
	v_mfma_f32_16x16x32_bf16 v[124:127], v[128:131], v[158:161], v[124:127]
	v_mfma_f32_16x16x32_bf16 v[120:123], v[136:139], v[158:161], v[120:123]
	v_mfma_f32_16x16x32_bf16 v[112:115], v[128:131], v[170:173], v[112:115]
	v_mfma_f32_16x16x32_bf16 v[108:111], v[136:139], v[170:173], v[108:111]
	v_mfma_f32_16x16x32_bf16 v[100:103], v[128:131], v[178:181], v[100:103]
	v_mfma_f32_16x16x32_bf16 v[92:95], v[136:139], v[178:181], v[92:95]
	v_mfma_f32_16x16x32_bf16 v[84:87], v[128:131], v[186:189], v[84:87]
	v_mfma_f32_16x16x32_bf16 v[76:79], v[136:139], v[186:189], v[76:79]
	v_mfma_f32_16x16x32_bf16 v[124:127], v[132:135], v[162:165], v[124:127]
	v_mfma_f32_16x16x32_bf16 v[120:123], v[154:157], v[162:165], v[120:123]
	v_mfma_f32_16x16x32_bf16 v[112:115], v[132:135], v[174:177], v[112:115]
	v_mfma_f32_16x16x32_bf16 v[108:111], v[154:157], v[174:177], v[108:111]
	v_mfma_f32_16x16x32_bf16 v[100:103], v[132:135], v[182:185], v[100:103]
	v_mfma_f32_16x16x32_bf16 v[92:95], v[154:157], v[182:185], v[92:95]
	v_mfma_f32_16x16x32_bf16 v[84:87], v[132:135], v[190:193], v[84:87]
	v_mfma_f32_16x16x32_bf16 v[76:79], v[154:157], v[190:193], v[76:79]
	s_barrier
	s_add_i32 s86, s85, s35
	v_lshl_add_u64 v[140:141], s[6:7], 0, v[142:143]
	s_mov_b32 m0, s86
	ds_read_b128 v[194:197], v169
	ds_read_b128 v[198:201], v169 offset:1024
	ds_read_b128 v[202:205], v169 offset:2048
	ds_read_b128 v[208:211], v169 offset:3072
	global_load_lds_dwordx4 v[140:141], off
	v_lshl_add_u64 v[212:213], s[6:7], 0, v[144:145]
	s_add_i32 m0, s86, 0x2000
	s_nop 0
	global_load_lds_dwordx4 v[212:213], off
	s_barrier
	s_waitcnt lgkmcnt(0)
	v_mfma_f32_16x16x32_bf16 v[116:119], v[194:197], v[158:161], v[116:119]
	v_mfma_f32_16x16x32_bf16 v[104:107], v[202:205], v[158:161], v[104:107]
	v_mfma_f32_16x16x32_bf16 v[96:99], v[194:197], v[170:173], v[96:99]
	v_mfma_f32_16x16x32_bf16 v[88:91], v[202:205], v[170:173], v[88:91]
	v_mfma_f32_16x16x32_bf16 v[80:83], v[194:197], v[178:181], v[80:83]
	v_mfma_f32_16x16x32_bf16 v[72:75], v[202:205], v[178:181], v[72:75]
	v_mfma_f32_16x16x32_bf16 v[68:71], v[194:197], v[186:189], v[68:71]
	v_mfma_f32_16x16x32_bf16 v[64:67], v[202:205], v[186:189], v[64:67]
	v_mfma_f32_16x16x32_bf16 v[116:119], v[198:201], v[162:165], v[116:119]
	v_mfma_f32_16x16x32_bf16 v[104:107], v[208:211], v[162:165], v[104:107]
	v_mfma_f32_16x16x32_bf16 v[96:99], v[198:201], v[174:177], v[96:99]
	v_mfma_f32_16x16x32_bf16 v[88:91], v[208:211], v[174:177], v[88:91]
	v_mfma_f32_16x16x32_bf16 v[80:83], v[198:201], v[182:185], v[80:83]
	v_mfma_f32_16x16x32_bf16 v[72:75], v[208:211], v[182:185], v[72:75]
	v_mfma_f32_16x16x32_bf16 v[68:71], v[198:201], v[190:193], v[68:71]
	v_mfma_f32_16x16x32_bf16 v[64:67], v[208:211], v[190:193], v[64:67]
	s_barrier
	s_mov_b32 m0, s74
	v_lshl_add_u64 v[214:215], s[62:63], 0, v[142:143]
	ds_read_b128 v[158:161], v168 offset:16384
	ds_read_b128 v[162:165], v168 offset:17408
	ds_read_b128 v[170:173], v168 offset:18432
	ds_read_b128 v[174:177], v168 offset:19456
	ds_read_b128 v[178:181], v168 offset:20480
	ds_read_b128 v[182:185], v168 offset:21504
	ds_read_b128 v[186:189], v168 offset:22528
	ds_read_b128 v[190:193], v168 offset:23552
	global_load_lds_dwordx4 v[214:215], off
	v_lshl_add_u64 v[216:217], s[62:63], 0, v[144:145]
	s_mov_b32 m0, s75
	s_nop 0
	global_load_lds_dwordx4 v[216:217], off
	s_barrier
	s_waitcnt lgkmcnt(0)
	v_mfma_f32_16x16x32_bf16 v[60:63], v[128:131], v[158:161], v[60:63]
	v_mfma_f32_16x16x32_bf16 v[56:59], v[136:139], v[158:161], v[56:59]
	v_mfma_f32_16x16x32_bf16 v[52:55], v[128:131], v[170:173], v[52:55]
	v_mfma_f32_16x16x32_bf16 v[44:47], v[136:139], v[170:173], v[44:47]
	v_mfma_f32_16x16x32_bf16 v[36:39], v[128:131], v[178:181], v[36:39]
	v_mfma_f32_16x16x32_bf16 v[28:31], v[136:139], v[178:181], v[28:31]
	v_mfma_f32_16x16x32_bf16 v[20:23], v[128:131], v[186:189], v[20:23]
	v_mfma_f32_16x16x32_bf16 v[12:15], v[136:139], v[186:189], v[12:15]
	v_mfma_f32_16x16x32_bf16 v[60:63], v[132:135], v[162:165], v[60:63]
	v_mfma_f32_16x16x32_bf16 v[56:59], v[154:157], v[162:165], v[56:59]
	v_mfma_f32_16x16x32_bf16 v[52:55], v[132:135], v[174:177], v[52:55]
	v_mfma_f32_16x16x32_bf16 v[44:47], v[154:157], v[174:177], v[44:47]
	v_mfma_f32_16x16x32_bf16 v[36:39], v[132:135], v[182:185], v[36:39]
	v_mfma_f32_16x16x32_bf16 v[28:31], v[154:157], v[182:185], v[28:31]
	v_mfma_f32_16x16x32_bf16 v[20:23], v[132:135], v[190:193], v[20:23]
	v_mfma_f32_16x16x32_bf16 v[12:15], v[154:157], v[190:193], v[12:15]
	s_barrier
	s_add_u32 s86, s6, 0x80000
	s_addc_u32 s87, s7, 0
	s_add_i32 s88, s96, s35
	s_mov_b32 m0, s88
	s_nop 0
	global_load_lds_dwordx4 v142, s[86:87]
	s_add_i32 m0, s88, 0x2000
	s_nop 0
	global_load_lds_dwordx4 v144, s[86:87]
	s_waitcnt vmcnt(6)
	s_barrier
; #define WAIT_V(n) asm volatile("s_waitcnt vmcnt(" #n ")" ::: "memory")
; #define WAIT_L(n) asm volatile("s_waitcnt lgkmcnt(" #n ")" ::: "memory")
; #define BAR __builtin_amdgcn_s_barrier()
; #define SCHED __builtin_amdgcn_sched_barrier(0)
; template <class Get, class Epi>
; DI void gemm_stream(LAS unsigned char* lds, const int K, const int ld, Get get, Epi epi) {
;     ...
;             WAIT_V(6); BAR; MMA(1, 1, At, B1); BAR;
;             LDB(B0, 1, 0); SCHED; LDA(At, 1, 0); STAGE(SAo(0, 1), a2 + hstep);
;             WAIT_L(8); BAR; WAIT_L(0); MMA(0, 0, At, B0); BAR; SCHED;
;             LDB(B1, 1, 1); STAGE(SBo(1, 0), b3);
;             BAR; WAIT_L(0); MMA(0, 1, At, B1); BAR;
	v_mfma_f32_16x16x32_bf16 v[48:51], v[194:197], v[158:161], v[48:51]
	v_mfma_f32_16x16x32_bf16 v[40:43], v[202:205], v[158:161], v[40:43]
	v_mfma_f32_16x16x32_bf16 v[32:35], v[194:197], v[170:173], v[32:35]
	v_mfma_f32_16x16x32_bf16 v[24:27], v[202:205], v[170:173], v[24:27]
	v_mfma_f32_16x16x32_bf16 v[16:19], v[194:197], v[178:181], v[16:19]
	v_mfma_f32_16x16x32_bf16 v[8:11], v[202:205], v[178:181], v[8:11]
	v_mfma_f32_16x16x32_bf16 v[4:7], v[194:197], v[186:189], v[4:7]
	v_mfma_f32_16x16x32_bf16 v[0:3], v[202:205], v[186:189], v[0:3]
	v_mfma_f32_16x16x32_bf16 v[48:51], v[198:201], v[162:165], v[48:51]
	v_mfma_f32_16x16x32_bf16 v[40:43], v[208:211], v[162:165], v[40:43]
	v_mfma_f32_16x16x32_bf16 v[32:35], v[198:201], v[174:177], v[32:35]
	v_mfma_f32_16x16x32_bf16 v[24:27], v[208:211], v[174:177], v[24:27]
	v_mfma_f32_16x16x32_bf16 v[16:19], v[198:201], v[182:185], v[16:19]
	v_mfma_f32_16x16x32_bf16 v[8:11], v[208:211], v[182:185], v[8:11]
	v_mfma_f32_16x16x32_bf16 v[4:7], v[198:201], v[190:193], v[4:7]
	v_mfma_f32_16x16x32_bf16 v[0:3], v[208:211], v[190:193], v[0:3]
	s_add_i32 s86, 16, 0x18000
	v_add_u32_e32 v146, s86, v166
	s_barrier
	ds_read_b128 v[128:131], v146
	ds_read_b128 v[132:135], v146 offset:1024
	ds_read_b128 v[136:139], v146 offset:2048
	ds_read_b128 v[154:157], v146 offset:3072
	s_add_u32 s62, s62, 0x80000
	s_addc_u32 s63, s63, 0
	s_mov_b32 m0, s76
	ds_read_b128 v[158:161], v168 offset:32768
	ds_read_b128 v[162:165], v168 offset:33792
	ds_read_b128 v[170:173], v168 offset:34816
	ds_read_b128 v[174:177], v168 offset:35840
	ds_read_b128 v[178:181], v168 offset:36864
	ds_read_b128 v[182:185], v168 offset:37888
	ds_read_b128 v[186:189], v168 offset:38912
	ds_read_b128 v[190:193], v168 offset:39936
	global_load_lds_dwordx4 v142, s[62:63]
	s_mov_b32 m0, s77
	s_nop 0
	global_load_lds_dwordx4 v144, s[62:63]
	s_waitcnt lgkmcnt(8)
	s_barrier
	s_waitcnt lgkmcnt(0)
	v_mfma_f32_16x16x32_bf16 v[124:127], v[128:131], v[158:161], v[124:127]
	v_mfma_f32_16x16x32_bf16 v[120:123], v[136:139], v[158:161], v[120:123]
	v_mfma_f32_16x16x32_bf16 v[112:115], v[128:131], v[170:173], v[112:115]
	v_mfma_f32_16x16x32_bf16 v[108:111], v[136:139], v[170:173], v[108:111]
	v_mfma_f32_16x16x32_bf16 v[100:103], v[128:131], v[178:181], v[100:103]
	v_mfma_f32_16x16x32_bf16 v[92:95], v[136:139], v[178:181], v[92:95]
	v_mfma_f32_16x16x32_bf16 v[84:87], v[128:131], v[186:189], v[84:87]
	v_mfma_f32_16x16x32_bf16 v[76:79], v[136:139], v[186:189], v[76:79]
	v_mfma_f32_16x16x32_bf16 v[124:127], v[132:135], v[162:165], v[124:127]
	v_mfma_f32_16x16x32_bf16 v[120:123], v[154:157], v[162:165], v[120:123]
	v_mfma_f32_16x16x32_bf16 v[112:115], v[132:135], v[174:177], v[112:115]
	v_mfma_f32_16x16x32_bf16 v[108:111], v[154:157], v[174:177], v[108:111]
	v_mfma_f32_16x16x32_bf16 v[100:103], v[132:135], v[182:185], v[100:103]
	v_mfma_f32_16x16x32_bf16 v[92:95], v[154:157], v[182:185], v[92:95]
	v_mfma_f32_16x16x32_bf16 v[84:87], v[132:135], v[190:193], v[84:87]
	v_mfma_f32_16x16x32_bf16 v[76:79], v[154:157], v[190:193], v[76:79]
	s_barrier
	s_add_i32 s62, 16, 0x1c000
	s_add_i32 s63, s86, s35
	v_add_u32_e32 v146, s62, v166
	v_lshl_add_u64 v[140:141], v[140:141], 0, s[0:1]
	s_mov_b32 m0, s63
	ds_read_b128 v[194:197], v146
	ds_read_b128 v[198:201], v146 offset:1024
	ds_read_b128 v[202:205], v146 offset:2048
	ds_read_b128 v[208:211], v146 offset:3072
	global_load_lds_dwordx4 v[140:141], off
	v_lshl_add_u64 v[140:141], v[212:213], 0, s[0:1]
	s_add_i32 m0, s63, 0x2000
	s_nop 0
	global_load_lds_dwordx4 v[140:141], off
	s_barrier
	s_waitcnt lgkmcnt(0)
	v_mfma_f32_16x16x32_bf16 v[116:119], v[194:197], v[158:161], v[116:119]
	v_mfma_f32_16x16x32_bf16 v[104:107], v[202:205], v[158:161], v[104:107]
	v_mfma_f32_16x16x32_bf16 v[96:99], v[194:197], v[170:173], v[96:99]
	v_mfma_f32_16x16x32_bf16 v[88:91], v[202:205], v[170:173], v[88:91]
	v_mfma_f32_16x16x32_bf16 v[80:83], v[194:197], v[178:181], v[80:83]
	v_mfma_f32_16x16x32_bf16 v[72:75], v[202:205], v[178:181], v[72:75]
	v_mfma_f32_16x16x32_bf16 v[68:71], v[194:197], v[186:189], v[68:71]
	v_mfma_f32_16x16x32_bf16 v[64:67], v[202:205], v[186:189], v[64:67]
	v_mfma_f32_16x16x32_bf16 v[116:119], v[198:201], v[162:165], v[116:119]
	v_mfma_f32_16x16x32_bf16 v[104:107], v[208:211], v[162:165], v[104:107]
	v_mfma_f32_16x16x32_bf16 v[96:99], v[198:201], v[174:177], v[96:99]
	v_mfma_f32_16x16x32_bf16 v[88:91], v[208:211], v[174:177], v[88:91]
	v_mfma_f32_16x16x32_bf16 v[80:83], v[198:201], v[182:185], v[80:83]
	v_mfma_f32_16x16x32_bf16 v[72:75], v[208:211], v[182:185], v[72:75]
	v_mfma_f32_16x16x32_bf16 v[68:71], v[198:201], v[190:193], v[68:71]
	v_mfma_f32_16x16x32_bf16 v[64:67], v[208:211], v[190:193], v[64:67]
	s_barrier
; #define WAIT_V(n) asm volatile("s_waitcnt vmcnt(" #n ")" ::: "memory")
; #define WAIT_L(n) asm volatile("s_waitcnt lgkmcnt(" #n ")" ::: "memory")
; #define BAR __builtin_amdgcn_s_barrier()
; #define SCHED __builtin_amdgcn_sched_barrier(0)
; template <class Get, class Epi>
; DI void gemm_stream(LAS unsigned char* lds, const int K, const int ld, Get get, Epi epi) {
;     ...
;             LDA(At, 1, 1); STAGE(SAo(1, 0), a3);
;             BAR; WAIT_L(0); MMA(1, 0, At, B0); BAR; SCHED;
;             STAGE(SBo(1, 1), b3 + hstep);
;             WAIT_V(6); BAR; MMA(1, 1, At, B1); BAR;
;         }
;         epi(acc, cur);
; DI void phase_inproj0(const P& p, char* shm) {
;     ...
;         const int brow = u.pm * 256, pn = u.pn;
;         if (pn == 5) epi_T<64>(acc, 0, brow, (bf16_t*)(p.ws + O_VAT), 256, nullptr);
;         else if (pn < 4) epi_rope<128>(acc, p, brow, (bf16_t*)(p.ws + O_QA), 1024, pn * 256, 128, nullptr, 2);
;         else if (pn == 4) epi_rope<128>(acc, p, brow, (bf16_t*)(p.ws + O_KA), 256, 0, 128, nullptr, 2);
;         else if (pn < 8) epi_plain(acc, brow, (bf16_t*)(p.ws + O_QLAT), 512, (pn - 6) * 256, nullptr);
;         else if (pn == 8) epi_plain(acc, brow, (bf16_t*)(p.ws + O_KVLAT), 256, 0, nullptr);
;         else epi_rope<64>(acc, p, brow, (bf16_t*)(p.ws + O_KR), 64, 0, 64, nullptr, 1);
	s_mov_b32 m0, s80
	v_lshl_add_u64 v[140:141], v[214:215], 0, s[0:1]
	ds_read_b128 v[158:161], v168 offset:49152
	ds_read_b128 v[162:165], v168 offset:50176
	ds_read_b128 v[170:173], v168 offset:51200
	ds_read_b128 v[174:177], v168 offset:52224
	ds_read_b128 v[178:181], v168 offset:53248
	ds_read_b128 v[182:185], v168 offset:54272
	ds_read_b128 v[186:189], v168 offset:55296
	ds_read_b128 v[190:193], v168 offset:56320
	global_load_lds_dwordx4 v[140:141], off
	v_lshl_add_u64 v[140:141], v[216:217], 0, s[0:1]
	s_mov_b32 m0, s81
	s_nop 0
	global_load_lds_dwordx4 v[140:141], off
	s_barrier
	s_waitcnt lgkmcnt(0)
	v_mfma_f32_16x16x32_bf16 v[60:63], v[128:131], v[158:161], v[60:63]
	v_mfma_f32_16x16x32_bf16 v[56:59], v[136:139], v[158:161], v[56:59]
	v_mfma_f32_16x16x32_bf16 v[52:55], v[128:131], v[170:173], v[52:55]
	v_mfma_f32_16x16x32_bf16 v[44:47], v[136:139], v[170:173], v[44:47]
	v_mfma_f32_16x16x32_bf16 v[36:39], v[128:131], v[178:181], v[36:39]
	v_mfma_f32_16x16x32_bf16 v[28:31], v[136:139], v[178:181], v[28:31]
	v_mfma_f32_16x16x32_bf16 v[20:23], v[128:131], v[186:189], v[20:23]
	v_mfma_f32_16x16x32_bf16 v[12:15], v[136:139], v[186:189], v[12:15]
	v_mfma_f32_16x16x32_bf16 v[60:63], v[132:135], v[162:165], v[60:63]
	v_mfma_f32_16x16x32_bf16 v[56:59], v[154:157], v[162:165], v[56:59]
	v_mfma_f32_16x16x32_bf16 v[52:55], v[132:135], v[174:177], v[52:55]
	v_mfma_f32_16x16x32_bf16 v[44:47], v[154:157], v[174:177], v[44:47]
	v_mfma_f32_16x16x32_bf16 v[36:39], v[132:135], v[182:185], v[36:39]
	v_mfma_f32_16x16x32_bf16 v[28:31], v[154:157], v[182:185], v[28:31]
	v_mfma_f32_16x16x32_bf16 v[20:23], v[132:135], v[190:193], v[20:23]
	v_mfma_f32_16x16x32_bf16 v[12:15], v[154:157], v[190:193], v[12:15]
	s_barrier
	s_add_u32 s6, s6, 0x80080
	s_addc_u32 s7, s7, 0
	s_add_i32 s62, s62, s35
	s_mov_b32 m0, s62
	s_nop 0
	global_load_lds_dwordx4 v142, s[6:7]
	s_add_i32 m0, s62, 0x2000
	s_nop 0
	global_load_lds_dwordx4 v144, s[6:7]
	s_add_i32 vcc_lo, vcc_lo, 2
	s_add_u32 s4, s4, 0x100
	s_addc_u32 s5, s5, 0
	s_add_u32 s29, s29, 0x100
	s_addc_u32 s55, s55, 0
	s_cmp_gt_u32 vcc_lo, 29
	s_waitcnt vmcnt(6)
	s_barrier
	v_mfma_f32_16x16x32_bf16 v[48:51], v[194:197], v[158:161], v[48:51]
	v_mfma_f32_16x16x32_bf16 v[40:43], v[202:205], v[158:161], v[40:43]
	v_mfma_f32_16x16x32_bf16 v[32:35], v[194:197], v[170:173], v[32:35]
	v_mfma_f32_16x16x32_bf16 v[24:27], v[202:205], v[170:173], v[24:27]
	v_mfma_f32_16x16x32_bf16 v[16:19], v[194:197], v[178:181], v[16:19]
	v_mfma_f32_16x16x32_bf16 v[8:11], v[202:205], v[178:181], v[8:11]
	v_mfma_f32_16x16x32_bf16 v[4:7], v[194:197], v[186:189], v[4:7]
	v_mfma_f32_16x16x32_bf16 v[0:3], v[202:205], v[186:189], v[0:3]
	v_mfma_f32_16x16x32_bf16 v[48:51], v[198:201], v[162:165], v[48:51]
	v_mfma_f32_16x16x32_bf16 v[40:43], v[208:211], v[162:165], v[40:43]
	v_mfma_f32_16x16x32_bf16 v[32:35], v[198:201], v[174:177], v[32:35]
	v_mfma_f32_16x16x32_bf16 v[24:27], v[208:211], v[174:177], v[24:27]
	v_mfma_f32_16x16x32_bf16 v[16:19], v[198:201], v[182:185], v[16:19]
	v_mfma_f32_16x16x32_bf16 v[8:11], v[208:211], v[182:185], v[8:11]
	v_mfma_f32_16x16x32_bf16 v[4:7], v[198:201], v[190:193], v[4:7]
	v_mfma_f32_16x16x32_bf16 v[0:3], v[208:211], v[190:193], v[0:3]
	s_barrier
	s_cbranch_scc0 .LBB0_726
	s_lshl_b32 s29, s21, 8
	s_cmp_lg_u32 s28, 5
	s_mov_b64 s[4:5], -1
	s_cbranch_scc0 .LBB0_849
	s_cmp_gt_i32 s28, 3
	s_cbranch_scc0 .LBB0_814
	s_cmp_lg_u32 s28, 4
	s_cbranch_scc0 .LBB0_779
	s_cmp_gt_u32 s28, 7
	s_cbranch_scc0 .LBB0_776
	s_cmp_lg_u32 s28, 8
	s_cbranch_scc0 .LBB0_773
	s_mul_hi_i32 s4, s29, 0x78787879
	s_lshr_b32 s5, s4, 31
	s_ashr_i32 s4, s4, 11
	v_mov_b32_e32 v128, v206
	s_add_i32 s4, s4, s5
	s_mulk_i32 s4, 0x1100
	v_and_b32_e32 v129, 15, v128
	v_ashrrev_i32_e32 v130, 2, v128
	s_sub_i32 s55, s29, s4
	v_and_or_b32 v154, v130, s97, v129
	v_lshrrev_b32_e32 v129, 2, v128
	s_cmpk_gt_i32 s55, 0xff
	v_and_b32_e32 v129, 28, v129
	s_cselect_b64 s[4:5], -1, 0
	v_lshlrev_b32_e32 v146, 2, v129
	v_and_b32_e32 v128, 0x80, v128
	v_lshl_add_u64 v[138:139], s[14:15], 0, v[146:147]
	v_lshl_add_u64 v[140:141], s[12:13], 0, v[146:147]
	v_lshlrev_b32_e32 v146, 1, v129
	v_cmp_eq_u32_e64 s[6:7], 0, v128
	v_cndmask_b32_e64 v128, 0, 1, s[4:5]
	s_addk_i32 s55, 0xff00
	v_lshl_add_u64 v[136:137], s[10:11], 0, v[146:147]
	v_cmp_ne_u32_e64 s[4:5], 1, v128
	s_and_saveexec_b64 s[62:63], s[6:7]
	s_cbranch_execz .LBB0_737
	s_and_b64 vcc, exec, s[4:5]
	s_cbranch_vccnz .LBB0_735
	v_add_u32_e32 v128, s55, v154
	v_ashrrev_i32_e32 v129, 31, v128
	v_lshlrev_b64 v[128:129], 7, v[128:129]
	v_lshl_add_u64 v[132:133], v[138:139], 0, v[128:129]
	v_lshl_add_u64 v[128:129], v[140:141], 0, v[128:129]
	global_load_dwordx4 v[128:131], v[128:129], off
	s_nop 0
	global_load_dwordx4 v[132:135], v[132:133], off
	s_branch .LBB0_736

; #define WAIT_V(n) asm volatile("s_waitcnt vmcnt(" #n ")" ::: "memory")
; #define WAIT_L(n) asm volatile("s_waitcnt lgkmcnt(" #n ")" ::: "memory")
; #define BAR __builtin_amdgcn_s_barrier()
; #define SCHED __builtin_amdgcn_sched_barrier(0)
; template <class Get, class Epi>
; DI void gemm_stream(LAS unsigned char* lds, const int K, const int ld, Get get, Epi epi) {
;     ...
;             LDB(B0, 0, 0); SCHED; LDA(At, 0, 0); STAGE(SAo(1, 1), a1 + hstep);
;             WAIT_L(8); BAR; WAIT_L(0); MMA(0, 0, At, B0); BAR; SCHED;
;             LDB(B1, 0, 1); STAGE(SBo(0, 0), b2);
;             BAR; WAIT_L(0); MMA(0, 1, At, B1); BAR;
;             LDA(At, 0, 1); STAGE(SAo(0, 0), a2);
;             BAR; WAIT_L(0); MMA(1, 0, At, B0); BAR; SCHED;
;             STAGE(SBo(0, 1), b2 + hstep);
;             WAIT_V(6); BAR; MMA(1, 1, At, B1); BAR;
.LBB0_1238:
	ds_read_b128 v[128:131], v198
	ds_read_b128 v[132:135], v198 offset:1024
	ds_read_b128 v[136:139], v198 offset:2048
	ds_read_b128 v[140:143], v198 offset:3072
	s_add_u32 s8, s6, 0x100
	s_addc_u32 s9, s7, 0
	s_cmp_eq_u32 s18, 28
	s_cselect_b32 s13, s39, s9
	s_cselect_b32 s12, s38, s8
	s_cselect_b32 s11, s41, s17
	s_cselect_b32 s10, s40, s16
	s_mov_b32 m0, s74
	ds_read_b128 v[144:147], v199
	ds_read_b128 v[148:151], v199 offset:1024
	ds_read_b128 v[152:155], v199 offset:2048
	ds_read_b128 v[156:159], v199 offset:3072
	ds_read_b128 v[160:163], v199 offset:4096
	ds_read_b128 v[174:177], v199 offset:5120
	ds_read_b128 v[178:181], v199 offset:6144
	ds_read_b128 v[182:185], v199 offset:7168
	global_load_lds_dwordx4 v168, s[6:7]
	s_mov_b32 m0, s75
	s_nop 0
	global_load_lds_dwordx4 v170, s[6:7]
	s_waitcnt lgkmcnt(8)
	s_barrier
	s_waitcnt lgkmcnt(0)
	v_mfma_f32_16x16x32_bf16 v[124:127], v[128:131], v[144:147], v[124:127]
	v_mfma_f32_16x16x32_bf16 v[92:95], v[136:139], v[144:147], v[92:95]
	v_mfma_f32_16x16x32_bf16 v[120:123], v[128:131], v[152:155], v[120:123]
	v_mfma_f32_16x16x32_bf16 v[88:91], v[136:139], v[152:155], v[88:91]
	v_mfma_f32_16x16x32_bf16 v[116:119], v[128:131], v[160:163], v[116:119]
	v_mfma_f32_16x16x32_bf16 v[84:87], v[136:139], v[160:163], v[84:87]
	v_mfma_f32_16x16x32_bf16 v[112:115], v[128:131], v[178:181], v[112:115]
	v_mfma_f32_16x16x32_bf16 v[80:83], v[136:139], v[178:181], v[80:83]
	v_mfma_f32_16x16x32_bf16 v[124:127], v[132:135], v[148:151], v[124:127]
	v_mfma_f32_16x16x32_bf16 v[92:95], v[140:143], v[148:151], v[92:95]
	v_mfma_f32_16x16x32_bf16 v[120:123], v[132:135], v[156:159], v[120:123]
	v_mfma_f32_16x16x32_bf16 v[88:91], v[140:143], v[156:159], v[88:91]
	v_mfma_f32_16x16x32_bf16 v[116:119], v[132:135], v[174:177], v[116:119]
	v_mfma_f32_16x16x32_bf16 v[84:87], v[140:143], v[174:177], v[84:87]
	v_mfma_f32_16x16x32_bf16 v[112:115], v[132:135], v[182:185], v[112:115]
	v_mfma_f32_16x16x32_bf16 v[80:83], v[140:143], v[182:185], v[80:83]
	s_barrier
	s_mov_b32 m0, s80
	v_lshl_add_u64 v[204:205], s[10:11], 0, v[164:165]
	ds_read_b128 v[186:189], v200
	ds_read_b128 v[190:193], v200 offset:1024
	ds_read_b128 v[194:197], v200 offset:2048
	ds_read_b128 v[208:211], v200 offset:3072
	global_load_lds_dwordx4 v[204:205], off
	v_lshl_add_u64 v[212:213], s[10:11], 0, v[166:167]
	s_mov_b32 m0, s81
	s_nop 0
	global_load_lds_dwordx4 v[212:213], off
	s_barrier
	s_waitcnt lgkmcnt(0)
	v_mfma_f32_16x16x32_bf16 v[60:63], v[186:189], v[144:147], v[60:63]
	v_mfma_f32_16x16x32_bf16 v[28:31], v[194:197], v[144:147], v[28:31]
	v_mfma_f32_16x16x32_bf16 v[56:59], v[186:189], v[152:155], v[56:59]
	v_mfma_f32_16x16x32_bf16 v[24:27], v[194:197], v[152:155], v[24:27]
	v_mfma_f32_16x16x32_bf16 v[52:55], v[186:189], v[160:163], v[52:55]
	v_mfma_f32_16x16x32_bf16 v[20:23], v[194:197], v[160:163], v[20:23]
	v_mfma_f32_16x16x32_bf16 v[48:51], v[186:189], v[178:181], v[48:51]
	v_mfma_f32_16x16x32_bf16 v[16:19], v[194:197], v[178:181], v[16:19]
	v_mfma_f32_16x16x32_bf16 v[60:63], v[190:193], v[148:151], v[60:63]
	v_mfma_f32_16x16x32_bf16 v[28:31], v[208:211], v[148:151], v[28:31]
	v_mfma_f32_16x16x32_bf16 v[56:59], v[190:193], v[156:159], v[56:59]
	v_mfma_f32_16x16x32_bf16 v[24:27], v[208:211], v[156:159], v[24:27]
	v_mfma_f32_16x16x32_bf16 v[52:55], v[190:193], v[174:177], v[52:55]
	v_mfma_f32_16x16x32_bf16 v[20:23], v[208:211], v[174:177], v[20:23]
	v_mfma_f32_16x16x32_bf16 v[48:51], v[190:193], v[182:185], v[48:51]
	v_mfma_f32_16x16x32_bf16 v[16:19], v[208:211], v[182:185], v[16:19]
	s_barrier
	s_mov_b32 m0, s21
	v_lshl_add_u64 v[214:215], s[12:13], 0, v[164:165]
	ds_read_b128 v[144:147], v199 offset:16384
	ds_read_b128 v[148:151], v199 offset:17408
	ds_read_b128 v[152:155], v199 offset:18432
	ds_read_b128 v[156:159], v199 offset:19456
	ds_read_b128 v[160:163], v199 offset:20480
	ds_read_b128 v[174:177], v199 offset:21504
	ds_read_b128 v[178:181], v199 offset:22528
	ds_read_b128 v[182:185], v199 offset:23552
	global_load_lds_dwordx4 v[214:215], off
	v_lshl_add_u64 v[216:217], s[12:13], 0, v[166:167]
	s_mov_b32 m0, s58
	s_nop 0
	global_load_lds_dwordx4 v[216:217], off
	s_barrier
	s_waitcnt lgkmcnt(0)
	v_mfma_f32_16x16x32_bf16 v[108:111], v[128:131], v[144:147], v[108:111]
	v_mfma_f32_16x16x32_bf16 v[76:79], v[136:139], v[144:147], v[76:79]
	v_mfma_f32_16x16x32_bf16 v[104:107], v[128:131], v[152:155], v[104:107]
	v_mfma_f32_16x16x32_bf16 v[72:75], v[136:139], v[152:155], v[72:75]
	v_mfma_f32_16x16x32_bf16 v[100:103], v[128:131], v[160:163], v[100:103]
	v_mfma_f32_16x16x32_bf16 v[68:71], v[136:139], v[160:163], v[68:71]
	v_mfma_f32_16x16x32_bf16 v[96:99], v[128:131], v[178:181], v[96:99]
	v_mfma_f32_16x16x32_bf16 v[64:67], v[136:139], v[178:181], v[64:67]
	v_mfma_f32_16x16x32_bf16 v[108:111], v[132:135], v[148:151], v[108:111]
	v_mfma_f32_16x16x32_bf16 v[76:79], v[140:143], v[148:151], v[76:79]
	v_mfma_f32_16x16x32_bf16 v[104:107], v[132:135], v[156:159], v[104:107]
	v_mfma_f32_16x16x32_bf16 v[72:75], v[140:143], v[156:159], v[72:75]
	v_mfma_f32_16x16x32_bf16 v[100:103], v[132:135], v[174:177], v[100:103]
	v_mfma_f32_16x16x32_bf16 v[68:71], v[140:143], v[174:177], v[68:71]
	v_mfma_f32_16x16x32_bf16 v[96:99], v[132:135], v[182:185], v[96:99]
	v_mfma_f32_16x16x32_bf16 v[64:67], v[140:143], v[182:185], v[64:67]
	s_barrier
	s_add_u32 s6, s10, 0x80000
	s_addc_u32 s7, s11, 0
	s_mov_b32 m0, s82
	v_lshl_add_u64 v[128:129], s[6:7], 0, v[164:165]
	global_load_lds_dwordx4 v[128:129], off
	s_mov_b32 m0, s83
	s_nop 0
	global_load_lds_dwordx4 v166, s[6:7]
	s_waitcnt vmcnt(6)
	s_barrier
; #define WAIT_L(n) asm volatile("s_waitcnt lgkmcnt(" #n ")" ::: "memory")
; #define BAR __builtin_amdgcn_s_barrier()
; #define SCHED __builtin_amdgcn_sched_barrier(0)
; template <class Get, class Epi>
; DI void gemm_stream(LAS unsigned char* lds, const int K, const int ld, Get get, Epi epi) {
;     ...
;             LDB(B0, 1, 0); SCHED; LDA(At, 1, 0); STAGE(SAo(0, 1), a2 + hstep);
;             WAIT_L(8); BAR; WAIT_L(0); MMA(0, 0, At, B0); BAR; SCHED;
;             LDB(B1, 1, 1); STAGE(SBo(1, 0), b3);
;             BAR; WAIT_L(0); MMA(0, 1, At, B1); BAR;
;             LDA(At, 1, 1); STAGE(SAo(1, 0), a3);
;             BAR; WAIT_L(0); MMA(1, 0, At, B0); BAR; SCHED;
;             STAGE(SBo(1, 1), b3 + hstep);
	v_mfma_f32_16x16x32_bf16 v[44:47], v[186:189], v[144:147], v[44:47]
	v_mfma_f32_16x16x32_bf16 v[12:15], v[194:197], v[144:147], v[12:15]
	v_mfma_f32_16x16x32_bf16 v[40:43], v[186:189], v[152:155], v[40:43]
	v_mfma_f32_16x16x32_bf16 v[8:11], v[194:197], v[152:155], v[8:11]
	v_mfma_f32_16x16x32_bf16 v[36:39], v[186:189], v[160:163], v[36:39]
	v_mfma_f32_16x16x32_bf16 v[4:7], v[194:197], v[160:163], v[4:7]
	v_mfma_f32_16x16x32_bf16 v[32:35], v[186:189], v[178:181], v[32:35]
	v_mfma_f32_16x16x32_bf16 v[0:3], v[194:197], v[178:181], v[0:3]
	v_mfma_f32_16x16x32_bf16 v[44:47], v[190:193], v[148:151], v[44:47]
	v_mfma_f32_16x16x32_bf16 v[12:15], v[208:211], v[148:151], v[12:15]
	v_mfma_f32_16x16x32_bf16 v[40:43], v[190:193], v[156:159], v[40:43]
	v_mfma_f32_16x16x32_bf16 v[8:11], v[208:211], v[156:159], v[8:11]
	v_mfma_f32_16x16x32_bf16 v[36:39], v[190:193], v[174:177], v[36:39]
	v_mfma_f32_16x16x32_bf16 v[4:7], v[208:211], v[174:177], v[4:7]
	v_mfma_f32_16x16x32_bf16 v[32:35], v[190:193], v[182:185], v[32:35]
	v_mfma_f32_16x16x32_bf16 v[0:3], v[208:211], v[182:185], v[0:3]
	s_barrier
	ds_read_b128 v[128:131], v201
	ds_read_b128 v[132:135], v201 offset:1024
	ds_read_b128 v[136:139], v201 offset:2048
	ds_read_b128 v[140:143], v201 offset:3072
	s_add_u32 s6, s12, 0x80000
	s_addc_u32 s7, s13, 0
	s_mov_b32 m0, s59
	ds_read_b128 v[144:147], v199 offset:32768
	ds_read_b128 v[148:151], v199 offset:33792
	ds_read_b128 v[152:155], v199 offset:34816
	ds_read_b128 v[156:159], v199 offset:35840
	ds_read_b128 v[160:163], v199 offset:36864
	ds_read_b128 v[174:177], v199 offset:37888
	ds_read_b128 v[178:181], v199 offset:38912
	ds_read_b128 v[182:185], v199 offset:39936
	global_load_lds_dwordx4 v164, s[6:7]
	s_mov_b32 m0, s60
	s_nop 0
	global_load_lds_dwordx4 v166, s[6:7]
	s_waitcnt lgkmcnt(8)
	s_barrier
	s_waitcnt lgkmcnt(0)
	v_mfma_f32_16x16x32_bf16 v[124:127], v[128:131], v[144:147], v[124:127]
	v_mfma_f32_16x16x32_bf16 v[92:95], v[136:139], v[144:147], v[92:95]
	v_mfma_f32_16x16x32_bf16 v[120:123], v[128:131], v[152:155], v[120:123]
	v_mfma_f32_16x16x32_bf16 v[88:91], v[136:139], v[152:155], v[88:91]
	v_mfma_f32_16x16x32_bf16 v[116:119], v[128:131], v[160:163], v[116:119]
	v_mfma_f32_16x16x32_bf16 v[84:87], v[136:139], v[160:163], v[84:87]
	v_mfma_f32_16x16x32_bf16 v[112:115], v[128:131], v[178:181], v[112:115]
	v_mfma_f32_16x16x32_bf16 v[80:83], v[136:139], v[178:181], v[80:83]
	v_mfma_f32_16x16x32_bf16 v[124:127], v[132:135], v[148:151], v[124:127]
	v_mfma_f32_16x16x32_bf16 v[92:95], v[140:143], v[148:151], v[92:95]
	v_mfma_f32_16x16x32_bf16 v[120:123], v[132:135], v[156:159], v[120:123]
	v_mfma_f32_16x16x32_bf16 v[88:91], v[140:143], v[156:159], v[88:91]
	v_mfma_f32_16x16x32_bf16 v[116:119], v[132:135], v[174:177], v[116:119]
	v_mfma_f32_16x16x32_bf16 v[84:87], v[140:143], v[174:177], v[84:87]
	v_mfma_f32_16x16x32_bf16 v[112:115], v[132:135], v[182:185], v[112:115]
	v_mfma_f32_16x16x32_bf16 v[80:83], v[140:143], v[182:185], v[80:83]
	s_barrier
	s_mov_b32 m0, s85
	v_lshl_add_u64 v[204:205], v[204:205], 0, s[0:1]
	ds_read_b128 v[186:189], v202
	ds_read_b128 v[190:193], v202 offset:1024
	ds_read_b128 v[194:197], v202 offset:2048
	ds_read_b128 v[208:211], v202 offset:3072
	global_load_lds_dwordx4 v[204:205], off
	v_lshl_add_u64 v[204:205], v[212:213], 0, s[0:1]
	s_mov_b32 m0, s96
	s_nop 0
	global_load_lds_dwordx4 v[204:205], off
	s_barrier
	s_waitcnt lgkmcnt(0)
	v_mfma_f32_16x16x32_bf16 v[60:63], v[186:189], v[144:147], v[60:63]
	v_mfma_f32_16x16x32_bf16 v[28:31], v[194:197], v[144:147], v[28:31]
	v_mfma_f32_16x16x32_bf16 v[56:59], v[186:189], v[152:155], v[56:59]
	v_mfma_f32_16x16x32_bf16 v[24:27], v[194:197], v[152:155], v[24:27]
	v_mfma_f32_16x16x32_bf16 v[52:55], v[186:189], v[160:163], v[52:55]
	v_mfma_f32_16x16x32_bf16 v[20:23], v[194:197], v[160:163], v[20:23]
	v_mfma_f32_16x16x32_bf16 v[48:51], v[186:189], v[178:181], v[48:51]
	v_mfma_f32_16x16x32_bf16 v[16:19], v[194:197], v[178:181], v[16:19]
	v_mfma_f32_16x16x32_bf16 v[60:63], v[190:193], v[148:151], v[60:63]
	v_mfma_f32_16x16x32_bf16 v[28:31], v[208:211], v[148:151], v[28:31]
	v_mfma_f32_16x16x32_bf16 v[56:59], v[190:193], v[156:159], v[56:59]
	v_mfma_f32_16x16x32_bf16 v[24:27], v[208:211], v[156:159], v[24:27]
	v_mfma_f32_16x16x32_bf16 v[52:55], v[190:193], v[174:177], v[52:55]
	v_mfma_f32_16x16x32_bf16 v[20:23], v[208:211], v[174:177], v[20:23]
	v_mfma_f32_16x16x32_bf16 v[48:51], v[190:193], v[182:185], v[48:51]
	v_mfma_f32_16x16x32_bf16 v[16:19], v[208:211], v[182:185], v[16:19]
	s_barrier
	s_mov_b32 m0, s61
	v_lshl_add_u64 v[204:205], v[214:215], 0, s[0:1]
	ds_read_b128 v[144:147], v199 offset:49152
	ds_read_b128 v[148:151], v199 offset:50176
	ds_read_b128 v[152:155], v199 offset:51200
	ds_read_b128 v[156:159], v199 offset:52224
	ds_read_b128 v[160:163], v199 offset:53248
	ds_read_b128 v[174:177], v199 offset:54272
	ds_read_b128 v[178:181], v199 offset:55296
	ds_read_b128 v[182:185], v199 offset:56320
	global_load_lds_dwordx4 v[204:205], off
	v_lshl_add_u64 v[204:205], v[216:217], 0, s[0:1]
	s_mov_b32 m0, s62
	s_nop 0
	global_load_lds_dwordx4 v[204:205], off
	s_barrier
; #define WAIT_V(n) asm volatile("s_waitcnt vmcnt(" #n ")" ::: "memory")
; #define BAR __builtin_amdgcn_s_barrier()
; #define EPI_DONE do { } while (0)
; template <class Get, class Epi>
; DI void gemm_stream(LAS unsigned char* lds, const int K, const int ld, Get get, Epi epi) {
;     ...
;             STAGE(SBo(1, 1), b3 + hstep);
;             WAIT_V(6); BAR; MMA(1, 1, At, B1); BAR;
;         }
; DI void epi_resid(const Acc& acc, const P& p, int brow, int bcol, int layer, int gch, bool from_input) {
;     EPI_IDX
;     const float* gate = modv(p, layer, brow, gch);
; #pragma unroll
;     for (int bj = 0; bj < 2; ++bj)
; #pragma unroll
;         for (int n = 0; n < 2; ++n) {
;             const int c0 = bcol + bj * 128 + wc * 32 + n * 16 + fq * 4;
;             const f32x4 g = *(const f32x4*)(gate + c0);
;             f32x4 xv[2][4];
; #pragma unroll
;             for (int ai = 0; ai < 2; ++ai)
; #pragma unroll
;                 for (int m = 0; m < 4; ++m) {
;                     const int r = brow + ai * 128 + wr * 64 + m * 16 + fr;
;                     const float* sp = (from_input ? inrow(p, r) : xrow(p, r)) + c0;
;                     xv[ai][m] = *(const f32x4*)sp;
;                 }
;             __builtin_amdgcn_sched_barrier(0);
; #pragma unroll
;             for (int ai = 0; ai < 2; ++ai)
; #pragma unroll
;                 for (int m = 0; m < 4; ++m) {
;                     const int r = brow + ai * 128 + wr * 64 + m * 16 + fr;
;                     *(f32x4*)(xrow(p, r) + c0) = xv[ai][m] + g * acc[ai][bj][m][n];
;                 }
;             __builtin_amdgcn_sched_barrier(0);
;         }
;     EPI_DONE;
; }
	s_waitcnt lgkmcnt(0)
	v_mfma_f32_16x16x32_bf16 v[108:111], v[128:131], v[144:147], v[108:111]
	v_mfma_f32_16x16x32_bf16 v[76:79], v[136:139], v[144:147], v[76:79]
	v_mfma_f32_16x16x32_bf16 v[104:107], v[128:131], v[152:155], v[104:107]
	v_mfma_f32_16x16x32_bf16 v[72:75], v[136:139], v[152:155], v[72:75]
	v_mfma_f32_16x16x32_bf16 v[100:103], v[128:131], v[160:163], v[100:103]
	v_mfma_f32_16x16x32_bf16 v[68:71], v[136:139], v[160:163], v[68:71]
	v_mfma_f32_16x16x32_bf16 v[96:99], v[128:131], v[178:181], v[96:99]
	v_mfma_f32_16x16x32_bf16 v[64:67], v[136:139], v[178:181], v[64:67]
	v_mfma_f32_16x16x32_bf16 v[108:111], v[132:135], v[148:151], v[108:111]
	v_mfma_f32_16x16x32_bf16 v[76:79], v[140:143], v[148:151], v[76:79]
	v_mfma_f32_16x16x32_bf16 v[104:107], v[132:135], v[156:159], v[104:107]
	v_mfma_f32_16x16x32_bf16 v[72:75], v[140:143], v[156:159], v[72:75]
	v_mfma_f32_16x16x32_bf16 v[100:103], v[132:135], v[174:177], v[100:103]
	v_mfma_f32_16x16x32_bf16 v[68:71], v[140:143], v[174:177], v[68:71]
	v_mfma_f32_16x16x32_bf16 v[96:99], v[132:135], v[182:185], v[96:99]
	v_mfma_f32_16x16x32_bf16 v[64:67], v[140:143], v[182:185], v[64:67]
	s_barrier
	s_add_u32 s6, s10, 0x80080
	s_addc_u32 s7, s11, 0
	s_mov_b32 m0, s97
	v_lshl_add_u64 v[128:129], s[6:7], 0, v[164:165]
	global_load_lds_dwordx4 v[128:129], off
	s_add_i32 m0, s97, 0x2000
	s_nop 0
	global_load_lds_dwordx4 v166, s[6:7]
	s_add_i32 s18, s18, 2
	s_add_u32 s16, s16, 0x100
	s_addc_u32 s17, s17, 0
	s_cmp_gt_u32 s18, 29
	s_mov_b64 s[6:7], s[8:9]
	s_waitcnt vmcnt(6)
	s_barrier
	v_mfma_f32_16x16x32_bf16 v[44:47], v[186:189], v[144:147], v[44:47]
	v_mfma_f32_16x16x32_bf16 v[12:15], v[194:197], v[144:147], v[12:15]
	v_mfma_f32_16x16x32_bf16 v[40:43], v[186:189], v[152:155], v[40:43]
	v_mfma_f32_16x16x32_bf16 v[8:11], v[194:197], v[152:155], v[8:11]
	v_mfma_f32_16x16x32_bf16 v[36:39], v[186:189], v[160:163], v[36:39]
	v_mfma_f32_16x16x32_bf16 v[4:7], v[194:197], v[160:163], v[4:7]
	v_mfma_f32_16x16x32_bf16 v[32:35], v[186:189], v[178:181], v[32:35]
	v_mfma_f32_16x16x32_bf16 v[0:3], v[194:197], v[178:181], v[0:3]
	v_mfma_f32_16x16x32_bf16 v[44:47], v[190:193], v[148:151], v[44:47]
	v_mfma_f32_16x16x32_bf16 v[12:15], v[208:211], v[148:151], v[12:15]
	v_mfma_f32_16x16x32_bf16 v[40:43], v[190:193], v[156:159], v[40:43]
	v_mfma_f32_16x16x32_bf16 v[8:11], v[208:211], v[156:159], v[8:11]
	v_mfma_f32_16x16x32_bf16 v[36:39], v[190:193], v[174:177], v[36:39]
	v_mfma_f32_16x16x32_bf16 v[4:7], v[208:211], v[174:177], v[4:7]
	v_mfma_f32_16x16x32_bf16 v[32:35], v[190:193], v[182:185], v[32:35]
	v_mfma_f32_16x16x32_bf16 v[0:3], v[208:211], v[182:185], v[0:3]
	s_barrier
	s_cbranch_scc0 .LBB0_1238
	s_lshl_b32 s12, s15, 21
	s_lshl_b32 s13, s14, 10
	s_lshr_b32 s16, s15, 4
	s_add_u32 s12, s12, s13
	s_mul_i32 s16, s16, 6
	s_add_i32 s16, s16, 2
	s_lshl_b32 s16, s16, 13
	s_add_u32 s16, s16, s13
	s_add_u32 s10, s26, s16
	s_addc_u32 s11, s27, 0
	s_add_u32 s8, s52, s12
	s_addc_u32 s9, s53, 0
	s_add_u32 s6, s24, s12
	s_addc_u32 s7, s25, 0
	v_lshrrev_b32_e32 v224, 6, v206
	v_and_b32_e32 v225, 3, v224
	v_lshrrev_b32_e32 v224, 2, v224
	v_and_b32_e32 v205, 15, v206
	v_bfe_u32 v226, v206, 4, 2
	v_lshl_add_u32 v225, v225, 3, v226
	v_lshl_add_u32 v224, v224, 6, v205
	v_lshlrev_b32_e32 v205, 4, v225
	v_lshl_add_u32 v203, v224, 13, v205
	v_mov_b32_e32 v204, v203
	global_load_dwordx4 v[128:131], v205, s[10:11] offset:0
	global_load_dwordx4 v[132:135], v205, s[10:11] offset:64
	global_load_dwordx4 v[136:139], v205, s[10:11] offset:512
	global_load_dwordx4 v[140:143], v205, s[10:11] offset:576
	global_load_dwordx4 v[144:147], v203, s[8:9] offset:0
	global_load_dwordx4 v[148:151], v203, s[8:9] offset:64
	global_load_dwordx4 v[152:155], v203, s[8:9] offset:512
	global_load_dwordx4 v[156:159], v203, s[8:9] offset:576
	v_add_u32_e32 v203, 0x20000, v203
	global_load_dwordx4 v[160:163], v203, s[8:9] offset:0
	global_load_dwordx4 v[174:177], v203, s[8:9] offset:64
	global_load_dwordx4 v[178:181], v203, s[8:9] offset:512
	global_load_dwordx4 v[182:185], v203, s[8:9] offset:576
	v_add_u32_e32 v203, 0x20000, v203
	global_load_dwordx4 v[186:189], v203, s[8:9] offset:0
	global_load_dwordx4 v[190:193], v203, s[8:9] offset:64
	global_load_dwordx4 v[194:197], v203, s[8:9] offset:512
	global_load_dwordx4 v[208:211], v203, s[8:9] offset:576
	v_add_u32_e32 v203, 0x20000, v203
	global_load_dwordx4 v[212:215], v203, s[8:9] offset:0
	global_load_dwordx4 v[216:219], v203, s[8:9] offset:64
	global_load_dwordx4 v[220:223], v203, s[8:9] offset:512
	global_load_dwordx4 v[224:227], v203, s[8:9] offset:576
	v_add_u32_e32 v203, 0xa0000, v203
	s_waitcnt vmcnt(12)
	v_pk_fma_f32 v[124:125], v[124:125], v[128:129], v[144:145]
	v_pk_fma_f32 v[126:127], v[126:127], v[130:131], v[146:147]
	v_pk_fma_f32 v[92:93], v[92:93], v[132:133], v[148:149]
	v_pk_fma_f32 v[94:95], v[94:95], v[134:135], v[150:151]
	v_pk_fma_f32 v[60:61], v[60:61], v[136:137], v[152:153]
	v_pk_fma_f32 v[62:63], v[62:63], v[138:139], v[154:155]
	v_pk_fma_f32 v[28:29], v[28:29], v[140:141], v[156:157]
	v_pk_fma_f32 v[30:31], v[30:31], v[142:143], v[158:159]
	global_store_dwordx4 v204, v[124:127], s[6:7] offset:0
	global_store_dwordx4 v204, v[92:95], s[6:7] offset:64
	global_store_dwordx4 v204, v[60:63], s[6:7] offset:512
	global_store_dwordx4 v204, v[28:31], s[6:7] offset:576
	v_add_u32_e32 v204, 0x20000, v204
	global_load_dwordx4 v[144:147], v203, s[8:9] offset:0
	global_load_dwordx4 v[148:151], v203, s[8:9] offset:64
	global_load_dwordx4 v[152:155], v203, s[8:9] offset:512
	global_load_dwordx4 v[156:159], v203, s[8:9] offset:576
	v_add_u32_e32 v203, 0x20000, v203
	s_waitcnt vmcnt(16)
; #define EPI_DONE do { } while (0)
; DI void epi_resid(const Acc& acc, const P& p, int brow, int bcol, int layer, int gch, bool from_input) {
;     EPI_IDX
;     const float* gate = modv(p, layer, brow, gch);
; #pragma unroll
;     for (int bj = 0; bj < 2; ++bj)
; #pragma unroll
;         for (int n = 0; n < 2; ++n) {
;             const int c0 = bcol + bj * 128 + wc * 32 + n * 16 + fq * 4;
;             const f32x4 g = *(const f32x4*)(gate + c0);
;             f32x4 xv[2][4];
; #pragma unroll
;             for (int ai = 0; ai < 2; ++ai)
; #pragma unroll
;                 for (int m = 0; m < 4; ++m) {
;                     const int r = brow + ai * 128 + wr * 64 + m * 16 + fr;
;                     const float* sp = (from_input ? inrow(p, r) : xrow(p, r)) + c0;
;                     xv[ai][m] = *(const f32x4*)sp;
;                 }
;             __builtin_amdgcn_sched_barrier(0);
; #pragma unroll
;             for (int ai = 0; ai < 2; ++ai)
; #pragma unroll
;                 for (int m = 0; m < 4; ++m) {
;                     const int r = brow + ai * 128 + wr * 64 + m * 16 + fr;
;                     *(f32x4*)(xrow(p, r) + c0) = xv[ai][m] + g * acc[ai][bj][m][n];
;                 }
;             __builtin_amdgcn_sched_barrier(0);
;         }
;     EPI_DONE;
; }
	v_pk_fma_f32 v[120:121], v[120:121], v[128:129], v[160:161]
	v_pk_fma_f32 v[122:123], v[122:123], v[130:131], v[162:163]
	v_pk_fma_f32 v[88:89], v[88:89], v[132:133], v[174:175]
	v_pk_fma_f32 v[90:91], v[90:91], v[134:135], v[176:177]
	v_pk_fma_f32 v[56:57], v[56:57], v[136:137], v[178:179]
	v_pk_fma_f32 v[58:59], v[58:59], v[138:139], v[180:181]
	v_pk_fma_f32 v[24:25], v[24:25], v[140:141], v[182:183]
	v_pk_fma_f32 v[26:27], v[26:27], v[142:143], v[184:185]
	global_store_dwordx4 v204, v[120:123], s[6:7] offset:0
	global_store_dwordx4 v204, v[88:91], s[6:7] offset:64
	global_store_dwordx4 v204, v[56:59], s[6:7] offset:512
	global_store_dwordx4 v204, v[24:27], s[6:7] offset:576
	v_add_u32_e32 v204, 0x20000, v204
	global_load_dwordx4 v[160:163], v203, s[8:9] offset:0
	global_load_dwordx4 v[174:177], v203, s[8:9] offset:64
	global_load_dwordx4 v[178:181], v203, s[8:9] offset:512
	global_load_dwordx4 v[182:185], v203, s[8:9] offset:576
	v_add_u32_e32 v203, 0x20000, v203
	s_waitcnt vmcnt(20)
	v_pk_fma_f32 v[116:117], v[116:117], v[128:129], v[186:187]
	v_pk_fma_f32 v[118:119], v[118:119], v[130:131], v[188:189]
	v_pk_fma_f32 v[84:85], v[84:85], v[132:133], v[190:191]
	v_pk_fma_f32 v[86:87], v[86:87], v[134:135], v[192:193]
	v_pk_fma_f32 v[52:53], v[52:53], v[136:137], v[194:195]
	v_pk_fma_f32 v[54:55], v[54:55], v[138:139], v[196:197]
	v_pk_fma_f32 v[20:21], v[20:21], v[140:141], v[208:209]
	v_pk_fma_f32 v[22:23], v[22:23], v[142:143], v[210:211]
	global_store_dwordx4 v204, v[116:119], s[6:7] offset:0
	global_store_dwordx4 v204, v[84:87], s[6:7] offset:64
	global_store_dwordx4 v204, v[52:55], s[6:7] offset:512
	global_store_dwordx4 v204, v[20:23], s[6:7] offset:576
	v_add_u32_e32 v204, 0x20000, v204
	global_load_dwordx4 v[186:189], v203, s[8:9] offset:0
	global_load_dwordx4 v[190:193], v203, s[8:9] offset:64
	global_load_dwordx4 v[194:197], v203, s[8:9] offset:512
	global_load_dwordx4 v[208:211], v203, s[8:9] offset:576
	v_add_u32_e32 v203, 0x20000, v203
	s_waitcnt vmcnt(24)
	v_pk_fma_f32 v[112:113], v[112:113], v[128:129], v[212:213]
	v_pk_fma_f32 v[114:115], v[114:115], v[130:131], v[214:215]
	v_pk_fma_f32 v[80:81], v[80:81], v[132:133], v[216:217]
	v_pk_fma_f32 v[82:83], v[82:83], v[134:135], v[218:219]
	v_pk_fma_f32 v[48:49], v[48:49], v[136:137], v[220:221]
	v_pk_fma_f32 v[50:51], v[50:51], v[138:139], v[222:223]
	v_pk_fma_f32 v[16:17], v[16:17], v[140:141], v[224:225]
	v_pk_fma_f32 v[18:19], v[18:19], v[142:143], v[226:227]
	global_store_dwordx4 v204, v[112:115], s[6:7] offset:0
	global_store_dwordx4 v204, v[80:83], s[6:7] offset:64
	global_store_dwordx4 v204, v[48:51], s[6:7] offset:512
	global_store_dwordx4 v204, v[16:19], s[6:7] offset:576
	v_add_u32_e32 v204, 0xa0000, v204
	global_load_dwordx4 v[212:215], v203, s[8:9] offset:0
	global_load_dwordx4 v[216:219], v203, s[8:9] offset:64
	global_load_dwordx4 v[220:223], v203, s[8:9] offset:512
	global_load_dwordx4 v[224:227], v203, s[8:9] offset:576
	s_waitcnt vmcnt(24)
	v_pk_fma_f32 v[108:109], v[108:109], v[128:129], v[144:145]
	v_pk_fma_f32 v[110:111], v[110:111], v[130:131], v[146:147]
	v_pk_fma_f32 v[76:77], v[76:77], v[132:133], v[148:149]
	v_pk_fma_f32 v[78:79], v[78:79], v[134:135], v[150:151]
	v_pk_fma_f32 v[44:45], v[44:45], v[136:137], v[152:153]
	v_pk_fma_f32 v[46:47], v[46:47], v[138:139], v[154:155]
	v_pk_fma_f32 v[12:13], v[12:13], v[140:141], v[156:157]
	v_pk_fma_f32 v[14:15], v[14:15], v[142:143], v[158:159]
	global_store_dwordx4 v204, v[108:111], s[6:7] offset:0
	global_store_dwordx4 v204, v[76:79], s[6:7] offset:64
	global_store_dwordx4 v204, v[44:47], s[6:7] offset:512
	global_store_dwordx4 v204, v[12:15], s[6:7] offset:576
	v_add_u32_e32 v204, 0x20000, v204
	s_waitcnt vmcnt(20)
	v_pk_fma_f32 v[104:105], v[104:105], v[128:129], v[160:161]
	v_pk_fma_f32 v[106:107], v[106:107], v[130:131], v[162:163]
	v_pk_fma_f32 v[72:73], v[72:73], v[132:133], v[174:175]
	v_pk_fma_f32 v[74:75], v[74:75], v[134:135], v[176:177]
	v_pk_fma_f32 v[40:41], v[40:41], v[136:137], v[178:179]
	v_pk_fma_f32 v[42:43], v[42:43], v[138:139], v[180:181]
	v_pk_fma_f32 v[8:9], v[8:9], v[140:141], v[182:183]
	v_pk_fma_f32 v[10:11], v[10:11], v[142:143], v[184:185]
	global_store_dwordx4 v204, v[104:107], s[6:7] offset:0
	global_store_dwordx4 v204, v[72:75], s[6:7] offset:64
	global_store_dwordx4 v204, v[40:43], s[6:7] offset:512
	global_store_dwordx4 v204, v[8:11], s[6:7] offset:576
	v_add_u32_e32 v204, 0x20000, v204
	s_waitcnt vmcnt(16)
	v_pk_fma_f32 v[100:101], v[100:101], v[128:129], v[186:187]
	v_pk_fma_f32 v[102:103], v[102:103], v[130:131], v[188:189]
	v_pk_fma_f32 v[68:69], v[68:69], v[132:133], v[190:191]
	v_pk_fma_f32 v[70:71], v[70:71], v[134:135], v[192:193]
	v_pk_fma_f32 v[36:37], v[36:37], v[136:137], v[194:195]
	v_pk_fma_f32 v[38:39], v[38:39], v[138:139], v[196:197]
	v_pk_fma_f32 v[4:5], v[4:5], v[140:141], v[208:209]
	v_pk_fma_f32 v[6:7], v[6:7], v[142:143], v[210:211]
	global_store_dwordx4 v204, v[100:103], s[6:7] offset:0
	global_store_dwordx4 v204, v[68:71], s[6:7] offset:64
	global_store_dwordx4 v204, v[36:39], s[6:7] offset:512
	global_store_dwordx4 v204, v[4:7], s[6:7] offset:576
	v_add_u32_e32 v204, 0x20000, v204
	s_waitcnt vmcnt(12)
	v_pk_fma_f32 v[96:97], v[96:97], v[128:129], v[212:213]
	v_pk_fma_f32 v[98:99], v[98:99], v[130:131], v[214:215]
	v_pk_fma_f32 v[64:65], v[64:65], v[132:133], v[216:217]
	v_pk_fma_f32 v[66:67], v[66:67], v[134:135], v[218:219]
	v_pk_fma_f32 v[32:33], v[32:33], v[136:137], v[220:221]
	v_pk_fma_f32 v[34:35], v[34:35], v[138:139], v[222:223]
	v_pk_fma_f32 v[0:1], v[0:1], v[140:141], v[224:225]
	v_pk_fma_f32 v[2:3], v[2:3], v[142:143], v[226:227]
	global_store_dwordx4 v204, v[96:99], s[6:7] offset:0
	global_store_dwordx4 v204, v[64:67], s[6:7] offset:64
	global_store_dwordx4 v204, v[32:35], s[6:7] offset:512
	global_store_dwordx4 v204, v[0:3], s[6:7] offset:576
	s_branch .Lresid_latch_wout0

; #define WAIT_V(n) asm volatile("s_waitcnt vmcnt(" #n ")" ::: "memory")
; #define WAIT_L(n) asm volatile("s_waitcnt lgkmcnt(" #n ")" ::: "memory")
; #define BAR __builtin_amdgcn_s_barrier()
; #define SCHED __builtin_amdgcn_sched_barrier(0)
; template <class Get, class Epi>
; DI void gemm_stream(LAS unsigned char* lds, const int K, const int ld, Get get, Epi epi) {
;     ...
;             const char* a1 = cA + (size_t)(t + 1) * kstep;
;             const char* a2 = last ? nA : cA + (size_t)(t + 2) * kstep;
;             const char* b2 = last ? nB : cB + (size_t)(t + 2) * kstep;
;             const char* a3 = a2 + kstep;
;             const char* b3 = b2 + kstep;
;             LDB(B0, 0, 0); SCHED; LDA(At, 0, 0); STAGE(SAo(1, 1), a1 + hstep);
;             WAIT_L(8); BAR; WAIT_L(0); MMA(0, 0, At, B0); BAR; SCHED;
;             LDB(B1, 0, 1); STAGE(SBo(0, 0), b2);
;             BAR; WAIT_L(0); MMA(0, 1, At, B1); BAR;
;             LDA(At, 0, 1); STAGE(SAo(0, 0), a2);
;             BAR; WAIT_L(0); MMA(1, 0, At, B0); BAR; SCHED;
;             STAGE(SBo(0, 1), b2 + hstep);
;             WAIT_V(6); BAR; MMA(1, 1, At, B1); BAR;
;             LDB(B0, 1, 0); SCHED; LDA(At, 1, 0); STAGE(SAo(0, 1), a2 + hstep);
;             WAIT_L(8); BAR; WAIT_L(0); MMA(0, 0, At, B0); BAR; SCHED;
;             LDB(B1, 1, 1); STAGE(SBo(1, 0), b3);
;             BAR; WAIT_L(0); MMA(0, 1, At, B1); BAR;
;             LDA(At, 1, 1); STAGE(SAo(1, 0), a3);
;             BAR; WAIT_L(0); MMA(1, 0, At, B0); BAR; SCHED;
;             STAGE(SBo(1, 1), b3 + hstep);
;             WAIT_V(6); BAR; MMA(1, 1, At, B1); BAR;
.LBB0_1630:
	ds_read_b128 v[148:151], v142
	ds_read_b128 v[152:155], v142 offset:1024
	ds_read_b128 v[156:159], v142 offset:2048
	ds_read_b128 v[160:163], v142 offset:3072
	s_add_u32 s12, s10, 0xfff80080
	s_addc_u32 s13, s11, -1
	s_cmp_eq_u32 s59, 28
	s_cselect_b32 s15, s7, s13
	s_cselect_b32 s14, s6, s12
	s_cselect_b32 s13, s9, s58
	s_cselect_b32 s12, s8, s57
	s_mov_b32 m0, s28
	ds_read_b128 v[164:167], v143
	ds_read_b128 v[168:171], v143 offset:1024
	ds_read_b128 v[172:175], v143 offset:2048
	ds_read_b128 v[176:179], v143 offset:3072
	ds_read_b128 v[180:183], v143 offset:4096
	ds_read_b128 v[184:187], v143 offset:5120
	ds_read_b128 v[188:191], v143 offset:6144
	ds_read_b128 v[192:195], v143 offset:7168
	global_load_lds_dwordx4 v134, s[10:11]
	s_mov_b32 m0, s29
	s_nop 0
	global_load_lds_dwordx4 v136, s[10:11]
	s_waitcnt lgkmcnt(8)
	s_barrier
	s_waitcnt lgkmcnt(0)
	v_mfma_f32_16x16x32_bf16 v[124:127], v[148:151], v[164:167], v[124:127]
	v_mfma_f32_16x16x32_bf16 v[116:119], v[156:159], v[164:167], v[116:119]
	v_mfma_f32_16x16x32_bf16 v[108:111], v[148:151], v[172:175], v[108:111]
	v_mfma_f32_16x16x32_bf16 v[100:103], v[156:159], v[172:175], v[100:103]
	v_mfma_f32_16x16x32_bf16 v[92:95], v[148:151], v[180:183], v[92:95]
	v_mfma_f32_16x16x32_bf16 v[84:87], v[156:159], v[180:183], v[84:87]
	v_mfma_f32_16x16x32_bf16 v[76:79], v[148:151], v[188:191], v[76:79]
	v_mfma_f32_16x16x32_bf16 v[68:71], v[156:159], v[188:191], v[68:71]
	v_mfma_f32_16x16x32_bf16 v[124:127], v[152:155], v[168:171], v[124:127]
	v_mfma_f32_16x16x32_bf16 v[116:119], v[160:163], v[168:171], v[116:119]
	v_mfma_f32_16x16x32_bf16 v[108:111], v[152:155], v[176:179], v[108:111]
	v_mfma_f32_16x16x32_bf16 v[100:103], v[160:163], v[176:179], v[100:103]
	v_mfma_f32_16x16x32_bf16 v[92:95], v[152:155], v[184:187], v[92:95]
	v_mfma_f32_16x16x32_bf16 v[84:87], v[160:163], v[184:187], v[84:87]
	v_mfma_f32_16x16x32_bf16 v[76:79], v[152:155], v[192:195], v[76:79]
	v_mfma_f32_16x16x32_bf16 v[68:71], v[160:163], v[192:195], v[68:71]
	s_barrier
	s_mov_b32 m0, s35
	v_lshl_add_u64 v[140:141], s[12:13], 0, v[130:131]
	ds_read_b128 v[196:199], v144
	ds_read_b128 v[200:203], v144 offset:1024
	ds_read_b128 v[208:211], v144 offset:2048
	ds_read_b128 v[212:215], v144 offset:3072
	global_load_lds_dwordx4 v[140:141], off
	v_lshl_add_u64 v[204:205], s[12:13], 0, v[128:129]
	s_mov_b32 m0, s36
	s_nop 0
	global_load_lds_dwordx4 v[204:205], off
	s_barrier
	s_waitcnt lgkmcnt(0)
	v_mfma_f32_16x16x32_bf16 v[120:123], v[196:199], v[164:167], v[120:123]
	v_mfma_f32_16x16x32_bf16 v[112:115], v[208:211], v[164:167], v[112:115]
	v_mfma_f32_16x16x32_bf16 v[104:107], v[196:199], v[172:175], v[104:107]
	v_mfma_f32_16x16x32_bf16 v[96:99], v[208:211], v[172:175], v[96:99]
	v_mfma_f32_16x16x32_bf16 v[88:91], v[196:199], v[180:183], v[88:91]
	v_mfma_f32_16x16x32_bf16 v[80:83], v[208:211], v[180:183], v[80:83]
	v_mfma_f32_16x16x32_bf16 v[72:75], v[196:199], v[188:191], v[72:75]
	v_mfma_f32_16x16x32_bf16 v[64:67], v[208:211], v[188:191], v[64:67]
	v_mfma_f32_16x16x32_bf16 v[120:123], v[200:203], v[168:171], v[120:123]
	v_mfma_f32_16x16x32_bf16 v[112:115], v[212:215], v[168:171], v[112:115]
	v_mfma_f32_16x16x32_bf16 v[104:107], v[200:203], v[176:179], v[104:107]
	v_mfma_f32_16x16x32_bf16 v[96:99], v[212:215], v[176:179], v[96:99]
	v_mfma_f32_16x16x32_bf16 v[88:91], v[200:203], v[184:187], v[88:91]
	v_mfma_f32_16x16x32_bf16 v[80:83], v[212:215], v[184:187], v[80:83]
	v_mfma_f32_16x16x32_bf16 v[72:75], v[200:203], v[192:195], v[72:75]
	v_mfma_f32_16x16x32_bf16 v[64:67], v[212:215], v[192:195], v[64:67]
	s_barrier
	s_mov_b32 m0, s3
	v_lshl_add_u64 v[216:217], s[14:15], 0, v[130:131]
	ds_read_b128 v[164:167], v143 offset:16384
	ds_read_b128 v[168:171], v143 offset:17408
	ds_read_b128 v[172:175], v143 offset:18432
	ds_read_b128 v[176:179], v143 offset:19456
	ds_read_b128 v[180:183], v143 offset:20480
	ds_read_b128 v[184:187], v143 offset:21504
	ds_read_b128 v[188:191], v143 offset:22528
	ds_read_b128 v[192:195], v143 offset:23552
	global_load_lds_dwordx4 v[216:217], off
	v_lshl_add_u64 v[218:219], s[14:15], 0, v[128:129]
	s_mov_b32 m0, s16
	s_nop 0
	global_load_lds_dwordx4 v[218:219], off
	s_barrier
	s_waitcnt lgkmcnt(0)
	v_mfma_f32_16x16x32_bf16 v[60:63], v[148:151], v[164:167], v[60:63]
	v_mfma_f32_16x16x32_bf16 v[52:55], v[156:159], v[164:167], v[52:55]
	v_mfma_f32_16x16x32_bf16 v[44:47], v[148:151], v[172:175], v[44:47]
	v_mfma_f32_16x16x32_bf16 v[36:39], v[156:159], v[172:175], v[36:39]
	v_mfma_f32_16x16x32_bf16 v[28:31], v[148:151], v[180:183], v[28:31]
	v_mfma_f32_16x16x32_bf16 v[20:23], v[156:159], v[180:183], v[20:23]
	v_mfma_f32_16x16x32_bf16 v[12:15], v[148:151], v[188:191], v[12:15]
	v_mfma_f32_16x16x32_bf16 v[4:7], v[156:159], v[188:191], v[4:7]
	v_mfma_f32_16x16x32_bf16 v[60:63], v[152:155], v[168:171], v[60:63]
	v_mfma_f32_16x16x32_bf16 v[52:55], v[160:163], v[168:171], v[52:55]
	v_mfma_f32_16x16x32_bf16 v[44:47], v[152:155], v[176:179], v[44:47]
	v_mfma_f32_16x16x32_bf16 v[36:39], v[160:163], v[176:179], v[36:39]
	v_mfma_f32_16x16x32_bf16 v[28:31], v[152:155], v[184:187], v[28:31]
	v_mfma_f32_16x16x32_bf16 v[20:23], v[160:163], v[184:187], v[20:23]
	v_mfma_f32_16x16x32_bf16 v[12:15], v[152:155], v[192:195], v[12:15]
	v_mfma_f32_16x16x32_bf16 v[4:7], v[160:163], v[192:195], v[4:7]
	s_barrier
	s_add_u32 s60, s12, 0x80000
	s_addc_u32 s61, s13, 0
	s_mov_b32 m0, s37
	v_lshl_add_u64 v[148:149], s[60:61], 0, v[130:131]
	global_load_lds_dwordx4 v[148:149], off
	s_mov_b32 m0, s38
	s_nop 0
	global_load_lds_dwordx4 v128, s[60:61]
	s_waitcnt vmcnt(6)
	s_barrier
; #define WAIT_V(n) asm volatile("s_waitcnt vmcnt(" #n ")" ::: "memory")
; #define WAIT_L(n) asm volatile("s_waitcnt lgkmcnt(" #n ")" ::: "memory")
; #define BAR __builtin_amdgcn_s_barrier()
; #define SCHED __builtin_amdgcn_sched_barrier(0)
; template <class Get, class Epi>
; DI void gemm_stream(LAS unsigned char* lds, const int K, const int ld, Get get, Epi epi) {
;     ...
;             LDB(B0, 0, 0); SCHED; LDA(At, 0, 0); STAGE(SAo(1, 1), a1 + hstep);
;             WAIT_L(8); BAR; WAIT_L(0); MMA(0, 0, At, B0); BAR; SCHED;
;             LDB(B1, 0, 1); STAGE(SBo(0, 0), b2);
;             BAR; WAIT_L(0); MMA(0, 1, At, B1); BAR;
;             LDA(At, 0, 1); STAGE(SAo(0, 0), a2);
;             BAR; WAIT_L(0); MMA(1, 0, At, B0); BAR; SCHED;
;             STAGE(SBo(0, 1), b2 + hstep);
;             WAIT_V(6); BAR; MMA(1, 1, At, B1); BAR;
;             LDB(B0, 1, 0); SCHED; LDA(At, 1, 0); STAGE(SAo(0, 1), a2 + hstep);
;             WAIT_L(8); BAR; WAIT_L(0); MMA(0, 0, At, B0); BAR; SCHED;
;             LDB(B1, 1, 1); STAGE(SBo(1, 0), b3);
;             BAR; WAIT_L(0); MMA(0, 1, At, B1); BAR;
;             LDA(At, 1, 1); STAGE(SAo(1, 0), a3);
;             BAR; WAIT_L(0); MMA(1, 0, At, B0); BAR; SCHED;
;             STAGE(SBo(1, 1), b3 + hstep);
;             WAIT_V(6); BAR; MMA(1, 1, At, B1); BAR;
	v_mfma_f32_16x16x32_bf16 v[56:59], v[196:199], v[164:167], v[56:59]
	v_mfma_f32_16x16x32_bf16 v[48:51], v[208:211], v[164:167], v[48:51]
	v_mfma_f32_16x16x32_bf16 v[40:43], v[196:199], v[172:175], v[40:43]
	v_mfma_f32_16x16x32_bf16 v[32:35], v[208:211], v[172:175], v[32:35]
	v_mfma_f32_16x16x32_bf16 v[24:27], v[196:199], v[180:183], v[24:27]
	v_mfma_f32_16x16x32_bf16 v[16:19], v[208:211], v[180:183], v[16:19]
	v_mfma_f32_16x16x32_bf16 v[8:11], v[196:199], v[188:191], v[8:11]
	v_mfma_f32_16x16x32_bf16 v[0:3], v[208:211], v[188:191], v[0:3]
	v_mfma_f32_16x16x32_bf16 v[56:59], v[200:203], v[168:171], v[56:59]
	v_mfma_f32_16x16x32_bf16 v[48:51], v[212:215], v[168:171], v[48:51]
	v_mfma_f32_16x16x32_bf16 v[40:43], v[200:203], v[176:179], v[40:43]
	v_mfma_f32_16x16x32_bf16 v[32:35], v[212:215], v[176:179], v[32:35]
	v_mfma_f32_16x16x32_bf16 v[24:27], v[200:203], v[184:187], v[24:27]
	v_mfma_f32_16x16x32_bf16 v[16:19], v[212:215], v[184:187], v[16:19]
	v_mfma_f32_16x16x32_bf16 v[8:11], v[200:203], v[192:195], v[8:11]
	v_mfma_f32_16x16x32_bf16 v[0:3], v[212:215], v[192:195], v[0:3]
	s_barrier
	ds_read_b128 v[148:151], v145
	ds_read_b128 v[152:155], v145 offset:1024
	ds_read_b128 v[156:159], v145 offset:2048
	ds_read_b128 v[160:163], v145 offset:3072
	s_add_u32 s14, s14, 0x80000
	s_addc_u32 s15, s15, 0
	s_mov_b32 m0, s17
	ds_read_b128 v[164:167], v143 offset:32768
	ds_read_b128 v[168:171], v143 offset:33792
	ds_read_b128 v[172:175], v143 offset:34816
	ds_read_b128 v[176:179], v143 offset:35840
	ds_read_b128 v[180:183], v143 offset:36864
	ds_read_b128 v[184:187], v143 offset:37888
	ds_read_b128 v[188:191], v143 offset:38912
	ds_read_b128 v[192:195], v143 offset:39936
	global_load_lds_dwordx4 v130, s[14:15]
	s_mov_b32 m0, s18
	s_nop 0
	global_load_lds_dwordx4 v128, s[14:15]
	s_waitcnt lgkmcnt(8)
	s_barrier
	s_waitcnt lgkmcnt(0)
	v_mfma_f32_16x16x32_bf16 v[124:127], v[148:151], v[164:167], v[124:127]
	v_mfma_f32_16x16x32_bf16 v[116:119], v[156:159], v[164:167], v[116:119]
	v_mfma_f32_16x16x32_bf16 v[108:111], v[148:151], v[172:175], v[108:111]
	v_mfma_f32_16x16x32_bf16 v[100:103], v[156:159], v[172:175], v[100:103]
	v_mfma_f32_16x16x32_bf16 v[92:95], v[148:151], v[180:183], v[92:95]
	v_mfma_f32_16x16x32_bf16 v[84:87], v[156:159], v[180:183], v[84:87]
	v_mfma_f32_16x16x32_bf16 v[76:79], v[148:151], v[188:191], v[76:79]
	v_mfma_f32_16x16x32_bf16 v[68:71], v[156:159], v[188:191], v[68:71]
	v_mfma_f32_16x16x32_bf16 v[124:127], v[152:155], v[168:171], v[124:127]
	v_mfma_f32_16x16x32_bf16 v[116:119], v[160:163], v[168:171], v[116:119]
	v_mfma_f32_16x16x32_bf16 v[108:111], v[152:155], v[176:179], v[108:111]
	v_mfma_f32_16x16x32_bf16 v[100:103], v[160:163], v[176:179], v[100:103]
	v_mfma_f32_16x16x32_bf16 v[92:95], v[152:155], v[184:187], v[92:95]
	v_mfma_f32_16x16x32_bf16 v[84:87], v[160:163], v[184:187], v[84:87]
	v_mfma_f32_16x16x32_bf16 v[76:79], v[152:155], v[192:195], v[76:79]
	v_mfma_f32_16x16x32_bf16 v[68:71], v[160:163], v[192:195], v[68:71]
	s_barrier
	s_mov_b32 m0, s39
	v_lshl_add_u64 v[140:141], v[140:141], 0, s[0:1]
	ds_read_b128 v[196:199], v146
	ds_read_b128 v[200:203], v146 offset:1024
	ds_read_b128 v[208:211], v146 offset:2048
	ds_read_b128 v[212:215], v146 offset:3072
	global_load_lds_dwordx4 v[140:141], off
	v_lshl_add_u64 v[140:141], v[204:205], 0, s[0:1]
	s_mov_b32 m0, s40
	s_nop 0
	global_load_lds_dwordx4 v[140:141], off
	s_barrier
	s_waitcnt lgkmcnt(0)
	v_mfma_f32_16x16x32_bf16 v[120:123], v[196:199], v[164:167], v[120:123]
	v_mfma_f32_16x16x32_bf16 v[112:115], v[208:211], v[164:167], v[112:115]
	v_mfma_f32_16x16x32_bf16 v[104:107], v[196:199], v[172:175], v[104:107]
	v_mfma_f32_16x16x32_bf16 v[96:99], v[208:211], v[172:175], v[96:99]
	v_mfma_f32_16x16x32_bf16 v[88:91], v[196:199], v[180:183], v[88:91]
	v_mfma_f32_16x16x32_bf16 v[80:83], v[208:211], v[180:183], v[80:83]
	v_mfma_f32_16x16x32_bf16 v[72:75], v[196:199], v[188:191], v[72:75]
	v_mfma_f32_16x16x32_bf16 v[64:67], v[208:211], v[188:191], v[64:67]
	v_mfma_f32_16x16x32_bf16 v[120:123], v[200:203], v[168:171], v[120:123]
	v_mfma_f32_16x16x32_bf16 v[112:115], v[212:215], v[168:171], v[112:115]
	v_mfma_f32_16x16x32_bf16 v[104:107], v[200:203], v[176:179], v[104:107]
	v_mfma_f32_16x16x32_bf16 v[96:99], v[212:215], v[176:179], v[96:99]
	v_mfma_f32_16x16x32_bf16 v[88:91], v[200:203], v[184:187], v[88:91]
	v_mfma_f32_16x16x32_bf16 v[80:83], v[212:215], v[184:187], v[80:83]
	v_mfma_f32_16x16x32_bf16 v[72:75], v[200:203], v[192:195], v[72:75]
	v_mfma_f32_16x16x32_bf16 v[64:67], v[212:215], v[192:195], v[64:67]
	s_barrier
	s_mov_b32 m0, s20
	v_lshl_add_u64 v[140:141], v[216:217], 0, s[0:1]
	ds_read_b128 v[164:167], v143 offset:49152
	ds_read_b128 v[168:171], v143 offset:50176
	ds_read_b128 v[172:175], v143 offset:51200
	ds_read_b128 v[176:179], v143 offset:52224
	ds_read_b128 v[180:183], v143 offset:53248
	ds_read_b128 v[184:187], v143 offset:54272
	ds_read_b128 v[188:191], v143 offset:55296
	ds_read_b128 v[192:195], v143 offset:56320
	global_load_lds_dwordx4 v[140:141], off
	v_lshl_add_u64 v[140:141], v[218:219], 0, s[0:1]
	s_mov_b32 m0, s21
	s_nop 0
	global_load_lds_dwordx4 v[140:141], off
	s_barrier
; DI float silu_f(float g) { return g * __builtin_amdgcn_rcpf(1.f + __builtin_amdgcn_exp2f(-LOG2E * g)); }
; #define WAIT_V(n) asm volatile("s_waitcnt vmcnt(" #n ")" ::: "memory")
; #define WAIT_L(n) asm volatile("s_waitcnt lgkmcnt(" #n ")" ::: "memory")
; #define BAR __builtin_amdgcn_s_barrier()
; #define SCHED __builtin_amdgcn_sched_barrier(0)
; template <class Get, class Epi>
; DI void gemm_stream(LAS unsigned char* lds, const int K, const int ld, Get get, Epi epi) {
;     ...
;             WAIT_L(8); BAR; WAIT_L(0); MMA(0, 0, At, B0); BAR; SCHED;
;             LDB(B1, 1, 1); STAGE(SBo(1, 0), b3);
;             BAR; WAIT_L(0); MMA(0, 1, At, B1); BAR;
;             LDA(At, 1, 1); STAGE(SAo(1, 0), a3);
;             BAR; WAIT_L(0); MMA(1, 0, At, B0); BAR; SCHED;
;             STAGE(SBo(1, 1), b3 + hstep);
;             WAIT_V(6); BAR; MMA(1, 1, At, B1); BAR;
;         }
;         epi(acc, cur);
; DI void epi_swiglu(const Acc& acc, int brow, int pn, bf16_t* hid) {
;     EPI_IDX
; #pragma unroll
;     for (int ai = 0; ai < 2; ++ai)
; #pragma unroll
;         for (int m = 0; m < 4; ++m) {
;             const int r = brow + ai * 128 + wr * 64 + m * 16 + fr;
;             bf16_t* rp = hid + (size_t)r * FF + pn * 128 + wc * 32 + fq * 4;
; #pragma unroll
;             for (int n = 0; n < 2; ++n) {
;                 const f32x4 g = acc[ai][0][m][n], u = acc[ai][1][m][n];
;                 float o[4];
; #pragma unroll
;                 for (int j = 0; j < 4; ++j) o[j] = silu_f(g[j]) * u[j];
;                 st4(rp + n * 16, o[0], o[1], o[2], o[3]);
	s_waitcnt lgkmcnt(0)
	v_mfma_f32_16x16x32_bf16 v[60:63], v[148:151], v[164:167], v[60:63]
	v_mfma_f32_16x16x32_bf16 v[52:55], v[156:159], v[164:167], v[52:55]
	v_mfma_f32_16x16x32_bf16 v[44:47], v[148:151], v[172:175], v[44:47]
	v_mfma_f32_16x16x32_bf16 v[36:39], v[156:159], v[172:175], v[36:39]
	v_mfma_f32_16x16x32_bf16 v[28:31], v[148:151], v[180:183], v[28:31]
	v_mfma_f32_16x16x32_bf16 v[20:23], v[156:159], v[180:183], v[20:23]
	v_mfma_f32_16x16x32_bf16 v[12:15], v[148:151], v[188:191], v[12:15]
	v_mfma_f32_16x16x32_bf16 v[4:7], v[156:159], v[188:191], v[4:7]
	v_mfma_f32_16x16x32_bf16 v[60:63], v[152:155], v[168:171], v[60:63]
	v_mfma_f32_16x16x32_bf16 v[52:55], v[160:163], v[168:171], v[52:55]
	v_mfma_f32_16x16x32_bf16 v[44:47], v[152:155], v[176:179], v[44:47]
	v_mfma_f32_16x16x32_bf16 v[36:39], v[160:163], v[176:179], v[36:39]
	v_mfma_f32_16x16x32_bf16 v[28:31], v[152:155], v[184:187], v[28:31]
	v_mfma_f32_16x16x32_bf16 v[20:23], v[160:163], v[184:187], v[20:23]
	v_mfma_f32_16x16x32_bf16 v[12:15], v[152:155], v[192:195], v[12:15]
	v_mfma_f32_16x16x32_bf16 v[4:7], v[160:163], v[192:195], v[4:7]
	s_barrier
	s_add_u32 s12, s12, 0x80080
	s_addc_u32 s13, s13, 0
	s_mov_b32 m0, s41
	v_lshl_add_u64 v[140:141], s[12:13], 0, v[130:131]
	global_load_lds_dwordx4 v[140:141], off
	v_lshl_add_u64 v[140:141], s[12:13], 0, v[128:129]
	s_mov_b32 m0, s52
	s_nop 0
	global_load_lds_dwordx4 v[140:141], off
	s_add_i32 s59, s59, 2
	s_add_u32 s10, s10, 0x100
	s_addc_u32 s11, s11, 0
	s_add_u32 s57, s57, 0x100
	s_addc_u32 s58, s58, 0
	s_cmp_gt_u32 s59, 29
	s_waitcnt vmcnt(6)
	s_barrier
	v_mfma_f32_16x16x32_bf16 v[56:59], v[196:199], v[164:167], v[56:59]
	v_mfma_f32_16x16x32_bf16 v[48:51], v[208:211], v[164:167], v[48:51]
	v_mfma_f32_16x16x32_bf16 v[40:43], v[196:199], v[172:175], v[40:43]
	v_mfma_f32_16x16x32_bf16 v[32:35], v[208:211], v[172:175], v[32:35]
	v_mfma_f32_16x16x32_bf16 v[24:27], v[196:199], v[180:183], v[24:27]
	v_mfma_f32_16x16x32_bf16 v[16:19], v[208:211], v[180:183], v[16:19]
	v_mfma_f32_16x16x32_bf16 v[8:11], v[196:199], v[188:191], v[8:11]
	v_mfma_f32_16x16x32_bf16 v[0:3], v[208:211], v[188:191], v[0:3]
	v_mfma_f32_16x16x32_bf16 v[56:59], v[200:203], v[168:171], v[56:59]
	v_mfma_f32_16x16x32_bf16 v[48:51], v[212:215], v[168:171], v[48:51]
	v_mfma_f32_16x16x32_bf16 v[40:43], v[200:203], v[176:179], v[40:43]
	v_mfma_f32_16x16x32_bf16 v[32:35], v[212:215], v[176:179], v[32:35]
	v_mfma_f32_16x16x32_bf16 v[24:27], v[200:203], v[184:187], v[24:27]
	v_mfma_f32_16x16x32_bf16 v[16:19], v[212:215], v[184:187], v[16:19]
	v_mfma_f32_16x16x32_bf16 v[8:11], v[200:203], v[192:195], v[8:11]
	v_mfma_f32_16x16x32_bf16 v[0:3], v[212:215], v[192:195], v[0:3]
	s_barrier
	s_cbranch_scc0 .LBB0_1630
	s_lshl_b32 s10, s55, 8
	v_mov_b32_e32 v132, v206
	v_mul_f32_e32 v149, 0xbfb8aa3b, v125
	v_and_or_b32 v141, v132, 15, s10
	s_lshl_b32 s10, s56, 7
	s_ashr_i32 s11, s10, 31
	s_lshl_b64 s[10:11], s[10:11], 1
	v_ashrrev_i32_e32 v140, 2, v132
	s_add_u32 s10, s80, s10
	v_and_b32_e32 v140, 0xffffffc0, v140
	s_addc_u32 s11, s81, s11
	v_lshrrev_b32_e32 v148, 1, v132
	v_and_b32_e32 v132, 0xc0, v132
	v_add_u32_e32 v147, v141, v140
	v_lshl_add_u64 v[140:141], s[10:11], 0, v[132:133]
	v_and_b32_e32 v132, 24, v148
	v_mul_f32_e32 v148, 0xbfb8aa3b, v124
	v_exp_f32_e32 v148, v148
	v_exp_f32_e32 v149, v149
	v_lshl_add_u64 v[140:141], v[140:141], 0, v[132:133]
	v_mad_i64_i32 v[152:153], s[10:11], v147, s23, v[140:141]
	v_add_f32_e32 v132, 1.0, v148
	v_rcp_f32_e32 v148, v132
	v_add_f32_e32 v132, 1.0, v149
	v_mul_f32_e32 v149, 0xbfb8aa3b, v126
	v_exp_f32_e32 v150, v149
	v_mul_f32_e32 v149, 0xbfb8aa3b, v127
	v_exp_f32_e32 v151, v149
	v_rcp_f32_e32 v149, v132
	v_add_f32_e32 v132, 1.0, v150
	v_rcp_f32_e32 v150, v132
	v_add_f32_e32 v132, 1.0, v151
	v_rcp_f32_e32 v151, v132
	v_pk_mul_f32 v[124:125], v[124:125], v[148:149]
	s_and_b64 vcc, exec, s[4:5]
	v_pk_mul_f32 v[120:121], v[124:125], v[120:121]
	v_pk_mul_f32 v[124:125], v[126:127], v[150:151]
	v_cvt_pk_bf16_f32 v120, v120, v121
	v_mul_f32_e32 v121, 0xbfb8aa3b, v116
	v_pk_mul_f32 v[122:123], v[124:125], v[122:123]
	v_exp_f32_e32 v124, v121
	v_mul_f32_e32 v121, 0xbfb8aa3b, v117
	v_exp_f32_e32 v125, v121
	v_cvt_pk_bf16_f32 v121, v122, v123
	v_add_f32_e32 v122, 1.0, v124
	v_mul_f32_e32 v124, 0xbfb8aa3b, v118
	v_add_f32_e32 v123, 1.0, v125
	v_mul_f32_e32 v125, 0xbfb8aa3b, v119
	v_exp_f32_e32 v124, v124
	v_exp_f32_e32 v125, v125
	v_rcp_f32_e32 v122, v122
	v_rcp_f32_e32 v123, v123
	v_add_f32_e32 v124, 1.0, v124
	v_add_f32_e32 v125, 1.0, v125
	v_rcp_f32_e32 v124, v124
	v_rcp_f32_e32 v125, v125
	v_pk_mul_f32 v[116:117], v[116:117], v[122:123]
	s_mov_b32 s56, s53
	v_pk_mul_f32 v[112:113], v[116:117], v[112:113]
	v_pk_mul_f32 v[116:117], v[118:119], v[124:125]
	v_cvt_pk_bf16_f32 v112, v112, v113
	v_pk_mul_f32 v[114:115], v[116:117], v[114:115]
	v_or_b32_e32 v116, 16, v147
	v_cvt_pk_bf16_f32 v113, v114, v115
	global_store_dwordx2 v[152:153], v[112:113], off offset:32
	v_mul_f32_e32 v112, 0xbfb8aa3b, v108
	v_mul_f32_e32 v113, 0xbfb8aa3b, v109
	v_exp_f32_e32 v112, v112
	v_exp_f32_e32 v113, v113
	v_mul_f32_e32 v114, 0xbfb8aa3b, v110
	v_mul_f32_e32 v115, 0xbfb8aa3b, v111
	v_exp_f32_e32 v114, v114
	v_exp_f32_e32 v115, v115
	v_add_f32_e32 v112, 1.0, v112
	v_add_f32_e32 v113, 1.0, v113
	v_rcp_f32_e32 v112, v112
	v_rcp_f32_e32 v113, v113
	v_add_f32_e32 v114, 1.0, v114
	v_add_f32_e32 v115, 1.0, v115
	v_rcp_f32_e32 v114, v114
	v_rcp_f32_e32 v115, v115
	v_pk_mul_f32 v[108:109], v[108:109], v[112:113]
	v_mad_i64_i32 v[116:117], s[10:11], v116, s23, v[140:141]
	v_pk_mul_f32 v[104:105], v[108:109], v[104:105]
	v_pk_mul_f32 v[108:109], v[110:111], v[114:115]
; DI float silu_f(float g) { return g * __builtin_amdgcn_rcpf(1.f + __builtin_amdgcn_exp2f(-LOG2E * g)); }
; DI void epi_swiglu(const Acc& acc, int brow, int pn, bf16_t* hid) {
;     ...
;     for (int ai = 0; ai < 2; ++ai)
; #pragma unroll
;         for (int m = 0; m < 4; ++m) {
;             const int r = brow + ai * 128 + wr * 64 + m * 16 + fr;
;             bf16_t* rp = hid + (size_t)r * FF + pn * 128 + wc * 32 + fq * 4;
; #pragma unroll
;             for (int n = 0; n < 2; ++n) {
;                 const f32x4 g = acc[ai][0][m][n], u = acc[ai][1][m][n];
;                 float o[4];
; #pragma unroll
;                 for (int j = 0; j < 4; ++j) o[j] = silu_f(g[j]) * u[j];
;                 st4(rp + n * 16, o[0], o[1], o[2], o[3]);
;             }
	v_cvt_pk_bf16_f32 v104, v104, v105
	v_mul_f32_e32 v105, 0xbfb8aa3b, v100
	v_pk_mul_f32 v[106:107], v[108:109], v[106:107]
	v_exp_f32_e32 v108, v105
	v_mul_f32_e32 v105, 0xbfb8aa3b, v101
	v_exp_f32_e32 v109, v105
	v_cvt_pk_bf16_f32 v105, v106, v107
	v_add_f32_e32 v106, 1.0, v108
	v_mul_f32_e32 v108, 0xbfb8aa3b, v102
	v_add_f32_e32 v107, 1.0, v109
	v_mul_f32_e32 v109, 0xbfb8aa3b, v103
	v_exp_f32_e32 v108, v108
	v_exp_f32_e32 v109, v109
	v_rcp_f32_e32 v106, v106
	v_rcp_f32_e32 v107, v107
	v_add_f32_e32 v108, 1.0, v108
	v_add_f32_e32 v109, 1.0, v109
	v_rcp_f32_e32 v108, v108
	v_rcp_f32_e32 v109, v109
	v_pk_mul_f32 v[100:101], v[100:101], v[106:107]
	s_mov_b32 s55, s54
	v_pk_mul_f32 v[96:97], v[100:101], v[96:97]
	v_pk_mul_f32 v[100:101], v[102:103], v[108:109]
	v_cvt_pk_bf16_f32 v96, v96, v97
	v_pk_mul_f32 v[98:99], v[100:101], v[98:99]
	v_or_b32_e32 v100, 32, v147
	v_cvt_pk_bf16_f32 v97, v98, v99
	global_store_dwordx2 v[116:117], v[96:97], off offset:32
	v_mul_f32_e32 v96, 0xbfb8aa3b, v92
	v_mul_f32_e32 v97, 0xbfb8aa3b, v93
	v_exp_f32_e32 v96, v96
	v_exp_f32_e32 v97, v97
	v_mul_f32_e32 v98, 0xbfb8aa3b, v94
	v_mul_f32_e32 v99, 0xbfb8aa3b, v95
	v_exp_f32_e32 v98, v98
	v_exp_f32_e32 v99, v99
	v_add_f32_e32 v96, 1.0, v96
	v_add_f32_e32 v97, 1.0, v97
	v_rcp_f32_e32 v96, v96
	v_rcp_f32_e32 v97, v97
	v_add_f32_e32 v98, 1.0, v98
	v_add_f32_e32 v99, 1.0, v99
	v_rcp_f32_e32 v98, v98
	v_rcp_f32_e32 v99, v99
	v_pk_mul_f32 v[92:93], v[92:93], v[96:97]
	v_mad_i64_i32 v[100:101], s[10:11], v100, s23, v[140:141]
	v_pk_mul_f32 v[88:89], v[92:93], v[88:89]
	v_pk_mul_f32 v[92:93], v[94:95], v[98:99]
	v_cvt_pk_bf16_f32 v88, v88, v89
	v_mul_f32_e32 v89, 0xbfb8aa3b, v84
	v_pk_mul_f32 v[90:91], v[92:93], v[90:91]
	v_exp_f32_e32 v92, v89
	v_mul_f32_e32 v89, 0xbfb8aa3b, v85
	v_exp_f32_e32 v93, v89
	v_cvt_pk_bf16_f32 v89, v90, v91
	v_add_f32_e32 v90, 1.0, v92
	v_mul_f32_e32 v92, 0xbfb8aa3b, v86
	v_add_f32_e32 v91, 1.0, v93
	v_mul_f32_e32 v93, 0xbfb8aa3b, v87
	v_exp_f32_e32 v92, v92
	v_exp_f32_e32 v93, v93
	v_rcp_f32_e32 v90, v90
	v_rcp_f32_e32 v91, v91
	v_add_f32_e32 v92, 1.0, v92
	v_add_f32_e32 v93, 1.0, v93
	v_rcp_f32_e32 v92, v92
	v_rcp_f32_e32 v93, v93
	v_pk_mul_f32 v[84:85], v[84:85], v[90:91]
	s_mov_b64 s[12:13], s[8:9]
	v_pk_mul_f32 v[80:81], v[84:85], v[80:81]
	v_pk_mul_f32 v[84:85], v[86:87], v[92:93]
	v_cvt_pk_bf16_f32 v80, v80, v81
	v_pk_mul_f32 v[82:83], v[84:85], v[82:83]
	v_or_b32_e32 v84, 48, v147
	v_cvt_pk_bf16_f32 v81, v82, v83
	global_store_dwordx2 v[100:101], v[80:81], off offset:32
	v_mul_f32_e32 v80, 0xbfb8aa3b, v76
	v_mul_f32_e32 v81, 0xbfb8aa3b, v77
	v_exp_f32_e32 v80, v80
	v_exp_f32_e32 v81, v81
	v_mul_f32_e32 v82, 0xbfb8aa3b, v78
	v_mul_f32_e32 v83, 0xbfb8aa3b, v79
	v_exp_f32_e32 v82, v82
	v_exp_f32_e32 v83, v83
	v_add_f32_e32 v80, 1.0, v80
	v_add_f32_e32 v81, 1.0, v81
	v_rcp_f32_e32 v80, v80
	v_rcp_f32_e32 v81, v81
	v_add_f32_e32 v82, 1.0, v82
	v_add_f32_e32 v83, 1.0, v83
	v_rcp_f32_e32 v82, v82
	v_rcp_f32_e32 v83, v83
	v_pk_mul_f32 v[76:77], v[76:77], v[80:81]
	v_mad_i64_i32 v[84:85], s[10:11], v84, s23, v[140:141]
	v_pk_mul_f32 v[72:73], v[76:77], v[72:73]
	v_pk_mul_f32 v[76:77], v[78:79], v[82:83]
	v_cvt_pk_bf16_f32 v72, v72, v73
	v_mul_f32_e32 v73, 0xbfb8aa3b, v68
	v_pk_mul_f32 v[74:75], v[76:77], v[74:75]
	v_exp_f32_e32 v76, v73
	v_mul_f32_e32 v73, 0xbfb8aa3b, v69
	v_exp_f32_e32 v77, v73
	v_cvt_pk_bf16_f32 v73, v74, v75
	v_add_f32_e32 v74, 1.0, v76
	v_mul_f32_e32 v76, 0xbfb8aa3b, v70
	v_add_f32_e32 v75, 1.0, v77
	v_mul_f32_e32 v77, 0xbfb8aa3b, v71
	v_exp_f32_e32 v76, v76
	v_exp_f32_e32 v77, v77
	v_rcp_f32_e32 v74, v74
	v_rcp_f32_e32 v75, v75
	v_add_f32_e32 v76, 1.0, v76
	v_add_f32_e32 v77, 1.0, v77
	v_rcp_f32_e32 v76, v76
	v_rcp_f32_e32 v77, v77
	v_pk_mul_f32 v[68:69], v[68:69], v[74:75]
	global_store_dwordx2 v[152:153], v[120:121], off
	v_pk_mul_f32 v[64:65], v[68:69], v[64:65]
	v_pk_mul_f32 v[68:69], v[70:71], v[76:77]
	v_cvt_pk_bf16_f32 v64, v64, v65
	v_pk_mul_f32 v[66:67], v[68:69], v[66:67]
	v_add_u32_e32 v68, 0x80, v147
	v_cvt_pk_bf16_f32 v65, v66, v67
	global_store_dwordx2 v[84:85], v[64:65], off offset:32
	v_mul_f32_e32 v64, 0xbfb8aa3b, v60
	v_mul_f32_e32 v65, 0xbfb8aa3b, v61
	v_exp_f32_e32 v64, v64
	v_exp_f32_e32 v65, v65
	v_mul_f32_e32 v66, 0xbfb8aa3b, v62
	v_mul_f32_e32 v67, 0xbfb8aa3b, v63
	v_exp_f32_e32 v66, v66
	v_exp_f32_e32 v67, v67
	v_add_f32_e32 v64, 1.0, v64
	v_add_f32_e32 v65, 1.0, v65
	v_rcp_f32_e32 v64, v64
	v_rcp_f32_e32 v65, v65
	v_add_f32_e32 v66, 1.0, v66
	v_add_f32_e32 v67, 1.0, v67
	v_rcp_f32_e32 v66, v66
	v_rcp_f32_e32 v67, v67
	v_pk_mul_f32 v[60:61], v[60:61], v[64:65]
	v_mad_i64_i32 v[68:69], s[10:11], v68, s23, v[140:141]
	v_pk_mul_f32 v[56:57], v[60:61], v[56:57]
	v_pk_mul_f32 v[60:61], v[62:63], v[66:67]
	v_cvt_pk_bf16_f32 v56, v56, v57
	v_mul_f32_e32 v57, 0xbfb8aa3b, v52
	v_pk_mul_f32 v[58:59], v[60:61], v[58:59]
	v_exp_f32_e32 v60, v57
	v_mul_f32_e32 v57, 0xbfb8aa3b, v53
	v_exp_f32_e32 v61, v57
	v_cvt_pk_bf16_f32 v57, v58, v59
	v_add_f32_e32 v58, 1.0, v60
	v_mul_f32_e32 v60, 0xbfb8aa3b, v54
	v_add_f32_e32 v59, 1.0, v61
	v_mul_f32_e32 v61, 0xbfb8aa3b, v55
	v_exp_f32_e32 v60, v60
	v_exp_f32_e32 v61, v61
	v_rcp_f32_e32 v58, v58
	v_rcp_f32_e32 v59, v59
	v_add_f32_e32 v60, 1.0, v60
	v_add_f32_e32 v61, 1.0, v61
	v_rcp_f32_e32 v60, v60
	v_rcp_f32_e32 v61, v61
; DI float silu_f(float g) { return g * __builtin_amdgcn_rcpf(1.f + __builtin_amdgcn_exp2f(-LOG2E * g)); }
; #define WAIT_V(n) asm volatile("s_waitcnt vmcnt(" #n ")" ::: "memory")
; #define BAR __builtin_amdgcn_s_barrier()
; template <class Get, class Epi>
; DI void gemm_stream(LAS unsigned char* lds, const int K, const int ld, Get get, Epi epi) {
;     ...
;     WAIT_V(0);
;     if (wr == 0) BAR;
;     BAR;
; DI void epi_swiglu(const Acc& acc, int brow, int pn, bf16_t* hid) {
;     ...
;     for (int ai = 0; ai < 2; ++ai)
; #pragma unroll
;         for (int m = 0; m < 4; ++m) {
;             const int r = brow + ai * 128 + wr * 64 + m * 16 + fr;
;             bf16_t* rp = hid + (size_t)r * FF + pn * 128 + wc * 32 + fq * 4;
; #pragma unroll
;             for (int n = 0; n < 2; ++n) {
;                 const f32x4 g = acc[ai][0][m][n], u = acc[ai][1][m][n];
;                 float o[4];
; #pragma unroll
;                 for (int j = 0; j < 4; ++j) o[j] = silu_f(g[j]) * u[j];
;                 st4(rp + n * 16, o[0], o[1], o[2], o[3]);
;             }
	v_pk_mul_f32 v[52:53], v[52:53], v[58:59]
	global_store_dwordx2 v[116:117], v[104:105], off
	v_pk_mul_f32 v[48:49], v[52:53], v[48:49]
	v_pk_mul_f32 v[52:53], v[54:55], v[60:61]
	v_cvt_pk_bf16_f32 v48, v48, v49
	v_pk_mul_f32 v[50:51], v[52:53], v[50:51]
	v_add_u32_e32 v52, 0x90, v147
	v_cvt_pk_bf16_f32 v49, v50, v51
	global_store_dwordx2 v[68:69], v[48:49], off offset:32
	v_mul_f32_e32 v48, 0xbfb8aa3b, v44
	v_mul_f32_e32 v49, 0xbfb8aa3b, v45
	v_exp_f32_e32 v48, v48
	v_exp_f32_e32 v49, v49
	v_mul_f32_e32 v50, 0xbfb8aa3b, v46
	v_mul_f32_e32 v51, 0xbfb8aa3b, v47
	v_exp_f32_e32 v50, v50
	v_exp_f32_e32 v51, v51
	v_add_f32_e32 v48, 1.0, v48
	v_add_f32_e32 v49, 1.0, v49
	v_rcp_f32_e32 v48, v48
	v_rcp_f32_e32 v49, v49
	v_add_f32_e32 v50, 1.0, v50
	v_add_f32_e32 v51, 1.0, v51
	v_rcp_f32_e32 v50, v50
	v_rcp_f32_e32 v51, v51
	v_pk_mul_f32 v[44:45], v[44:45], v[48:49]
	v_mad_i64_i32 v[52:53], s[10:11], v52, s23, v[140:141]
	v_pk_mul_f32 v[40:41], v[44:45], v[40:41]
	v_pk_mul_f32 v[44:45], v[46:47], v[50:51]
	v_cvt_pk_bf16_f32 v40, v40, v41
	v_mul_f32_e32 v41, 0xbfb8aa3b, v36
	v_pk_mul_f32 v[42:43], v[44:45], v[42:43]
	v_exp_f32_e32 v44, v41
	v_mul_f32_e32 v41, 0xbfb8aa3b, v37
	v_exp_f32_e32 v45, v41
	v_cvt_pk_bf16_f32 v41, v42, v43
	v_add_f32_e32 v42, 1.0, v44
	v_mul_f32_e32 v44, 0xbfb8aa3b, v38
	v_add_f32_e32 v43, 1.0, v45
	v_mul_f32_e32 v45, 0xbfb8aa3b, v39
	v_exp_f32_e32 v44, v44
	v_exp_f32_e32 v45, v45
	v_rcp_f32_e32 v42, v42
	v_rcp_f32_e32 v43, v43
	v_add_f32_e32 v44, 1.0, v44
	v_add_f32_e32 v45, 1.0, v45
	v_rcp_f32_e32 v44, v44
	v_rcp_f32_e32 v45, v45
	v_pk_mul_f32 v[36:37], v[36:37], v[42:43]
	global_store_dwordx2 v[100:101], v[88:89], off
	v_pk_mul_f32 v[32:33], v[36:37], v[32:33]
	v_pk_mul_f32 v[36:37], v[38:39], v[44:45]
	v_cvt_pk_bf16_f32 v32, v32, v33
	v_pk_mul_f32 v[34:35], v[36:37], v[34:35]
	v_add_u32_e32 v36, 0xa0, v147
	v_cvt_pk_bf16_f32 v33, v34, v35
	global_store_dwordx2 v[52:53], v[32:33], off offset:32
	v_mul_f32_e32 v32, 0xbfb8aa3b, v28
	v_mul_f32_e32 v33, 0xbfb8aa3b, v29
	v_exp_f32_e32 v32, v32
	v_exp_f32_e32 v33, v33
	v_mul_f32_e32 v34, 0xbfb8aa3b, v30
	v_mul_f32_e32 v35, 0xbfb8aa3b, v31
	v_exp_f32_e32 v34, v34
	v_exp_f32_e32 v35, v35
	v_add_f32_e32 v32, 1.0, v32
	v_add_f32_e32 v33, 1.0, v33
	v_rcp_f32_e32 v32, v32
	v_rcp_f32_e32 v33, v33
	v_add_f32_e32 v34, 1.0, v34
	v_add_f32_e32 v35, 1.0, v35
	v_rcp_f32_e32 v34, v34
	v_rcp_f32_e32 v35, v35
	v_pk_mul_f32 v[28:29], v[28:29], v[32:33]
	v_mad_i64_i32 v[36:37], s[10:11], v36, s23, v[140:141]
	v_pk_mul_f32 v[24:25], v[28:29], v[24:25]
	v_pk_mul_f32 v[28:29], v[30:31], v[34:35]
	v_cvt_pk_bf16_f32 v24, v24, v25
	v_mul_f32_e32 v25, 0xbfb8aa3b, v20
	v_pk_mul_f32 v[26:27], v[28:29], v[26:27]
	v_exp_f32_e32 v28, v25
	v_mul_f32_e32 v25, 0xbfb8aa3b, v21
	v_exp_f32_e32 v29, v25
	v_cvt_pk_bf16_f32 v25, v26, v27
	v_add_f32_e32 v26, 1.0, v28
	v_mul_f32_e32 v28, 0xbfb8aa3b, v22
	v_add_f32_e32 v27, 1.0, v29
	v_mul_f32_e32 v29, 0xbfb8aa3b, v23
	v_exp_f32_e32 v28, v28
	v_exp_f32_e32 v29, v29
	v_rcp_f32_e32 v26, v26
	v_rcp_f32_e32 v27, v27
	v_add_f32_e32 v28, 1.0, v28
	v_add_f32_e32 v29, 1.0, v29
	v_rcp_f32_e32 v28, v28
	v_rcp_f32_e32 v29, v29
	v_pk_mul_f32 v[20:21], v[20:21], v[26:27]
	global_store_dwordx2 v[84:85], v[72:73], off
	v_pk_mul_f32 v[16:17], v[20:21], v[16:17]
	v_pk_mul_f32 v[20:21], v[22:23], v[28:29]
	v_cvt_pk_bf16_f32 v16, v16, v17
	v_pk_mul_f32 v[18:19], v[20:21], v[18:19]
	v_add_u32_e32 v20, 0xb0, v147
	v_cvt_pk_bf16_f32 v17, v18, v19
	global_store_dwordx2 v[36:37], v[16:17], off offset:32
	v_mul_f32_e32 v16, 0xbfb8aa3b, v12
	v_mul_f32_e32 v17, 0xbfb8aa3b, v13
	v_exp_f32_e32 v16, v16
	v_exp_f32_e32 v17, v17
	v_mul_f32_e32 v18, 0xbfb8aa3b, v14
	v_mul_f32_e32 v19, 0xbfb8aa3b, v15
	v_exp_f32_e32 v18, v18
	v_exp_f32_e32 v19, v19
	v_add_f32_e32 v16, 1.0, v16
	v_add_f32_e32 v17, 1.0, v17
	v_rcp_f32_e32 v16, v16
	v_rcp_f32_e32 v17, v17
	v_add_f32_e32 v18, 1.0, v18
	v_add_f32_e32 v19, 1.0, v19
	v_rcp_f32_e32 v18, v18
	v_rcp_f32_e32 v19, v19
	v_pk_mul_f32 v[12:13], v[12:13], v[16:17]
	v_mad_i64_i32 v[20:21], s[10:11], v20, s23, v[140:141]
	v_pk_mul_f32 v[8:9], v[12:13], v[8:9]
	v_pk_mul_f32 v[12:13], v[14:15], v[18:19]
	v_cvt_pk_bf16_f32 v8, v8, v9
	v_mul_f32_e32 v9, 0xbfb8aa3b, v4
	v_pk_mul_f32 v[10:11], v[12:13], v[10:11]
	v_exp_f32_e32 v12, v9
	v_mul_f32_e32 v9, 0xbfb8aa3b, v5
	v_exp_f32_e32 v13, v9
	v_cvt_pk_bf16_f32 v9, v10, v11
	v_add_f32_e32 v10, 1.0, v12
	v_mul_f32_e32 v12, 0xbfb8aa3b, v6
	v_add_f32_e32 v11, 1.0, v13
	v_mul_f32_e32 v13, 0xbfb8aa3b, v7
	v_exp_f32_e32 v12, v12
	v_exp_f32_e32 v13, v13
	v_rcp_f32_e32 v10, v10
	v_rcp_f32_e32 v11, v11
	v_add_f32_e32 v12, 1.0, v12
	v_add_f32_e32 v13, 1.0, v13
	v_rcp_f32_e32 v12, v12
	v_rcp_f32_e32 v13, v13
	v_pk_mul_f32 v[4:5], v[4:5], v[10:11]
	s_mov_b64 s[10:11], s[6:7]
	v_pk_mul_f32 v[0:1], v[4:5], v[0:1]
	v_pk_mul_f32 v[4:5], v[6:7], v[12:13]
	v_cvt_pk_bf16_f32 v0, v0, v1
	v_pk_mul_f32 v[2:3], v[4:5], v[2:3]
	global_store_dwordx2 v[68:69], v[56:57], off
	v_cvt_pk_bf16_f32 v1, v2, v3
	global_store_dwordx2 v[52:53], v[40:41], off
	global_store_dwordx2 v[36:37], v[24:25], off
	global_store_dwordx2 v[20:21], v[8:9], off
	global_store_dwordx2 v[20:21], v[0:1], off offset:32
	s_cbranch_vccz .LBB0_1627
	s_waitcnt vmcnt(0)
	s_cmpk_gt_u32 s2, 0xff
	s_cbranch_scc1 .LBB0_1634
	s_barrier

; #define WAIT_V(n) asm volatile("s_waitcnt vmcnt(" #n ")" ::: "memory")
; #define WAIT_L(n) asm volatile("s_waitcnt lgkmcnt(" #n ")" ::: "memory")
; #define BAR __builtin_amdgcn_s_barrier()
; #define SCHED __builtin_amdgcn_sched_barrier(0)
; template <class Get, class Epi>
; DI void gemm_stream(LAS unsigned char* lds, const int K, const int ld, Get get, Epi epi) {
;     ...
;             LDB(B0, 0, 0); SCHED; LDA(At, 0, 0); STAGE(SAo(1, 1), a1 + hstep);
;             WAIT_L(8); BAR; WAIT_L(0); MMA(0, 0, At, B0); BAR; SCHED;
;             LDB(B1, 0, 1); STAGE(SBo(0, 0), b2);
;             BAR; WAIT_L(0); MMA(0, 1, At, B1); BAR;
;             LDA(At, 0, 1); STAGE(SAo(0, 0), a2);
;             BAR; WAIT_L(0); MMA(1, 0, At, B0); BAR; SCHED;
;             STAGE(SBo(0, 1), b2 + hstep);
;             WAIT_V(6); BAR; MMA(1, 1, At, B1); BAR;
;             LDB(B0, 1, 0); SCHED; LDA(At, 1, 0); STAGE(SAo(0, 1), a2 + hstep);
;             WAIT_L(8); BAR; WAIT_L(0); MMA(0, 0, At, B0); BAR; SCHED;
;             LDB(B1, 1, 1); STAGE(SBo(1, 0), b3);
;             BAR; WAIT_L(0); MMA(0, 1, At, B1); BAR;
;             LDA(At, 1, 1); STAGE(SAo(1, 0), a3);
;             BAR; WAIT_L(0); MMA(1, 0, At, B0); BAR; SCHED;
;             STAGE(SBo(1, 1), b3 + hstep);
;             WAIT_V(6); BAR; MMA(1, 1, At, B1); BAR;
.LBB0_1697:
	ds_read_b128 v[128:131], v199
	ds_read_b128 v[132:135], v199 offset:1024
	ds_read_b128 v[136:139], v199 offset:2048
	ds_read_b128 v[140:143], v199 offset:3072
	s_add_u32 s8, s6, 0x100
	s_addc_u32 s9, s7, 0
	s_cmpk_eq_i32 s16, 0x54
	s_cselect_b32 s13, s39, s9
	s_cselect_b32 s12, s38, s8
	s_cselect_b32 s11, s41, s15
	s_cselect_b32 s10, s40, s14
	s_mov_b32 m0, s63
	ds_read_b128 v[144:147], v200
	ds_read_b128 v[148:151], v200 offset:1024
	ds_read_b128 v[152:155], v200 offset:2048
	ds_read_b128 v[156:159], v200 offset:3072
	ds_read_b128 v[160:163], v200 offset:4096
	ds_read_b128 v[174:177], v200 offset:5120
	ds_read_b128 v[178:181], v200 offset:6144
	ds_read_b128 v[182:185], v200 offset:7168
	global_load_lds_dwordx4 v168, s[6:7]
	s_mov_b32 m0, s74
	s_nop 0
	global_load_lds_dwordx4 v170, s[6:7]
	s_waitcnt lgkmcnt(8)
	s_barrier
	s_waitcnt lgkmcnt(0)
	v_mfma_f32_16x16x32_bf16 v[124:127], v[128:131], v[144:147], v[124:127]
	v_mfma_f32_16x16x32_bf16 v[92:95], v[136:139], v[144:147], v[92:95]
	v_mfma_f32_16x16x32_bf16 v[120:123], v[128:131], v[152:155], v[120:123]
	v_mfma_f32_16x16x32_bf16 v[88:91], v[136:139], v[152:155], v[88:91]
	v_mfma_f32_16x16x32_bf16 v[116:119], v[128:131], v[160:163], v[116:119]
	v_mfma_f32_16x16x32_bf16 v[84:87], v[136:139], v[160:163], v[84:87]
	v_mfma_f32_16x16x32_bf16 v[112:115], v[128:131], v[178:181], v[112:115]
	v_mfma_f32_16x16x32_bf16 v[80:83], v[136:139], v[178:181], v[80:83]
	v_mfma_f32_16x16x32_bf16 v[124:127], v[132:135], v[148:151], v[124:127]
	v_mfma_f32_16x16x32_bf16 v[92:95], v[140:143], v[148:151], v[92:95]
	v_mfma_f32_16x16x32_bf16 v[120:123], v[132:135], v[156:159], v[120:123]
	v_mfma_f32_16x16x32_bf16 v[88:91], v[140:143], v[156:159], v[88:91]
	v_mfma_f32_16x16x32_bf16 v[116:119], v[132:135], v[174:177], v[116:119]
	v_mfma_f32_16x16x32_bf16 v[84:87], v[140:143], v[174:177], v[84:87]
	v_mfma_f32_16x16x32_bf16 v[112:115], v[132:135], v[182:185], v[112:115]
	v_mfma_f32_16x16x32_bf16 v[80:83], v[140:143], v[182:185], v[80:83]
	s_barrier
	s_mov_b32 m0, s75
	v_lshl_add_u64 v[208:209], s[10:11], 0, v[164:165]
	ds_read_b128 v[186:189], v201
	ds_read_b128 v[190:193], v201 offset:1024
	ds_read_b128 v[194:197], v201 offset:2048
	ds_read_b128 v[202:205], v201 offset:3072
	global_load_lds_dwordx4 v[208:209], off
	v_lshl_add_u64 v[210:211], s[10:11], 0, v[166:167]
	s_mov_b32 m0, s76
	s_nop 0
	global_load_lds_dwordx4 v[210:211], off
	s_barrier
	s_waitcnt lgkmcnt(0)
	v_mfma_f32_16x16x32_bf16 v[60:63], v[186:189], v[144:147], v[60:63]
	v_mfma_f32_16x16x32_bf16 v[28:31], v[194:197], v[144:147], v[28:31]
	v_mfma_f32_16x16x32_bf16 v[56:59], v[186:189], v[152:155], v[56:59]
	v_mfma_f32_16x16x32_bf16 v[24:27], v[194:197], v[152:155], v[24:27]
	v_mfma_f32_16x16x32_bf16 v[52:55], v[186:189], v[160:163], v[52:55]
	v_mfma_f32_16x16x32_bf16 v[20:23], v[194:197], v[160:163], v[20:23]
	v_mfma_f32_16x16x32_bf16 v[48:51], v[186:189], v[178:181], v[48:51]
	v_mfma_f32_16x16x32_bf16 v[16:19], v[194:197], v[178:181], v[16:19]
	v_mfma_f32_16x16x32_bf16 v[60:63], v[190:193], v[148:151], v[60:63]
	v_mfma_f32_16x16x32_bf16 v[28:31], v[202:205], v[148:151], v[28:31]
	v_mfma_f32_16x16x32_bf16 v[56:59], v[190:193], v[156:159], v[56:59]
	v_mfma_f32_16x16x32_bf16 v[24:27], v[202:205], v[156:159], v[24:27]
	v_mfma_f32_16x16x32_bf16 v[52:55], v[190:193], v[174:177], v[52:55]
	v_mfma_f32_16x16x32_bf16 v[20:23], v[202:205], v[174:177], v[20:23]
	v_mfma_f32_16x16x32_bf16 v[48:51], v[190:193], v[182:185], v[48:51]
	v_mfma_f32_16x16x32_bf16 v[16:19], v[202:205], v[182:185], v[16:19]
	s_barrier
	s_mov_b32 m0, s23
	v_lshl_add_u64 v[212:213], s[12:13], 0, v[164:165]
	ds_read_b128 v[144:147], v200 offset:16384
	ds_read_b128 v[148:151], v200 offset:17408
	ds_read_b128 v[152:155], v200 offset:18432
	ds_read_b128 v[156:159], v200 offset:19456
	ds_read_b128 v[160:163], v200 offset:20480
	ds_read_b128 v[174:177], v200 offset:21504
	ds_read_b128 v[178:181], v200 offset:22528
	ds_read_b128 v[182:185], v200 offset:23552
	global_load_lds_dwordx4 v[212:213], off
	v_lshl_add_u64 v[214:215], s[12:13], 0, v[166:167]
	s_mov_b32 m0, s35
	s_nop 0
	global_load_lds_dwordx4 v[214:215], off
	s_barrier
	s_waitcnt lgkmcnt(0)
	v_mfma_f32_16x16x32_bf16 v[108:111], v[128:131], v[144:147], v[108:111]
	v_mfma_f32_16x16x32_bf16 v[76:79], v[136:139], v[144:147], v[76:79]
	v_mfma_f32_16x16x32_bf16 v[104:107], v[128:131], v[152:155], v[104:107]
	v_mfma_f32_16x16x32_bf16 v[72:75], v[136:139], v[152:155], v[72:75]
	v_mfma_f32_16x16x32_bf16 v[100:103], v[128:131], v[160:163], v[100:103]
	v_mfma_f32_16x16x32_bf16 v[68:71], v[136:139], v[160:163], v[68:71]
	v_mfma_f32_16x16x32_bf16 v[96:99], v[128:131], v[178:181], v[96:99]
	v_mfma_f32_16x16x32_bf16 v[64:67], v[136:139], v[178:181], v[64:67]
	v_mfma_f32_16x16x32_bf16 v[108:111], v[132:135], v[148:151], v[108:111]
	v_mfma_f32_16x16x32_bf16 v[76:79], v[140:143], v[148:151], v[76:79]
	v_mfma_f32_16x16x32_bf16 v[104:107], v[132:135], v[156:159], v[104:107]
	v_mfma_f32_16x16x32_bf16 v[72:75], v[140:143], v[156:159], v[72:75]
	v_mfma_f32_16x16x32_bf16 v[100:103], v[132:135], v[174:177], v[100:103]
	v_mfma_f32_16x16x32_bf16 v[68:71], v[140:143], v[174:177], v[68:71]
	v_mfma_f32_16x16x32_bf16 v[96:99], v[132:135], v[182:185], v[96:99]
	v_mfma_f32_16x16x32_bf16 v[64:67], v[140:143], v[182:185], v[64:67]
	s_barrier
	s_add_u32 s6, s10, 0x160000
	s_addc_u32 s7, s11, 0
	s_mov_b32 m0, s77
	v_lshl_add_u64 v[128:129], s[6:7], 0, v[164:165]
	global_load_lds_dwordx4 v[128:129], off
	s_mov_b32 m0, s78
	s_nop 0
	global_load_lds_dwordx4 v166, s[6:7]
	s_waitcnt vmcnt(6)
	s_barrier
; #define WAIT_V(n) asm volatile("s_waitcnt vmcnt(" #n ")" ::: "memory")
; #define WAIT_L(n) asm volatile("s_waitcnt lgkmcnt(" #n ")" ::: "memory")
; #define BAR __builtin_amdgcn_s_barrier()
; #define SCHED __builtin_amdgcn_sched_barrier(0)
; template <class Get, class Epi>
; DI void gemm_stream(LAS unsigned char* lds, const int K, const int ld, Get get, Epi epi) {
;     ...
;             LDB(B0, 0, 0); SCHED; LDA(At, 0, 0); STAGE(SAo(1, 1), a1 + hstep);
;             WAIT_L(8); BAR; WAIT_L(0); MMA(0, 0, At, B0); BAR; SCHED;
;             LDB(B1, 0, 1); STAGE(SBo(0, 0), b2);
;             BAR; WAIT_L(0); MMA(0, 1, At, B1); BAR;
;             LDA(At, 0, 1); STAGE(SAo(0, 0), a2);
;             BAR; WAIT_L(0); MMA(1, 0, At, B0); BAR; SCHED;
;             STAGE(SBo(0, 1), b2 + hstep);
;             WAIT_V(6); BAR; MMA(1, 1, At, B1); BAR;
;             LDB(B0, 1, 0); SCHED; LDA(At, 1, 0); STAGE(SAo(0, 1), a2 + hstep);
;             WAIT_L(8); BAR; WAIT_L(0); MMA(0, 0, At, B0); BAR; SCHED;
;             LDB(B1, 1, 1); STAGE(SBo(1, 0), b3);
;             BAR; WAIT_L(0); MMA(0, 1, At, B1); BAR;
;             LDA(At, 1, 1); STAGE(SAo(1, 0), a3);
;             BAR; WAIT_L(0); MMA(1, 0, At, B0); BAR; SCHED;
;             STAGE(SBo(1, 1), b3 + hstep);
;             WAIT_V(6); BAR; MMA(1, 1, At, B1); BAR;
	v_mfma_f32_16x16x32_bf16 v[44:47], v[186:189], v[144:147], v[44:47]
	v_mfma_f32_16x16x32_bf16 v[12:15], v[194:197], v[144:147], v[12:15]
	v_mfma_f32_16x16x32_bf16 v[40:43], v[186:189], v[152:155], v[40:43]
	v_mfma_f32_16x16x32_bf16 v[8:11], v[194:197], v[152:155], v[8:11]
	v_mfma_f32_16x16x32_bf16 v[36:39], v[186:189], v[160:163], v[36:39]
	v_mfma_f32_16x16x32_bf16 v[4:7], v[194:197], v[160:163], v[4:7]
	v_mfma_f32_16x16x32_bf16 v[32:35], v[186:189], v[178:181], v[32:35]
	v_mfma_f32_16x16x32_bf16 v[0:3], v[194:197], v[178:181], v[0:3]
	v_mfma_f32_16x16x32_bf16 v[44:47], v[190:193], v[148:151], v[44:47]
	v_mfma_f32_16x16x32_bf16 v[12:15], v[202:205], v[148:151], v[12:15]
	v_mfma_f32_16x16x32_bf16 v[40:43], v[190:193], v[156:159], v[40:43]
	v_mfma_f32_16x16x32_bf16 v[8:11], v[202:205], v[156:159], v[8:11]
	v_mfma_f32_16x16x32_bf16 v[36:39], v[190:193], v[174:177], v[36:39]
	v_mfma_f32_16x16x32_bf16 v[4:7], v[202:205], v[174:177], v[4:7]
	v_mfma_f32_16x16x32_bf16 v[32:35], v[190:193], v[182:185], v[32:35]
	v_mfma_f32_16x16x32_bf16 v[0:3], v[202:205], v[182:185], v[0:3]
	s_add_i32 s17, 16, 0x18000
	v_add_u32_e32 v140, s17, v198
	s_barrier
	ds_read_b128 v[128:131], v140
	ds_read_b128 v[132:135], v140 offset:1024
	ds_read_b128 v[136:139], v140 offset:2048
	ds_read_b128 v[140:143], v140 offset:3072
	s_add_u32 s6, s12, 0x160000
	s_addc_u32 s7, s13, 0
	s_mov_b32 m0, s54
	ds_read_b128 v[144:147], v200 offset:32768
	ds_read_b128 v[148:151], v200 offset:33792
	ds_read_b128 v[152:155], v200 offset:34816
	ds_read_b128 v[156:159], v200 offset:35840
	ds_read_b128 v[160:163], v200 offset:36864
	ds_read_b128 v[174:177], v200 offset:37888
	ds_read_b128 v[178:181], v200 offset:38912
	ds_read_b128 v[182:185], v200 offset:39936
	global_load_lds_dwordx4 v164, s[6:7]
	s_mov_b32 m0, s55
	s_nop 0
	global_load_lds_dwordx4 v166, s[6:7]
	s_waitcnt lgkmcnt(8)
	s_barrier
	s_waitcnt lgkmcnt(0)
	v_mfma_f32_16x16x32_bf16 v[124:127], v[128:131], v[144:147], v[124:127]
	v_mfma_f32_16x16x32_bf16 v[92:95], v[136:139], v[144:147], v[92:95]
	v_mfma_f32_16x16x32_bf16 v[120:123], v[128:131], v[152:155], v[120:123]
	v_mfma_f32_16x16x32_bf16 v[88:91], v[136:139], v[152:155], v[88:91]
	v_mfma_f32_16x16x32_bf16 v[116:119], v[128:131], v[160:163], v[116:119]
	v_mfma_f32_16x16x32_bf16 v[84:87], v[136:139], v[160:163], v[84:87]
	v_mfma_f32_16x16x32_bf16 v[112:115], v[128:131], v[178:181], v[112:115]
	v_mfma_f32_16x16x32_bf16 v[80:83], v[136:139], v[178:181], v[80:83]
	v_mfma_f32_16x16x32_bf16 v[124:127], v[132:135], v[148:151], v[124:127]
	v_mfma_f32_16x16x32_bf16 v[92:95], v[140:143], v[148:151], v[92:95]
	v_mfma_f32_16x16x32_bf16 v[120:123], v[132:135], v[156:159], v[120:123]
	v_mfma_f32_16x16x32_bf16 v[88:91], v[140:143], v[156:159], v[88:91]
	v_mfma_f32_16x16x32_bf16 v[116:119], v[132:135], v[174:177], v[116:119]
	v_mfma_f32_16x16x32_bf16 v[84:87], v[140:143], v[174:177], v[84:87]
	v_mfma_f32_16x16x32_bf16 v[112:115], v[132:135], v[182:185], v[112:115]
	v_mfma_f32_16x16x32_bf16 v[80:83], v[140:143], v[182:185], v[80:83]
	s_barrier
	s_add_i32 s12, 16, 0x1c000
	s_add_i32 s6, s17, s21
	v_add_u32_e32 v202, s12, v198
	v_lshl_add_u64 v[208:209], v[208:209], 0, s[0:1]
	s_mov_b32 m0, s6
	ds_read_b128 v[186:189], v202
	ds_read_b128 v[190:193], v202 offset:1024
	ds_read_b128 v[194:197], v202 offset:2048
	ds_read_b128 v[202:205], v202 offset:3072
	global_load_lds_dwordx4 v[208:209], off
	v_lshl_add_u64 v[208:209], v[210:211], 0, s[0:1]
	s_add_i32 m0, s6, 0x2000
	s_nop 0
	global_load_lds_dwordx4 v[208:209], off
	s_barrier
	s_waitcnt lgkmcnt(0)
	v_mfma_f32_16x16x32_bf16 v[60:63], v[186:189], v[144:147], v[60:63]
	v_mfma_f32_16x16x32_bf16 v[28:31], v[194:197], v[144:147], v[28:31]
	v_mfma_f32_16x16x32_bf16 v[56:59], v[186:189], v[152:155], v[56:59]
	v_mfma_f32_16x16x32_bf16 v[24:27], v[194:197], v[152:155], v[24:27]
	v_mfma_f32_16x16x32_bf16 v[52:55], v[186:189], v[160:163], v[52:55]
	v_mfma_f32_16x16x32_bf16 v[20:23], v[194:197], v[160:163], v[20:23]
	v_mfma_f32_16x16x32_bf16 v[48:51], v[186:189], v[178:181], v[48:51]
	v_mfma_f32_16x16x32_bf16 v[16:19], v[194:197], v[178:181], v[16:19]
	v_mfma_f32_16x16x32_bf16 v[60:63], v[190:193], v[148:151], v[60:63]
	v_mfma_f32_16x16x32_bf16 v[28:31], v[202:205], v[148:151], v[28:31]
	v_mfma_f32_16x16x32_bf16 v[56:59], v[190:193], v[156:159], v[56:59]
	v_mfma_f32_16x16x32_bf16 v[24:27], v[202:205], v[156:159], v[24:27]
	v_mfma_f32_16x16x32_bf16 v[52:55], v[190:193], v[174:177], v[52:55]
	v_mfma_f32_16x16x32_bf16 v[20:23], v[202:205], v[174:177], v[20:23]
	v_mfma_f32_16x16x32_bf16 v[48:51], v[190:193], v[182:185], v[48:51]
	v_mfma_f32_16x16x32_bf16 v[16:19], v[202:205], v[182:185], v[16:19]
	s_barrier
	s_mov_b32 m0, s56
	v_lshl_add_u64 v[208:209], v[212:213], 0, s[0:1]
	ds_read_b128 v[144:147], v200 offset:49152
	ds_read_b128 v[148:151], v200 offset:50176
	ds_read_b128 v[152:155], v200 offset:51200
	ds_read_b128 v[156:159], v200 offset:52224
	ds_read_b128 v[160:163], v200 offset:53248
	ds_read_b128 v[174:177], v200 offset:54272
	ds_read_b128 v[178:181], v200 offset:55296
	ds_read_b128 v[182:185], v200 offset:56320
	global_load_lds_dwordx4 v[208:209], off
	v_lshl_add_u64 v[208:209], v[214:215], 0, s[0:1]
	s_mov_b32 m0, s57
	s_nop 0
	global_load_lds_dwordx4 v[208:209], off
	s_barrier
; #define WAIT_V(n) asm volatile("s_waitcnt vmcnt(" #n ")" ::: "memory")
; #define WAIT_L(n) asm volatile("s_waitcnt lgkmcnt(" #n ")" ::: "memory")
; #define BAR __builtin_amdgcn_s_barrier()
; #define SCHED __builtin_amdgcn_sched_barrier(0)
; template <class Get, class Epi>
; DI void gemm_stream(LAS unsigned char* lds, const int K, const int ld, Get get, Epi epi) {
;     ...
;             LDB(B1, 1, 1); STAGE(SBo(1, 0), b3);
;             BAR; WAIT_L(0); MMA(0, 1, At, B1); BAR;
;             LDA(At, 1, 1); STAGE(SAo(1, 0), a3);
;             BAR; WAIT_L(0); MMA(1, 0, At, B0); BAR; SCHED;
;             STAGE(SBo(1, 1), b3 + hstep);
;             WAIT_V(6); BAR; MMA(1, 1, At, B1); BAR;
;         }
;         epi(acc, cur);
; DI void epi_resid(const Acc& acc, const P& p, int brow, int bcol, int layer, int gch, bool from_input) {
;     EPI_IDX
;     const float* gate = modv(p, layer, brow, gch);
; #pragma unroll
;     for (int bj = 0; bj < 2; ++bj)
; #pragma unroll
;         for (int n = 0; n < 2; ++n) {
;             const int c0 = bcol + bj * 128 + wc * 32 + n * 16 + fq * 4;
;             const f32x4 g = *(const f32x4*)(gate + c0);
;             f32x4 xv[2][4];
; #pragma unroll
;             for (int ai = 0; ai < 2; ++ai)
; #pragma unroll
;                 for (int m = 0; m < 4; ++m) {
;                     const int r = brow + ai * 128 + wr * 64 + m * 16 + fr;
;                     const float* sp = (from_input ? inrow(p, r) : xrow(p, r)) + c0;
;                     xv[ai][m] = *(const f32x4*)sp;
;                 }
;             __builtin_amdgcn_sched_barrier(0);
; #pragma unroll
;             for (int ai = 0; ai < 2; ++ai)
; #pragma unroll
;                 for (int m = 0; m < 4; ++m) {
;                     const int r = brow + ai * 128 + wr * 64 + m * 16 + fr;
;                     *(f32x4*)(xrow(p, r) + c0) = xv[ai][m] + g * acc[ai][bj][m][n];
;                 }
;             __builtin_amdgcn_sched_barrier(0);
;         }
	s_waitcnt lgkmcnt(0)
	v_mfma_f32_16x16x32_bf16 v[108:111], v[128:131], v[144:147], v[108:111]
	v_mfma_f32_16x16x32_bf16 v[76:79], v[136:139], v[144:147], v[76:79]
	v_mfma_f32_16x16x32_bf16 v[104:107], v[128:131], v[152:155], v[104:107]
	v_mfma_f32_16x16x32_bf16 v[72:75], v[136:139], v[152:155], v[72:75]
	v_mfma_f32_16x16x32_bf16 v[100:103], v[128:131], v[160:163], v[100:103]
	v_mfma_f32_16x16x32_bf16 v[68:71], v[136:139], v[160:163], v[68:71]
	v_mfma_f32_16x16x32_bf16 v[96:99], v[128:131], v[178:181], v[96:99]
	v_mfma_f32_16x16x32_bf16 v[64:67], v[136:139], v[178:181], v[64:67]
	v_mfma_f32_16x16x32_bf16 v[108:111], v[132:135], v[148:151], v[108:111]
	v_mfma_f32_16x16x32_bf16 v[76:79], v[140:143], v[148:151], v[76:79]
	v_mfma_f32_16x16x32_bf16 v[104:107], v[132:135], v[156:159], v[104:107]
	v_mfma_f32_16x16x32_bf16 v[72:75], v[140:143], v[156:159], v[72:75]
	v_mfma_f32_16x16x32_bf16 v[100:103], v[132:135], v[174:177], v[100:103]
	v_mfma_f32_16x16x32_bf16 v[68:71], v[140:143], v[174:177], v[68:71]
	v_mfma_f32_16x16x32_bf16 v[96:99], v[132:135], v[182:185], v[96:99]
	v_mfma_f32_16x16x32_bf16 v[64:67], v[140:143], v[182:185], v[64:67]
	s_barrier
	s_add_u32 s6, s10, 0x160080
	s_addc_u32 s7, s11, 0
	s_add_i32 s10, s12, s21
	s_mov_b32 m0, s10
	s_nop 0
	global_load_lds_dwordx4 v164, s[6:7]
	s_add_i32 m0, s10, 0x2000
	s_nop 0
	global_load_lds_dwordx4 v166, s[6:7]
	s_add_i32 s16, s16, 2
	s_add_u32 s14, s14, 0x100
	s_addc_u32 s15, s15, 0
	s_cmpk_gt_u32 s16, 0x55
	s_mov_b64 s[6:7], s[8:9]
	s_waitcnt vmcnt(6)
	s_barrier
	v_mfma_f32_16x16x32_bf16 v[44:47], v[186:189], v[144:147], v[44:47]
	v_mfma_f32_16x16x32_bf16 v[12:15], v[194:197], v[144:147], v[12:15]
	v_mfma_f32_16x16x32_bf16 v[40:43], v[186:189], v[152:155], v[40:43]
	v_mfma_f32_16x16x32_bf16 v[8:11], v[194:197], v[152:155], v[8:11]
	v_mfma_f32_16x16x32_bf16 v[36:39], v[186:189], v[160:163], v[36:39]
	v_mfma_f32_16x16x32_bf16 v[4:7], v[194:197], v[160:163], v[4:7]
	v_mfma_f32_16x16x32_bf16 v[32:35], v[186:189], v[178:181], v[32:35]
	v_mfma_f32_16x16x32_bf16 v[0:3], v[194:197], v[178:181], v[0:3]
	v_mfma_f32_16x16x32_bf16 v[44:47], v[190:193], v[148:151], v[44:47]
	v_mfma_f32_16x16x32_bf16 v[12:15], v[202:205], v[148:151], v[12:15]
	v_mfma_f32_16x16x32_bf16 v[40:43], v[190:193], v[156:159], v[40:43]
	v_mfma_f32_16x16x32_bf16 v[8:11], v[202:205], v[156:159], v[8:11]
	v_mfma_f32_16x16x32_bf16 v[36:39], v[190:193], v[174:177], v[36:39]
	v_mfma_f32_16x16x32_bf16 v[4:7], v[202:205], v[174:177], v[4:7]
	v_mfma_f32_16x16x32_bf16 v[32:35], v[190:193], v[182:185], v[32:35]
	v_mfma_f32_16x16x32_bf16 v[0:3], v[202:205], v[182:185], v[0:3]
	s_barrier
	s_cbranch_scc0 .LBB0_1697
	s_lshl_b32 s12, s3, 21
	s_lshl_b32 s13, s2, 10
	s_lshr_b32 s16, s3, 4
	s_add_u32 s12, s12, s13
	s_mul_i32 s16, s16, 6
	s_add_i32 s16, s16, 5
	s_lshl_b32 s16, s16, 13
	s_add_u32 s16, s16, s13
	s_add_u32 s10, s26, s16
	s_addc_u32 s11, s27, 0
	s_add_u32 s6, s24, s12
	s_addc_u32 s7, s25, 0
	v_lshrrev_b32_e32 v224, 6, v206
	v_and_b32_e32 v225, 3, v224
	v_lshrrev_b32_e32 v224, 2, v224
	v_and_b32_e32 v205, 15, v206
	v_bfe_u32 v226, v206, 4, 2
	v_lshl_add_u32 v225, v225, 3, v226
	v_lshl_add_u32 v224, v224, 6, v205
	v_lshlrev_b32_e32 v205, 4, v225
	v_lshl_add_u32 v203, v224, 13, v205
	v_mov_b32_e32 v204, v203
	global_load_dwordx4 v[128:131], v205, s[10:11] offset:0
	global_load_dwordx4 v[132:135], v205, s[10:11] offset:64
	global_load_dwordx4 v[136:139], v205, s[10:11] offset:512
	global_load_dwordx4 v[140:143], v205, s[10:11] offset:576
	global_load_dwordx4 v[144:147], v203, s[6:7] offset:0
	global_load_dwordx4 v[148:151], v203, s[6:7] offset:64
	global_load_dwordx4 v[152:155], v203, s[6:7] offset:512
	global_load_dwordx4 v[156:159], v203, s[6:7] offset:576
	v_add_u32_e32 v203, 0x20000, v203
	global_load_dwordx4 v[160:163], v203, s[6:7] offset:0
	global_load_dwordx4 v[174:177], v203, s[6:7] offset:64
	global_load_dwordx4 v[178:181], v203, s[6:7] offset:512
	global_load_dwordx4 v[182:185], v203, s[6:7] offset:576
	v_add_u32_e32 v203, 0x20000, v203
	global_load_dwordx4 v[186:189], v203, s[6:7] offset:0
	global_load_dwordx4 v[190:193], v203, s[6:7] offset:64
	global_load_dwordx4 v[194:197], v203, s[6:7] offset:512
	global_load_dwordx4 v[208:211], v203, s[6:7] offset:576
	v_add_u32_e32 v203, 0x20000, v203
	global_load_dwordx4 v[212:215], v203, s[6:7] offset:0
	global_load_dwordx4 v[216:219], v203, s[6:7] offset:64
	global_load_dwordx4 v[220:223], v203, s[6:7] offset:512
	global_load_dwordx4 v[224:227], v203, s[6:7] offset:576
	v_add_u32_e32 v203, 0xa0000, v203
	s_waitcnt vmcnt(12)
	v_pk_fma_f32 v[124:125], v[124:125], v[128:129], v[144:145]
	v_pk_fma_f32 v[126:127], v[126:127], v[130:131], v[146:147]
	v_pk_fma_f32 v[92:93], v[92:93], v[132:133], v[148:149]
	v_pk_fma_f32 v[94:95], v[94:95], v[134:135], v[150:151]
	v_pk_fma_f32 v[60:61], v[60:61], v[136:137], v[152:153]
	v_pk_fma_f32 v[62:63], v[62:63], v[138:139], v[154:155]
	v_pk_fma_f32 v[28:29], v[28:29], v[140:141], v[156:157]
	v_pk_fma_f32 v[30:31], v[30:31], v[142:143], v[158:159]
	global_store_dwordx4 v204, v[124:127], s[6:7] offset:0
	global_store_dwordx4 v204, v[92:95], s[6:7] offset:64
	global_store_dwordx4 v204, v[60:63], s[6:7] offset:512
	global_store_dwordx4 v204, v[28:31], s[6:7] offset:576
	v_add_u32_e32 v204, 0x20000, v204
	global_load_dwordx4 v[144:147], v203, s[6:7] offset:0
	global_load_dwordx4 v[148:151], v203, s[6:7] offset:64
	global_load_dwordx4 v[152:155], v203, s[6:7] offset:512
	global_load_dwordx4 v[156:159], v203, s[6:7] offset:576
	v_add_u32_e32 v203, 0x20000, v203
	s_waitcnt vmcnt(16)
; DI void epi_resid(const Acc& acc, const P& p, int brow, int bcol, int layer, int gch, bool from_input) {
;     ...
;     for (int bj = 0; bj < 2; ++bj)
; #pragma unroll
;         for (int n = 0; n < 2; ++n) {
;             const int c0 = bcol + bj * 128 + wc * 32 + n * 16 + fq * 4;
;             const f32x4 g = *(const f32x4*)(gate + c0);
;             f32x4 xv[2][4];
; #pragma unroll
;             for (int ai = 0; ai < 2; ++ai)
; #pragma unroll
;                 for (int m = 0; m < 4; ++m) {
;                     const int r = brow + ai * 128 + wr * 64 + m * 16 + fr;
;                     const float* sp = (from_input ? inrow(p, r) : xrow(p, r)) + c0;
;                     xv[ai][m] = *(const f32x4*)sp;
;                 }
;             __builtin_amdgcn_sched_barrier(0);
; #pragma unroll
;             for (int ai = 0; ai < 2; ++ai)
; #pragma unroll
;                 for (int m = 0; m < 4; ++m) {
;                     const int r = brow + ai * 128 + wr * 64 + m * 16 + fr;
;                     *(f32x4*)(xrow(p, r) + c0) = xv[ai][m] + g * acc[ai][bj][m][n];
;                 }
;             __builtin_amdgcn_sched_barrier(0);
	v_pk_fma_f32 v[120:121], v[120:121], v[128:129], v[160:161]
	v_pk_fma_f32 v[122:123], v[122:123], v[130:131], v[162:163]
	v_pk_fma_f32 v[88:89], v[88:89], v[132:133], v[174:175]
	v_pk_fma_f32 v[90:91], v[90:91], v[134:135], v[176:177]
	v_pk_fma_f32 v[56:57], v[56:57], v[136:137], v[178:179]
	v_pk_fma_f32 v[58:59], v[58:59], v[138:139], v[180:181]
	v_pk_fma_f32 v[24:25], v[24:25], v[140:141], v[182:183]
	v_pk_fma_f32 v[26:27], v[26:27], v[142:143], v[184:185]
	global_store_dwordx4 v204, v[120:123], s[6:7] offset:0
	global_store_dwordx4 v204, v[88:91], s[6:7] offset:64
	global_store_dwordx4 v204, v[56:59], s[6:7] offset:512
	global_store_dwordx4 v204, v[24:27], s[6:7] offset:576
	v_add_u32_e32 v204, 0x20000, v204
	global_load_dwordx4 v[160:163], v203, s[6:7] offset:0
	global_load_dwordx4 v[174:177], v203, s[6:7] offset:64
	global_load_dwordx4 v[178:181], v203, s[6:7] offset:512
	global_load_dwordx4 v[182:185], v203, s[6:7] offset:576
	v_add_u32_e32 v203, 0x20000, v203
	s_waitcnt vmcnt(20)
	v_pk_fma_f32 v[116:117], v[116:117], v[128:129], v[186:187]
	v_pk_fma_f32 v[118:119], v[118:119], v[130:131], v[188:189]
	v_pk_fma_f32 v[84:85], v[84:85], v[132:133], v[190:191]
	v_pk_fma_f32 v[86:87], v[86:87], v[134:135], v[192:193]
	v_pk_fma_f32 v[52:53], v[52:53], v[136:137], v[194:195]
	v_pk_fma_f32 v[54:55], v[54:55], v[138:139], v[196:197]
	v_pk_fma_f32 v[20:21], v[20:21], v[140:141], v[208:209]
	v_pk_fma_f32 v[22:23], v[22:23], v[142:143], v[210:211]
	global_store_dwordx4 v204, v[116:119], s[6:7] offset:0
	global_store_dwordx4 v204, v[84:87], s[6:7] offset:64
	global_store_dwordx4 v204, v[52:55], s[6:7] offset:512
	global_store_dwordx4 v204, v[20:23], s[6:7] offset:576
	v_add_u32_e32 v204, 0x20000, v204
	global_load_dwordx4 v[186:189], v203, s[6:7] offset:0
	global_load_dwordx4 v[190:193], v203, s[6:7] offset:64
	global_load_dwordx4 v[194:197], v203, s[6:7] offset:512
	global_load_dwordx4 v[208:211], v203, s[6:7] offset:576
	v_add_u32_e32 v203, 0x20000, v203
	s_waitcnt vmcnt(24)
	v_pk_fma_f32 v[112:113], v[112:113], v[128:129], v[212:213]
	v_pk_fma_f32 v[114:115], v[114:115], v[130:131], v[214:215]
	v_pk_fma_f32 v[80:81], v[80:81], v[132:133], v[216:217]
	v_pk_fma_f32 v[82:83], v[82:83], v[134:135], v[218:219]
	v_pk_fma_f32 v[48:49], v[48:49], v[136:137], v[220:221]
	v_pk_fma_f32 v[50:51], v[50:51], v[138:139], v[222:223]
	v_pk_fma_f32 v[16:17], v[16:17], v[140:141], v[224:225]
	v_pk_fma_f32 v[18:19], v[18:19], v[142:143], v[226:227]
	global_store_dwordx4 v204, v[112:115], s[6:7] offset:0
	global_store_dwordx4 v204, v[80:83], s[6:7] offset:64
	global_store_dwordx4 v204, v[48:51], s[6:7] offset:512
	global_store_dwordx4 v204, v[16:19], s[6:7] offset:576
	v_add_u32_e32 v204, 0xa0000, v204
	global_load_dwordx4 v[212:215], v203, s[6:7] offset:0
	global_load_dwordx4 v[216:219], v203, s[6:7] offset:64
	global_load_dwordx4 v[220:223], v203, s[6:7] offset:512
	global_load_dwordx4 v[224:227], v203, s[6:7] offset:576
	s_waitcnt vmcnt(24)
	v_pk_fma_f32 v[108:109], v[108:109], v[128:129], v[144:145]
	v_pk_fma_f32 v[110:111], v[110:111], v[130:131], v[146:147]
	v_pk_fma_f32 v[76:77], v[76:77], v[132:133], v[148:149]
	v_pk_fma_f32 v[78:79], v[78:79], v[134:135], v[150:151]
	v_pk_fma_f32 v[44:45], v[44:45], v[136:137], v[152:153]
	v_pk_fma_f32 v[46:47], v[46:47], v[138:139], v[154:155]
	v_pk_fma_f32 v[12:13], v[12:13], v[140:141], v[156:157]
	v_pk_fma_f32 v[14:15], v[14:15], v[142:143], v[158:159]
	global_store_dwordx4 v204, v[108:111], s[6:7] offset:0
	global_store_dwordx4 v204, v[76:79], s[6:7] offset:64
	global_store_dwordx4 v204, v[44:47], s[6:7] offset:512
	global_store_dwordx4 v204, v[12:15], s[6:7] offset:576
	v_add_u32_e32 v204, 0x20000, v204
	s_waitcnt vmcnt(20)
	v_pk_fma_f32 v[104:105], v[104:105], v[128:129], v[160:161]
	v_pk_fma_f32 v[106:107], v[106:107], v[130:131], v[162:163]
	v_pk_fma_f32 v[72:73], v[72:73], v[132:133], v[174:175]
	v_pk_fma_f32 v[74:75], v[74:75], v[134:135], v[176:177]
	v_pk_fma_f32 v[40:41], v[40:41], v[136:137], v[178:179]
	v_pk_fma_f32 v[42:43], v[42:43], v[138:139], v[180:181]
	v_pk_fma_f32 v[8:9], v[8:9], v[140:141], v[182:183]
	v_pk_fma_f32 v[10:11], v[10:11], v[142:143], v[184:185]
	global_store_dwordx4 v204, v[104:107], s[6:7] offset:0
	global_store_dwordx4 v204, v[72:75], s[6:7] offset:64
	global_store_dwordx4 v204, v[40:43], s[6:7] offset:512
	global_store_dwordx4 v204, v[8:11], s[6:7] offset:576
	v_add_u32_e32 v204, 0x20000, v204
	s_waitcnt vmcnt(16)
	v_pk_fma_f32 v[100:101], v[100:101], v[128:129], v[186:187]
	v_pk_fma_f32 v[102:103], v[102:103], v[130:131], v[188:189]
	v_pk_fma_f32 v[68:69], v[68:69], v[132:133], v[190:191]
	v_pk_fma_f32 v[70:71], v[70:71], v[134:135], v[192:193]
	v_pk_fma_f32 v[36:37], v[36:37], v[136:137], v[194:195]
	v_pk_fma_f32 v[38:39], v[38:39], v[138:139], v[196:197]
	v_pk_fma_f32 v[4:5], v[4:5], v[140:141], v[208:209]
	v_pk_fma_f32 v[6:7], v[6:7], v[142:143], v[210:211]
	global_store_dwordx4 v204, v[100:103], s[6:7] offset:0
	global_store_dwordx4 v204, v[68:71], s[6:7] offset:64
	global_store_dwordx4 v204, v[36:39], s[6:7] offset:512
	global_store_dwordx4 v204, v[4:7], s[6:7] offset:576
	v_add_u32_e32 v204, 0x20000, v204
	s_waitcnt vmcnt(12)
	v_pk_fma_f32 v[96:97], v[96:97], v[128:129], v[212:213]
	v_pk_fma_f32 v[98:99], v[98:99], v[130:131], v[214:215]
	v_pk_fma_f32 v[64:65], v[64:65], v[132:133], v[216:217]
	v_pk_fma_f32 v[66:67], v[66:67], v[134:135], v[218:219]
	v_pk_fma_f32 v[32:33], v[32:33], v[136:137], v[220:221]
	v_pk_fma_f32 v[34:35], v[34:35], v[138:139], v[222:223]
	v_pk_fma_f32 v[0:1], v[0:1], v[140:141], v[224:225]
	v_pk_fma_f32 v[2:3], v[2:3], v[142:143], v[226:227]
	global_store_dwordx4 v204, v[96:99], s[6:7] offset:0
	global_store_dwordx4 v204, v[64:67], s[6:7] offset:64
	global_store_dwordx4 v204, v[32:35], s[6:7] offset:512
	global_store_dwordx4 v204, v[0:3], s[6:7] offset:576
	s_branch .Lresid_latch_ffndL0

; #define WAIT_V(n) asm volatile("s_waitcnt vmcnt(" #n ")" ::: "memory")
; #define WAIT_L(n) asm volatile("s_waitcnt lgkmcnt(" #n ")" ::: "memory")
; #define BAR __builtin_amdgcn_s_barrier()
; #define SCHED __builtin_amdgcn_sched_barrier(0)
; template <class Get, class Epi>
; DI void gemm_stream(LAS unsigned char* lds, const int K, const int ld, Get get, Epi epi) {
;     ...
;             LDB(B0, 0, 0); SCHED; LDA(At, 0, 0); STAGE(SAo(1, 1), a1 + hstep);
;             WAIT_L(8); BAR; WAIT_L(0); MMA(0, 0, At, B0); BAR; SCHED;
;             LDB(B1, 0, 1); STAGE(SBo(0, 0), b2);
;             BAR; WAIT_L(0); MMA(0, 1, At, B1); BAR;
;             LDA(At, 0, 1); STAGE(SAo(0, 0), a2);
;             BAR; WAIT_L(0); MMA(1, 0, At, B0); BAR; SCHED;
;             STAGE(SBo(0, 1), b2 + hstep);
;             WAIT_V(6); BAR; MMA(1, 1, At, B1); BAR;
;             LDB(B0, 1, 0); SCHED; LDA(At, 1, 0); STAGE(SAo(0, 1), a2 + hstep);
;             WAIT_L(8); BAR; WAIT_L(0); MMA(0, 0, At, B0); BAR; SCHED;
;             LDB(B1, 1, 1); STAGE(SBo(1, 0), b3);
;             BAR; WAIT_L(0); MMA(0, 1, At, B1); BAR;
;             LDA(At, 1, 1); STAGE(SAo(1, 0), a3);
;             BAR; WAIT_L(0); MMA(1, 0, At, B0); BAR; SCHED;
;             STAGE(SBo(1, 1), b3 + hstep);
;             WAIT_V(6); BAR; MMA(1, 1, At, B1); BAR;
.LBB0_1964:
	ds_read_b128 v[144:147], v141
	ds_read_b128 v[148:151], v141 offset:1024
	ds_read_b128 v[152:155], v141 offset:2048
	ds_read_b128 v[156:159], v141 offset:3072
	s_add_u32 s38, s36, 0x100
	s_addc_u32 s39, s37, 0
	s_cmp_eq_u32 s77, 4
	s_cselect_b32 s53, s17, s39
	s_cselect_b32 s52, s16, s38
	s_cselect_b32 s41, s19, s76
	s_cselect_b32 s40, s18, s0
	s_add_i32 m0, s20, 0xc000
	ds_read_b128 v[160:163], v142
	ds_read_b128 v[164:167], v142 offset:1024
	ds_read_b128 v[168:171], v142 offset:2048
	ds_read_b128 v[172:175], v142 offset:3072
	ds_read_b128 v[176:179], v142 offset:4096
	ds_read_b128 v[180:183], v142 offset:5120
	ds_read_b128 v[184:187], v142 offset:6144
	ds_read_b128 v[188:191], v142 offset:7168
	global_load_lds_dwordx4 v134, s[36:37]
	s_add_i32 m0, s20, 0xe000
	s_nop 0
	global_load_lds_dwordx4 v136, s[36:37]
	s_waitcnt lgkmcnt(8)
	s_barrier
	s_waitcnt lgkmcnt(0)
	v_mfma_f32_16x16x32_bf16 v[124:127], v[144:147], v[160:163], v[124:127]
	v_mfma_f32_16x16x32_bf16 v[120:123], v[152:155], v[160:163], v[120:123]
	v_mfma_f32_16x16x32_bf16 v[116:119], v[144:147], v[168:171], v[116:119]
	v_mfma_f32_16x16x32_bf16 v[112:115], v[152:155], v[168:171], v[112:115]
	v_mfma_f32_16x16x32_bf16 v[104:107], v[144:147], v[176:179], v[104:107]
	v_mfma_f32_16x16x32_bf16 v[96:99], v[152:155], v[176:179], v[96:99]
	v_mfma_f32_16x16x32_bf16 v[88:91], v[144:147], v[184:187], v[88:91]
	v_mfma_f32_16x16x32_bf16 v[80:83], v[152:155], v[184:187], v[80:83]
	v_mfma_f32_16x16x32_bf16 v[124:127], v[148:151], v[164:167], v[124:127]
	v_mfma_f32_16x16x32_bf16 v[120:123], v[156:159], v[164:167], v[120:123]
	v_mfma_f32_16x16x32_bf16 v[116:119], v[148:151], v[172:175], v[116:119]
	v_mfma_f32_16x16x32_bf16 v[112:115], v[156:159], v[172:175], v[112:115]
	v_mfma_f32_16x16x32_bf16 v[104:107], v[148:151], v[180:183], v[104:107]
	v_mfma_f32_16x16x32_bf16 v[96:99], v[156:159], v[180:183], v[96:99]
	v_mfma_f32_16x16x32_bf16 v[88:91], v[148:151], v[188:191], v[88:91]
	v_mfma_f32_16x16x32_bf16 v[80:83], v[156:159], v[188:191], v[80:83]
	s_barrier
	s_add_i32 s36, s56, s3
	v_lshl_add_u64 v[204:205], s[40:41], 0, v[130:131]
	s_mov_b32 m0, s36
	ds_read_b128 v[192:195], v143
	ds_read_b128 v[196:199], v143 offset:1024
	ds_read_b128 v[200:203], v143 offset:2048
	ds_read_b128 v[208:211], v143 offset:3072
	global_load_lds_dwordx4 v[204:205], off
	v_lshl_add_u64 v[212:213], s[40:41], 0, v[128:129]
	s_add_i32 m0, s36, 0x2000
	s_nop 0
	global_load_lds_dwordx4 v[212:213], off
	s_barrier
	s_waitcnt lgkmcnt(0)
	v_mfma_f32_16x16x32_bf16 v[108:111], v[192:195], v[160:163], v[108:111]
	v_mfma_f32_16x16x32_bf16 v[100:103], v[200:203], v[160:163], v[100:103]
	v_mfma_f32_16x16x32_bf16 v[92:95], v[192:195], v[168:171], v[92:95]
	v_mfma_f32_16x16x32_bf16 v[84:87], v[200:203], v[168:171], v[84:87]
	v_mfma_f32_16x16x32_bf16 v[76:79], v[192:195], v[176:179], v[76:79]
	v_mfma_f32_16x16x32_bf16 v[72:75], v[200:203], v[176:179], v[72:75]
	v_mfma_f32_16x16x32_bf16 v[68:71], v[192:195], v[184:187], v[68:71]
	v_mfma_f32_16x16x32_bf16 v[64:67], v[200:203], v[184:187], v[64:67]
	v_mfma_f32_16x16x32_bf16 v[108:111], v[196:199], v[164:167], v[108:111]
	v_mfma_f32_16x16x32_bf16 v[100:103], v[208:211], v[164:167], v[100:103]
	v_mfma_f32_16x16x32_bf16 v[92:95], v[196:199], v[172:175], v[92:95]
	v_mfma_f32_16x16x32_bf16 v[84:87], v[208:211], v[172:175], v[84:87]
	v_mfma_f32_16x16x32_bf16 v[76:79], v[196:199], v[180:183], v[76:79]
	v_mfma_f32_16x16x32_bf16 v[72:75], v[208:211], v[180:183], v[72:75]
	v_mfma_f32_16x16x32_bf16 v[68:71], v[196:199], v[188:191], v[68:71]
	v_mfma_f32_16x16x32_bf16 v[64:67], v[208:211], v[188:191], v[64:67]
	s_barrier
	s_mov_b32 m0, s20
	v_lshl_add_u64 v[214:215], s[52:53], 0, v[130:131]
	ds_read_b128 v[160:163], v142 offset:16384
	ds_read_b128 v[164:167], v142 offset:17408
	ds_read_b128 v[168:171], v142 offset:18432
	ds_read_b128 v[172:175], v142 offset:19456
	ds_read_b128 v[176:179], v142 offset:20480
	ds_read_b128 v[180:183], v142 offset:21504
	ds_read_b128 v[184:187], v142 offset:22528
	ds_read_b128 v[188:191], v142 offset:23552
	global_load_lds_dwordx4 v[214:215], off
	v_lshl_add_u64 v[216:217], s[52:53], 0, v[128:129]
	s_mov_b32 m0, s21
	s_nop 0
	global_load_lds_dwordx4 v[216:217], off
	s_barrier
	s_waitcnt lgkmcnt(0)
	v_mfma_f32_16x16x32_bf16 v[60:63], v[144:147], v[160:163], v[60:63]
	v_mfma_f32_16x16x32_bf16 v[56:59], v[152:155], v[160:163], v[56:59]
	v_mfma_f32_16x16x32_bf16 v[52:55], v[144:147], v[168:171], v[52:55]
	v_mfma_f32_16x16x32_bf16 v[48:51], v[152:155], v[168:171], v[48:51]
	v_mfma_f32_16x16x32_bf16 v[40:43], v[144:147], v[176:179], v[40:43]
	v_mfma_f32_16x16x32_bf16 v[32:35], v[152:155], v[176:179], v[32:35]
	v_mfma_f32_16x16x32_bf16 v[24:27], v[144:147], v[184:187], v[24:27]
	v_mfma_f32_16x16x32_bf16 v[16:19], v[152:155], v[184:187], v[16:19]
	v_mfma_f32_16x16x32_bf16 v[60:63], v[148:151], v[164:167], v[60:63]
	v_mfma_f32_16x16x32_bf16 v[56:59], v[156:159], v[164:167], v[56:59]
	v_mfma_f32_16x16x32_bf16 v[52:55], v[148:151], v[172:175], v[52:55]
	v_mfma_f32_16x16x32_bf16 v[48:51], v[156:159], v[172:175], v[48:51]
	v_mfma_f32_16x16x32_bf16 v[40:43], v[148:151], v[180:183], v[40:43]
	v_mfma_f32_16x16x32_bf16 v[32:35], v[156:159], v[180:183], v[32:35]
	v_mfma_f32_16x16x32_bf16 v[24:27], v[148:151], v[188:191], v[24:27]
	v_mfma_f32_16x16x32_bf16 v[16:19], v[156:159], v[188:191], v[16:19]
	s_barrier
	s_add_u32 s36, s40, 0x160000
	s_addc_u32 s37, s41, 0
	s_add_i32 s78, s57, s3
	s_mov_b32 m0, s78
	s_nop 0
	global_load_lds_dwordx4 v130, s[36:37]
	s_add_i32 m0, s78, 0x2000
	s_nop 0
	global_load_lds_dwordx4 v128, s[36:37]
	s_waitcnt vmcnt(6)
	s_barrier
; #define WAIT_V(n) asm volatile("s_waitcnt vmcnt(" #n ")" ::: "memory")
; #define WAIT_L(n) asm volatile("s_waitcnt lgkmcnt(" #n ")" ::: "memory")
; #define BAR __builtin_amdgcn_s_barrier()
; #define SCHED __builtin_amdgcn_sched_barrier(0)
; template <class Get, class Epi>
; DI void gemm_stream(LAS unsigned char* lds, const int K, const int ld, Get get, Epi epi) {
;     ...
;             LDB(B0, 0, 0); SCHED; LDA(At, 0, 0); STAGE(SAo(1, 1), a1 + hstep);
;             WAIT_L(8); BAR; WAIT_L(0); MMA(0, 0, At, B0); BAR; SCHED;
;             LDB(B1, 0, 1); STAGE(SBo(0, 0), b2);
;             BAR; WAIT_L(0); MMA(0, 1, At, B1); BAR;
;             LDA(At, 0, 1); STAGE(SAo(0, 0), a2);
;             BAR; WAIT_L(0); MMA(1, 0, At, B0); BAR; SCHED;
;             STAGE(SBo(0, 1), b2 + hstep);
;             WAIT_V(6); BAR; MMA(1, 1, At, B1); BAR;
;             LDB(B0, 1, 0); SCHED; LDA(At, 1, 0); STAGE(SAo(0, 1), a2 + hstep);
;             WAIT_L(8); BAR; WAIT_L(0); MMA(0, 0, At, B0); BAR; SCHED;
;             LDB(B1, 1, 1); STAGE(SBo(1, 0), b3);
;             BAR; WAIT_L(0); MMA(0, 1, At, B1); BAR;
;             LDA(At, 1, 1); STAGE(SAo(1, 0), a3);
;             BAR; WAIT_L(0); MMA(1, 0, At, B0); BAR; SCHED;
;             STAGE(SBo(1, 1), b3 + hstep);
;             WAIT_V(6); BAR; MMA(1, 1, At, B1); BAR;
	v_mfma_f32_16x16x32_bf16 v[44:47], v[192:195], v[160:163], v[44:47]
	v_mfma_f32_16x16x32_bf16 v[36:39], v[200:203], v[160:163], v[36:39]
	v_mfma_f32_16x16x32_bf16 v[28:31], v[192:195], v[168:171], v[28:31]
	v_mfma_f32_16x16x32_bf16 v[20:23], v[200:203], v[168:171], v[20:23]
	v_mfma_f32_16x16x32_bf16 v[12:15], v[192:195], v[176:179], v[12:15]
	v_mfma_f32_16x16x32_bf16 v[8:11], v[200:203], v[176:179], v[8:11]
	v_mfma_f32_16x16x32_bf16 v[4:7], v[192:195], v[184:187], v[4:7]
	v_mfma_f32_16x16x32_bf16 v[0:3], v[200:203], v[184:187], v[0:3]
	v_mfma_f32_16x16x32_bf16 v[44:47], v[196:199], v[164:167], v[44:47]
	v_mfma_f32_16x16x32_bf16 v[36:39], v[208:211], v[164:167], v[36:39]
	v_mfma_f32_16x16x32_bf16 v[28:31], v[196:199], v[172:175], v[28:31]
	v_mfma_f32_16x16x32_bf16 v[20:23], v[208:211], v[172:175], v[20:23]
	v_mfma_f32_16x16x32_bf16 v[12:15], v[196:199], v[180:183], v[12:15]
	v_mfma_f32_16x16x32_bf16 v[8:11], v[208:211], v[180:183], v[8:11]
	v_mfma_f32_16x16x32_bf16 v[4:7], v[196:199], v[188:191], v[4:7]
	v_mfma_f32_16x16x32_bf16 v[0:3], v[208:211], v[188:191], v[0:3]
	s_add_i32 s78, 16, 0x18000
	v_add_u32_e32 v132, s78, v140
	s_barrier
	ds_read_b128 v[144:147], v132
	ds_read_b128 v[148:151], v132 offset:1024
	ds_read_b128 v[152:155], v132 offset:2048
	ds_read_b128 v[156:159], v132 offset:3072
	s_add_u32 s36, s52, 0x160000
	s_addc_u32 s37, s53, 0
	s_mov_b32 m0, s23
	ds_read_b128 v[160:163], v142 offset:32768
	ds_read_b128 v[164:167], v142 offset:33792
	ds_read_b128 v[168:171], v142 offset:34816
	ds_read_b128 v[172:175], v142 offset:35840
	ds_read_b128 v[176:179], v142 offset:36864
	ds_read_b128 v[180:183], v142 offset:37888
	ds_read_b128 v[184:187], v142 offset:38912
	ds_read_b128 v[188:191], v142 offset:39936
	global_load_lds_dwordx4 v130, s[36:37]
	s_mov_b32 m0, s28
	s_nop 0
	global_load_lds_dwordx4 v128, s[36:37]
	s_waitcnt lgkmcnt(8)
	s_barrier
	s_waitcnt lgkmcnt(0)
	v_mfma_f32_16x16x32_bf16 v[124:127], v[144:147], v[160:163], v[124:127]
	v_mfma_f32_16x16x32_bf16 v[120:123], v[152:155], v[160:163], v[120:123]
	v_mfma_f32_16x16x32_bf16 v[116:119], v[144:147], v[168:171], v[116:119]
	v_mfma_f32_16x16x32_bf16 v[112:115], v[152:155], v[168:171], v[112:115]
	v_mfma_f32_16x16x32_bf16 v[104:107], v[144:147], v[176:179], v[104:107]
	v_mfma_f32_16x16x32_bf16 v[96:99], v[152:155], v[176:179], v[96:99]
	v_mfma_f32_16x16x32_bf16 v[88:91], v[144:147], v[184:187], v[88:91]
	v_mfma_f32_16x16x32_bf16 v[80:83], v[152:155], v[184:187], v[80:83]
	v_mfma_f32_16x16x32_bf16 v[124:127], v[148:151], v[164:167], v[124:127]
	v_mfma_f32_16x16x32_bf16 v[120:123], v[156:159], v[164:167], v[120:123]
	v_mfma_f32_16x16x32_bf16 v[116:119], v[148:151], v[172:175], v[116:119]
	v_mfma_f32_16x16x32_bf16 v[112:115], v[156:159], v[172:175], v[112:115]
	v_mfma_f32_16x16x32_bf16 v[104:107], v[148:151], v[180:183], v[104:107]
	v_mfma_f32_16x16x32_bf16 v[96:99], v[156:159], v[180:183], v[96:99]
	v_mfma_f32_16x16x32_bf16 v[88:91], v[148:151], v[188:191], v[88:91]
	v_mfma_f32_16x16x32_bf16 v[80:83], v[156:159], v[188:191], v[80:83]
	s_barrier
	s_add_i32 s52, 16, 0x1c000
	s_add_i32 s36, s78, s3
	v_add_u32_e32 v132, s52, v140
	v_lshl_add_u64 v[204:205], v[204:205], 0, s[8:9]
	s_mov_b32 m0, s36
	ds_read_b128 v[192:195], v132
	ds_read_b128 v[196:199], v132 offset:1024
	ds_read_b128 v[200:203], v132 offset:2048
	ds_read_b128 v[208:211], v132 offset:3072
	global_load_lds_dwordx4 v[204:205], off
	v_lshl_add_u64 v[204:205], v[212:213], 0, s[8:9]
	s_add_i32 m0, s36, 0x2000
	s_nop 0
	global_load_lds_dwordx4 v[204:205], off
	s_barrier
	s_waitcnt lgkmcnt(0)
	v_mfma_f32_16x16x32_bf16 v[108:111], v[192:195], v[160:163], v[108:111]
	v_mfma_f32_16x16x32_bf16 v[100:103], v[200:203], v[160:163], v[100:103]
	v_mfma_f32_16x16x32_bf16 v[92:95], v[192:195], v[168:171], v[92:95]
	v_mfma_f32_16x16x32_bf16 v[84:87], v[200:203], v[168:171], v[84:87]
	v_mfma_f32_16x16x32_bf16 v[76:79], v[192:195], v[176:179], v[76:79]
	v_mfma_f32_16x16x32_bf16 v[72:75], v[200:203], v[176:179], v[72:75]
	v_mfma_f32_16x16x32_bf16 v[68:71], v[192:195], v[184:187], v[68:71]
	v_mfma_f32_16x16x32_bf16 v[64:67], v[200:203], v[184:187], v[64:67]
	v_mfma_f32_16x16x32_bf16 v[108:111], v[196:199], v[164:167], v[108:111]
	v_mfma_f32_16x16x32_bf16 v[100:103], v[208:211], v[164:167], v[100:103]
	v_mfma_f32_16x16x32_bf16 v[92:95], v[196:199], v[172:175], v[92:95]
	v_mfma_f32_16x16x32_bf16 v[84:87], v[208:211], v[172:175], v[84:87]
	v_mfma_f32_16x16x32_bf16 v[76:79], v[196:199], v[180:183], v[76:79]
	v_mfma_f32_16x16x32_bf16 v[72:75], v[208:211], v[180:183], v[72:75]
	v_mfma_f32_16x16x32_bf16 v[68:71], v[196:199], v[188:191], v[68:71]
	v_mfma_f32_16x16x32_bf16 v[64:67], v[208:211], v[188:191], v[64:67]
	s_barrier
	s_mov_b32 m0, s29
	v_lshl_add_u64 v[204:205], v[214:215], 0, s[8:9]
	ds_read_b128 v[160:163], v142 offset:49152
	ds_read_b128 v[164:167], v142 offset:50176
	ds_read_b128 v[168:171], v142 offset:51200
	ds_read_b128 v[172:175], v142 offset:52224
	ds_read_b128 v[176:179], v142 offset:53248
	ds_read_b128 v[180:183], v142 offset:54272
	ds_read_b128 v[184:187], v142 offset:55296
	ds_read_b128 v[188:191], v142 offset:56320
	global_load_lds_dwordx4 v[204:205], off
	v_lshl_add_u64 v[204:205], v[216:217], 0, s[8:9]
	s_mov_b32 m0, s35
	s_nop 0
	global_load_lds_dwordx4 v[204:205], off
	s_barrier
; #define WAIT_V(n) asm volatile("s_waitcnt vmcnt(" #n ")" ::: "memory")
; #define WAIT_L(n) asm volatile("s_waitcnt lgkmcnt(" #n ")" ::: "memory")
; #define BAR __builtin_amdgcn_s_barrier()
; #define SCHED __builtin_amdgcn_sched_barrier(0)
; template <class Get, class Epi>
; DI void gemm_stream(LAS unsigned char* lds, const int K, const int ld, Get get, Epi epi) {
;     ...
;             LDB(B1, 1, 1); STAGE(SBo(1, 0), b3);
;             BAR; WAIT_L(0); MMA(0, 1, At, B1); BAR;
;             LDA(At, 1, 1); STAGE(SAo(1, 0), a3);
;             BAR; WAIT_L(0); MMA(1, 0, At, B0); BAR; SCHED;
;             STAGE(SBo(1, 1), b3 + hstep);
;             WAIT_V(6); BAR; MMA(1, 1, At, B1); BAR;
;         }
;         epi(acc, cur);
; DI void epi_part(const Acc& acc, const P& p, int brow, int bcol, int sl) {
;     EPI_IDX
;     const int b = brow / PB;
;     float* part = (float*)(p.ws + O_PART) + ((size_t)sl * (NBATCH * CTXL) + b * CTXL) * DM;
; #pragma unroll
;     for (int ai = 0; ai < 2; ++ai)
; #pragma unroll
;         for (int m = 0; m < 4; ++m) {
;             float* rp = part + (size_t)(ai * 128 + wr * 64 + m * 16 + fr) * DM + bcol + wc * 32 + fq * 4;
; #pragma unroll
;             for (int bj = 0; bj < 2; ++bj)
; #pragma unroll
;                 for (int n = 0; n < 2; ++n) *(f32x4*)(rp + bj * 128 + n * 16) = acc[ai][bj][m][n];
;         }
	s_waitcnt lgkmcnt(0)
	v_mfma_f32_16x16x32_bf16 v[60:63], v[144:147], v[160:163], v[60:63]
	v_mfma_f32_16x16x32_bf16 v[56:59], v[152:155], v[160:163], v[56:59]
	v_mfma_f32_16x16x32_bf16 v[52:55], v[144:147], v[168:171], v[52:55]
	v_mfma_f32_16x16x32_bf16 v[48:51], v[152:155], v[168:171], v[48:51]
	v_mfma_f32_16x16x32_bf16 v[40:43], v[144:147], v[176:179], v[40:43]
	v_mfma_f32_16x16x32_bf16 v[32:35], v[152:155], v[176:179], v[32:35]
	v_mfma_f32_16x16x32_bf16 v[24:27], v[144:147], v[184:187], v[24:27]
	v_mfma_f32_16x16x32_bf16 v[16:19], v[152:155], v[184:187], v[16:19]
	v_mfma_f32_16x16x32_bf16 v[60:63], v[148:151], v[164:167], v[60:63]
	v_mfma_f32_16x16x32_bf16 v[56:59], v[156:159], v[164:167], v[56:59]
	v_mfma_f32_16x16x32_bf16 v[52:55], v[148:151], v[172:175], v[52:55]
	v_mfma_f32_16x16x32_bf16 v[48:51], v[156:159], v[172:175], v[48:51]
	v_mfma_f32_16x16x32_bf16 v[40:43], v[148:151], v[180:183], v[40:43]
	v_mfma_f32_16x16x32_bf16 v[32:35], v[156:159], v[180:183], v[32:35]
	v_mfma_f32_16x16x32_bf16 v[24:27], v[148:151], v[188:191], v[24:27]
	v_mfma_f32_16x16x32_bf16 v[16:19], v[156:159], v[188:191], v[16:19]
	s_barrier
	s_add_u32 s36, s40, 0x160080
	s_addc_u32 s37, s41, 0
	s_add_i32 s40, s52, s3
	s_mov_b32 m0, s40
	s_nop 0
	global_load_lds_dwordx4 v130, s[36:37]
	s_add_i32 m0, s40, 0x2000
	s_nop 0
	global_load_lds_dwordx4 v128, s[36:37]
	s_add_i32 s77, s77, 2
	s_add_u32 s0, s0, 0x100
	s_addc_u32 s76, s76, 0
	s_cmp_gt_u32 s77, 5
	s_mov_b64 s[36:37], s[38:39]
	s_waitcnt vmcnt(6)
	s_barrier
	v_mfma_f32_16x16x32_bf16 v[44:47], v[192:195], v[160:163], v[44:47]
	v_mfma_f32_16x16x32_bf16 v[36:39], v[200:203], v[160:163], v[36:39]
	v_mfma_f32_16x16x32_bf16 v[28:31], v[192:195], v[168:171], v[28:31]
	v_mfma_f32_16x16x32_bf16 v[20:23], v[200:203], v[168:171], v[20:23]
	v_mfma_f32_16x16x32_bf16 v[12:15], v[192:195], v[176:179], v[12:15]
	v_mfma_f32_16x16x32_bf16 v[8:11], v[200:203], v[176:179], v[8:11]
	v_mfma_f32_16x16x32_bf16 v[4:7], v[192:195], v[184:187], v[4:7]
	v_mfma_f32_16x16x32_bf16 v[0:3], v[200:203], v[184:187], v[0:3]
	v_mfma_f32_16x16x32_bf16 v[44:47], v[196:199], v[164:167], v[44:47]
	v_mfma_f32_16x16x32_bf16 v[36:39], v[208:211], v[164:167], v[36:39]
	v_mfma_f32_16x16x32_bf16 v[28:31], v[196:199], v[172:175], v[28:31]
	v_mfma_f32_16x16x32_bf16 v[20:23], v[208:211], v[172:175], v[20:23]
	v_mfma_f32_16x16x32_bf16 v[12:15], v[196:199], v[180:183], v[12:15]
	v_mfma_f32_16x16x32_bf16 v[8:11], v[208:211], v[180:183], v[8:11]
	v_mfma_f32_16x16x32_bf16 v[4:7], v[196:199], v[188:191], v[4:7]
	v_mfma_f32_16x16x32_bf16 v[0:3], v[208:211], v[188:191], v[0:3]
	s_barrier
	s_cbranch_scc0 .LBB0_1964
	s_mul_hi_i32 s0, s75, 0x78787879
	s_lshr_b32 s37, s0, 31
	s_lshr_b32 s0, s0, 3
	s_ashr_i32 s36, s61, 4
	s_add_i32 s0, s0, s37
	s_ashr_i32 s37, s36, 31
	s_lshl_b32 s38, s0, 8
	s_ashr_i32 s39, s38, 31
	s_lshl_b64 s[36:37], s[36:37], 23
	s_add_u32 s0, s54, s36
	s_addc_u32 s40, s55, s37
	s_lshl_b64 s[36:37], s[38:39], 13
	s_add_u32 s0, s0, s36
	v_mov_b32_e32 v145, v206
	s_addc_u32 s37, s40, s37
	s_lshl_b32 s36, s61, 10
	s_and_b32 s36, s36, 0x3c00
	v_and_b32_e32 v132, 15, v145
	v_ashrrev_i32_e32 v144, 2, v145
	v_and_or_b32 v144, v144, s58, v132
	s_add_u32 s36, s0, s36
	v_lshlrev_b32_e32 v132, 1, v145
	s_addc_u32 s37, s37, 0
	v_and_b32_e32 v132, 0x180, v132
	v_lshl_add_u64 v[146:147], s[36:37], 0, v[132:133]
	v_and_b32_e32 v132, 48, v145
	v_ashrrev_i32_e32 v145, 31, v144
	v_lshl_add_u64 v[146:147], v[146:147], 0, v[132:133]
	v_lshlrev_b64 v[148:149], 13, v[144:145]
	v_lshl_add_u64 v[148:149], v[146:147], 0, v[148:149]
	global_store_dwordx4 v[148:149], v[124:127], off
	global_store_dwordx4 v[148:149], v[120:123], off offset:64
	global_store_dwordx4 v[148:149], v[108:111], off offset:512
	global_store_dwordx4 v[148:149], v[100:103], off offset:576
	s_mov_b32 s61, s74
	s_mov_b32 s75, s63
	v_or_b32_e32 v100, 16, v144
	v_ashrrev_i32_e32 v101, 31, v100
	v_lshlrev_b64 v[100:101], 13, v[100:101]
	v_lshl_add_u64 v[100:101], v[146:147], 0, v[100:101]
	global_store_dwordx4 v[100:101], v[116:119], off
	global_store_dwordx4 v[100:101], v[112:115], off offset:64
	global_store_dwordx4 v[100:101], v[92:95], off offset:512
	global_store_dwordx4 v[100:101], v[84:87], off offset:576
	s_mov_b64 s[38:39], s[18:19]
	s_mov_b64 s[36:37], s[16:17]
	v_or_b32_e32 v84, 32, v144
	v_ashrrev_i32_e32 v85, 31, v84
	v_lshlrev_b64 v[84:85], 13, v[84:85]
	v_lshl_add_u64 v[84:85], v[146:147], 0, v[84:85]
	global_store_dwordx4 v[84:85], v[104:107], off
	global_store_dwordx4 v[84:85], v[96:99], off offset:64
	global_store_dwordx4 v[84:85], v[76:79], off offset:512
	global_store_dwordx4 v[84:85], v[72:75], off offset:576
	s_nop 1
	v_or_b32_e32 v72, 48, v144
	v_ashrrev_i32_e32 v73, 31, v72
	v_lshlrev_b64 v[72:73], 13, v[72:73]
	v_lshl_add_u64 v[72:73], v[146:147], 0, v[72:73]
	global_store_dwordx4 v[72:73], v[88:91], off
	global_store_dwordx4 v[72:73], v[80:83], off offset:64
	global_store_dwordx4 v[72:73], v[68:71], off offset:512
	global_store_dwordx4 v[72:73], v[64:67], off offset:576
	s_nop 1
	v_add_co_u32_e32 v66, vcc, s59, v148
	v_lshl_add_u64 v[64:65], v[148:149], 0, s[10:11]
	s_nop 0
	v_addc_co_u32_e32 v67, vcc, 0, v149, vcc
	global_store_dwordx4 v[66:67], v[60:63], off
	global_store_dwordx4 v[64:65], v[56:59], off offset:64
	global_store_dwordx4 v[64:65], v[44:47], off offset:512
	global_store_dwordx4 v[64:65], v[36:39], off offset:576
	s_nop 1
	v_add_co_u32_e32 v38, vcc, s60, v148
	v_lshl_add_u64 v[36:37], v[148:149], 0, s[12:13]
	s_nop 0
	v_addc_co_u32_e32 v39, vcc, 0, v149, vcc
	global_store_dwordx4 v[38:39], v[52:55], off
	global_store_dwordx4 v[36:37], v[48:51], off offset:64
	global_store_dwordx4 v[36:37], v[28:31], off offset:512
	global_store_dwordx4 v[36:37], v[20:23], off offset:576
	s_nop 1
	v_add_co_u32_e32 v22, vcc, 0x140000, v148
	v_lshl_add_u64 v[20:21], v[148:149], 0, s[14:15]
	s_nop 0
	v_addc_co_u32_e32 v23, vcc, 0, v149, vcc
	global_store_dwordx4 v[22:23], v[40:43], off
	global_store_dwordx4 v[20:21], v[32:35], off offset:64
	global_store_dwordx4 v[20:21], v[12:15], off offset:512
	global_store_dwordx4 v[20:21], v[8:11], off offset:576
	s_nop 1
	v_add_co_u32_e32 v10, vcc, 0x160000, v148
	v_lshl_add_u64 v[8:9], v[148:149], 0, s[6:7]
	s_nop 0
	v_addc_co_u32_e32 v11, vcc, 0, v149, vcc
	s_and_b64 vcc, exec, s[4:5]
	global_store_dwordx4 v[10:11], v[24:27], off
	global_store_dwordx4 v[8:9], v[16:19], off offset:64
	global_store_dwordx4 v[8:9], v[4:7], off offset:512
	global_store_dwordx4 v[8:9], v[0:3], off offset:576
	s_cbranch_vccz .LBB0_1961
	s_waitcnt vmcnt(0)
	s_cmpk_gt_u32 s2, 0xff
	s_cbranch_scc1 .LBB0_1968
	s_barrier

; #define WAIT_V(n) asm volatile("s_waitcnt vmcnt(" #n ")" ::: "memory")
; #define WAIT_L(n) asm volatile("s_waitcnt lgkmcnt(" #n ")" ::: "memory")
; #define BAR __builtin_amdgcn_s_barrier()
; #define SCHED __builtin_amdgcn_sched_barrier(0)
; template <class Get, class Epi>
; DI void gemm_stream(LAS unsigned char* lds, const int K, const int ld, Get get, Epi epi) {
;     ...
;             LDB(B0, 0, 0); SCHED; LDA(At, 0, 0); STAGE(SAo(1, 1), a1 + hstep);
;             WAIT_L(8); BAR; WAIT_L(0); MMA(0, 0, At, B0); BAR; SCHED;
;             LDB(B1, 0, 1); STAGE(SBo(0, 0), b2);
;             BAR; WAIT_L(0); MMA(0, 1, At, B1); BAR;
;             LDA(At, 0, 1); STAGE(SAo(0, 0), a2);
;             BAR; WAIT_L(0); MMA(1, 0, At, B0); BAR; SCHED;
;             STAGE(SBo(0, 1), b2 + hstep);
;             WAIT_V(6); BAR; MMA(1, 1, At, B1); BAR;
;             LDB(B0, 1, 0); SCHED; LDA(At, 1, 0); STAGE(SAo(0, 1), a2 + hstep);
;             WAIT_L(8); BAR; WAIT_L(0); MMA(0, 0, At, B0); BAR; SCHED;
;             LDB(B1, 1, 1); STAGE(SBo(1, 0), b3);
;             BAR; WAIT_L(0); MMA(0, 1, At, B1); BAR;
;             LDA(At, 1, 1); STAGE(SAo(1, 0), a3);
;             BAR; WAIT_L(0); MMA(1, 0, At, B0); BAR; SCHED;
;             STAGE(SBo(1, 1), b3 + hstep);
;             WAIT_V(6); BAR; MMA(1, 1, At, B1); BAR;
.LBB0_2102:
	ds_read_b128 v[128:131], v209
	ds_read_b128 v[132:135], v209 offset:1024
	ds_read_b128 v[136:139], v209 offset:2048
	ds_read_b128 v[156:159], v209 offset:3072
	s_add_u32 s28, s64, 0xfff80080
	s_addc_u32 s29, s65, -1
	s_cmp_eq_u32 s7, 28
	s_cselect_b32 s77, s59, s29
	s_cselect_b32 s76, s58, s28
	s_cselect_b32 s75, s61, s3
	s_cselect_b32 s74, s60, s2
	s_add_i32 m0, s23, 0xc000
	ds_read_b128 v[160:163], v210
	ds_read_b128 v[164:167], v210 offset:1024
	ds_read_b128 v[168:171], v210 offset:2048
	ds_read_b128 v[172:175], v210 offset:3072
	ds_read_b128 v[176:179], v210 offset:4096
	ds_read_b128 v[180:183], v210 offset:5120
	ds_read_b128 v[184:187], v210 offset:6144
	ds_read_b128 v[188:191], v210 offset:7168
	global_load_lds_dwordx4 v148, s[64:65]
	s_add_i32 m0, s23, 0xe000
	s_nop 0
	global_load_lds_dwordx4 v150, s[64:65]
	s_waitcnt lgkmcnt(8)
	s_barrier
	s_waitcnt lgkmcnt(0)
	v_mfma_f32_16x16x32_bf16 v[124:127], v[128:131], v[160:163], v[124:127]
	v_mfma_f32_16x16x32_bf16 v[116:119], v[136:139], v[160:163], v[116:119]
	v_mfma_f32_16x16x32_bf16 v[108:111], v[128:131], v[168:171], v[108:111]
	v_mfma_f32_16x16x32_bf16 v[100:103], v[136:139], v[168:171], v[100:103]
	v_mfma_f32_16x16x32_bf16 v[92:95], v[128:131], v[176:179], v[92:95]
	v_mfma_f32_16x16x32_bf16 v[84:87], v[136:139], v[176:179], v[84:87]
	v_mfma_f32_16x16x32_bf16 v[76:79], v[128:131], v[184:187], v[76:79]
	v_mfma_f32_16x16x32_bf16 v[68:71], v[136:139], v[184:187], v[68:71]
	v_mfma_f32_16x16x32_bf16 v[124:127], v[132:135], v[164:167], v[124:127]
	v_mfma_f32_16x16x32_bf16 v[116:119], v[156:159], v[164:167], v[116:119]
	v_mfma_f32_16x16x32_bf16 v[108:111], v[132:135], v[172:175], v[108:111]
	v_mfma_f32_16x16x32_bf16 v[100:103], v[156:159], v[172:175], v[100:103]
	v_mfma_f32_16x16x32_bf16 v[92:95], v[132:135], v[180:183], v[92:95]
	v_mfma_f32_16x16x32_bf16 v[84:87], v[156:159], v[180:183], v[84:87]
	v_mfma_f32_16x16x32_bf16 v[76:79], v[132:135], v[188:191], v[76:79]
	v_mfma_f32_16x16x32_bf16 v[68:71], v[156:159], v[188:191], v[68:71]
	s_barrier
	s_add_i32 s28, s90, s21
	v_lshl_add_u64 v[140:141], s[74:75], 0, v[142:143]
	s_mov_b32 m0, s28
	ds_read_b128 v[192:195], v211
	ds_read_b128 v[196:199], v211 offset:1024
	ds_read_b128 v[200:203], v211 offset:2048
	ds_read_b128 v[212:215], v211 offset:3072
	global_load_lds_dwordx4 v[140:141], off
	v_lshl_add_u64 v[204:205], s[74:75], 0, v[144:145]
	s_add_i32 m0, s28, 0x2000
	s_nop 0
	global_load_lds_dwordx4 v[204:205], off
	s_barrier
	s_waitcnt lgkmcnt(0)
	v_mfma_f32_16x16x32_bf16 v[120:123], v[192:195], v[160:163], v[120:123]
	v_mfma_f32_16x16x32_bf16 v[112:115], v[200:203], v[160:163], v[112:115]
	v_mfma_f32_16x16x32_bf16 v[104:107], v[192:195], v[168:171], v[104:107]
	v_mfma_f32_16x16x32_bf16 v[96:99], v[200:203], v[168:171], v[96:99]
	v_mfma_f32_16x16x32_bf16 v[88:91], v[192:195], v[176:179], v[88:91]
	v_mfma_f32_16x16x32_bf16 v[80:83], v[200:203], v[176:179], v[80:83]
	v_mfma_f32_16x16x32_bf16 v[72:75], v[192:195], v[184:187], v[72:75]
	v_mfma_f32_16x16x32_bf16 v[64:67], v[200:203], v[184:187], v[64:67]
	v_mfma_f32_16x16x32_bf16 v[120:123], v[196:199], v[164:167], v[120:123]
	v_mfma_f32_16x16x32_bf16 v[112:115], v[212:215], v[164:167], v[112:115]
	v_mfma_f32_16x16x32_bf16 v[104:107], v[196:199], v[172:175], v[104:107]
	v_mfma_f32_16x16x32_bf16 v[96:99], v[212:215], v[172:175], v[96:99]
	v_mfma_f32_16x16x32_bf16 v[88:91], v[196:199], v[180:183], v[88:91]
	v_mfma_f32_16x16x32_bf16 v[80:83], v[212:215], v[180:183], v[80:83]
	v_mfma_f32_16x16x32_bf16 v[72:75], v[196:199], v[188:191], v[72:75]
	v_mfma_f32_16x16x32_bf16 v[64:67], v[212:215], v[188:191], v[64:67]
	s_barrier
	s_mov_b32 m0, s23
	v_lshl_add_u64 v[216:217], s[76:77], 0, v[142:143]
	ds_read_b128 v[160:163], v210 offset:16384
	ds_read_b128 v[164:167], v210 offset:17408
	ds_read_b128 v[168:171], v210 offset:18432
	ds_read_b128 v[172:175], v210 offset:19456
	ds_read_b128 v[176:179], v210 offset:20480
	ds_read_b128 v[180:183], v210 offset:21504
	ds_read_b128 v[184:187], v210 offset:22528
	ds_read_b128 v[188:191], v210 offset:23552
	global_load_lds_dwordx4 v[216:217], off
	v_lshl_add_u64 v[218:219], s[76:77], 0, v[144:145]
	s_mov_b32 m0, s35
	s_nop 0
	global_load_lds_dwordx4 v[218:219], off
	s_barrier
	s_waitcnt lgkmcnt(0)
	v_mfma_f32_16x16x32_bf16 v[60:63], v[128:131], v[160:163], v[60:63]
	v_mfma_f32_16x16x32_bf16 v[52:55], v[136:139], v[160:163], v[52:55]
	v_mfma_f32_16x16x32_bf16 v[44:47], v[128:131], v[168:171], v[44:47]
	v_mfma_f32_16x16x32_bf16 v[36:39], v[136:139], v[168:171], v[36:39]
	v_mfma_f32_16x16x32_bf16 v[28:31], v[128:131], v[176:179], v[28:31]
	v_mfma_f32_16x16x32_bf16 v[20:23], v[136:139], v[176:179], v[20:23]
	v_mfma_f32_16x16x32_bf16 v[12:15], v[128:131], v[184:187], v[12:15]
	v_mfma_f32_16x16x32_bf16 v[4:7], v[136:139], v[184:187], v[4:7]
	v_mfma_f32_16x16x32_bf16 v[60:63], v[132:135], v[164:167], v[60:63]
	v_mfma_f32_16x16x32_bf16 v[52:55], v[156:159], v[164:167], v[52:55]
	v_mfma_f32_16x16x32_bf16 v[44:47], v[132:135], v[172:175], v[44:47]
	v_mfma_f32_16x16x32_bf16 v[36:39], v[156:159], v[172:175], v[36:39]
	v_mfma_f32_16x16x32_bf16 v[28:31], v[132:135], v[180:183], v[28:31]
	v_mfma_f32_16x16x32_bf16 v[20:23], v[156:159], v[180:183], v[20:23]
	v_mfma_f32_16x16x32_bf16 v[12:15], v[132:135], v[188:191], v[12:15]
	v_mfma_f32_16x16x32_bf16 v[4:7], v[156:159], v[188:191], v[4:7]
	s_barrier
	s_add_u32 s28, s74, 0x80000
	s_addc_u32 s29, s75, 0
	s_add_i32 s57, s91, s21
	s_mov_b32 m0, s57
	s_nop 0
	global_load_lds_dwordx4 v142, s[28:29]
	s_add_i32 m0, s57, 0x2000
	s_nop 0
	global_load_lds_dwordx4 v144, s[28:29]
	s_waitcnt vmcnt(6)
	s_barrier
; #define WAIT_V(n) asm volatile("s_waitcnt vmcnt(" #n ")" ::: "memory")
; #define WAIT_L(n) asm volatile("s_waitcnt lgkmcnt(" #n ")" ::: "memory")
; #define BAR __builtin_amdgcn_s_barrier()
; #define SCHED __builtin_amdgcn_sched_barrier(0)
; template <class Get, class Epi>
; DI void gemm_stream(LAS unsigned char* lds, const int K, const int ld, Get get, Epi epi) {
;     ...
;             LDB(B0, 0, 0); SCHED; LDA(At, 0, 0); STAGE(SAo(1, 1), a1 + hstep);
;             WAIT_L(8); BAR; WAIT_L(0); MMA(0, 0, At, B0); BAR; SCHED;
;             LDB(B1, 0, 1); STAGE(SBo(0, 0), b2);
;             BAR; WAIT_L(0); MMA(0, 1, At, B1); BAR;
;             LDA(At, 0, 1); STAGE(SAo(0, 0), a2);
;             BAR; WAIT_L(0); MMA(1, 0, At, B0); BAR; SCHED;
;             STAGE(SBo(0, 1), b2 + hstep);
;             WAIT_V(6); BAR; MMA(1, 1, At, B1); BAR;
;             LDB(B0, 1, 0); SCHED; LDA(At, 1, 0); STAGE(SAo(0, 1), a2 + hstep);
;             WAIT_L(8); BAR; WAIT_L(0); MMA(0, 0, At, B0); BAR; SCHED;
;             LDB(B1, 1, 1); STAGE(SBo(1, 0), b3);
;             BAR; WAIT_L(0); MMA(0, 1, At, B1); BAR;
;             LDA(At, 1, 1); STAGE(SAo(1, 0), a3);
;             BAR; WAIT_L(0); MMA(1, 0, At, B0); BAR; SCHED;
;             STAGE(SBo(1, 1), b3 + hstep);
;             WAIT_V(6); BAR; MMA(1, 1, At, B1); BAR;
	v_mfma_f32_16x16x32_bf16 v[56:59], v[192:195], v[160:163], v[56:59]
	v_mfma_f32_16x16x32_bf16 v[48:51], v[200:203], v[160:163], v[48:51]
	v_mfma_f32_16x16x32_bf16 v[40:43], v[192:195], v[168:171], v[40:43]
	v_mfma_f32_16x16x32_bf16 v[32:35], v[200:203], v[168:171], v[32:35]
	v_mfma_f32_16x16x32_bf16 v[24:27], v[192:195], v[176:179], v[24:27]
	v_mfma_f32_16x16x32_bf16 v[16:19], v[200:203], v[176:179], v[16:19]
	v_mfma_f32_16x16x32_bf16 v[8:11], v[192:195], v[184:187], v[8:11]
	v_mfma_f32_16x16x32_bf16 v[0:3], v[200:203], v[184:187], v[0:3]
	v_mfma_f32_16x16x32_bf16 v[56:59], v[196:199], v[164:167], v[56:59]
	v_mfma_f32_16x16x32_bf16 v[48:51], v[212:215], v[164:167], v[48:51]
	v_mfma_f32_16x16x32_bf16 v[40:43], v[196:199], v[172:175], v[40:43]
	v_mfma_f32_16x16x32_bf16 v[32:35], v[212:215], v[172:175], v[32:35]
	v_mfma_f32_16x16x32_bf16 v[24:27], v[196:199], v[180:183], v[24:27]
	v_mfma_f32_16x16x32_bf16 v[16:19], v[212:215], v[180:183], v[16:19]
	v_mfma_f32_16x16x32_bf16 v[8:11], v[196:199], v[188:191], v[8:11]
	v_mfma_f32_16x16x32_bf16 v[0:3], v[212:215], v[188:191], v[0:3]
	s_add_i32 s57, 16, 0x18000
	v_add_u32_e32 v146, s57, v208
	s_barrier
	ds_read_b128 v[128:131], v146
	ds_read_b128 v[132:135], v146 offset:1024
	ds_read_b128 v[136:139], v146 offset:2048
	ds_read_b128 v[156:159], v146 offset:3072
	s_add_u32 s28, s76, 0x80000
	s_addc_u32 s29, s77, 0
	s_mov_b32 m0, s55
	ds_read_b128 v[160:163], v210 offset:32768
	ds_read_b128 v[164:167], v210 offset:33792
	ds_read_b128 v[168:171], v210 offset:34816
	ds_read_b128 v[172:175], v210 offset:35840
	ds_read_b128 v[176:179], v210 offset:36864
	ds_read_b128 v[180:183], v210 offset:37888
	ds_read_b128 v[184:187], v210 offset:38912
	ds_read_b128 v[188:191], v210 offset:39936
	global_load_lds_dwordx4 v142, s[28:29]
	s_mov_b32 m0, s82
	s_nop 0
	global_load_lds_dwordx4 v144, s[28:29]
	s_waitcnt lgkmcnt(8)
	s_barrier
	s_waitcnt lgkmcnt(0)
	v_mfma_f32_16x16x32_bf16 v[124:127], v[128:131], v[160:163], v[124:127]
	v_mfma_f32_16x16x32_bf16 v[116:119], v[136:139], v[160:163], v[116:119]
	v_mfma_f32_16x16x32_bf16 v[108:111], v[128:131], v[168:171], v[108:111]
	v_mfma_f32_16x16x32_bf16 v[100:103], v[136:139], v[168:171], v[100:103]
	v_mfma_f32_16x16x32_bf16 v[92:95], v[128:131], v[176:179], v[92:95]
	v_mfma_f32_16x16x32_bf16 v[84:87], v[136:139], v[176:179], v[84:87]
	v_mfma_f32_16x16x32_bf16 v[76:79], v[128:131], v[184:187], v[76:79]
	v_mfma_f32_16x16x32_bf16 v[68:71], v[136:139], v[184:187], v[68:71]
	v_mfma_f32_16x16x32_bf16 v[124:127], v[132:135], v[164:167], v[124:127]
	v_mfma_f32_16x16x32_bf16 v[116:119], v[156:159], v[164:167], v[116:119]
	v_mfma_f32_16x16x32_bf16 v[108:111], v[132:135], v[172:175], v[108:111]
	v_mfma_f32_16x16x32_bf16 v[100:103], v[156:159], v[172:175], v[100:103]
	v_mfma_f32_16x16x32_bf16 v[92:95], v[132:135], v[180:183], v[92:95]
	v_mfma_f32_16x16x32_bf16 v[84:87], v[156:159], v[180:183], v[84:87]
	v_mfma_f32_16x16x32_bf16 v[76:79], v[132:135], v[188:191], v[76:79]
	v_mfma_f32_16x16x32_bf16 v[68:71], v[156:159], v[188:191], v[68:71]
	s_barrier
	s_add_i32 s63, 16, 0x1c000
	s_add_i32 s28, s57, s21
	v_add_u32_e32 v146, s63, v208
	v_lshl_add_u64 v[140:141], v[140:141], 0, s[0:1]
	s_mov_b32 m0, s28
	ds_read_b128 v[192:195], v146
	ds_read_b128 v[196:199], v146 offset:1024
	ds_read_b128 v[200:203], v146 offset:2048
	ds_read_b128 v[212:215], v146 offset:3072
	global_load_lds_dwordx4 v[140:141], off
	v_lshl_add_u64 v[140:141], v[204:205], 0, s[0:1]
	s_add_i32 m0, s28, 0x2000
	s_nop 0
	global_load_lds_dwordx4 v[140:141], off
	s_barrier
	s_waitcnt lgkmcnt(0)
	v_mfma_f32_16x16x32_bf16 v[120:123], v[192:195], v[160:163], v[120:123]
	v_mfma_f32_16x16x32_bf16 v[112:115], v[200:203], v[160:163], v[112:115]
	v_mfma_f32_16x16x32_bf16 v[104:107], v[192:195], v[168:171], v[104:107]
	v_mfma_f32_16x16x32_bf16 v[96:99], v[200:203], v[168:171], v[96:99]
	v_mfma_f32_16x16x32_bf16 v[88:91], v[192:195], v[176:179], v[88:91]
	v_mfma_f32_16x16x32_bf16 v[80:83], v[200:203], v[176:179], v[80:83]
	v_mfma_f32_16x16x32_bf16 v[72:75], v[192:195], v[184:187], v[72:75]
	v_mfma_f32_16x16x32_bf16 v[64:67], v[200:203], v[184:187], v[64:67]
	v_mfma_f32_16x16x32_bf16 v[120:123], v[196:199], v[164:167], v[120:123]
	v_mfma_f32_16x16x32_bf16 v[112:115], v[212:215], v[164:167], v[112:115]
	v_mfma_f32_16x16x32_bf16 v[104:107], v[196:199], v[172:175], v[104:107]
	v_mfma_f32_16x16x32_bf16 v[96:99], v[212:215], v[172:175], v[96:99]
	v_mfma_f32_16x16x32_bf16 v[88:91], v[196:199], v[180:183], v[88:91]
	v_mfma_f32_16x16x32_bf16 v[80:83], v[212:215], v[180:183], v[80:83]
	v_mfma_f32_16x16x32_bf16 v[72:75], v[196:199], v[188:191], v[72:75]
	v_mfma_f32_16x16x32_bf16 v[64:67], v[212:215], v[188:191], v[64:67]
	s_barrier
	s_mov_b32 m0, s83
	v_lshl_add_u64 v[140:141], v[216:217], 0, s[0:1]
	ds_read_b128 v[160:163], v210 offset:49152
	ds_read_b128 v[164:167], v210 offset:50176
	ds_read_b128 v[168:171], v210 offset:51200
	ds_read_b128 v[172:175], v210 offset:52224
	ds_read_b128 v[176:179], v210 offset:53248
	ds_read_b128 v[180:183], v210 offset:54272
	ds_read_b128 v[184:187], v210 offset:55296
	ds_read_b128 v[188:191], v210 offset:56320
	global_load_lds_dwordx4 v[140:141], off
	v_lshl_add_u64 v[140:141], v[218:219], 0, s[0:1]
	s_mov_b32 m0, s85
	s_nop 0
	global_load_lds_dwordx4 v[140:141], off
	s_barrier
; #define WAIT_V(n) asm volatile("s_waitcnt vmcnt(" #n ")" ::: "memory")
; #define WAIT_L(n) asm volatile("s_waitcnt lgkmcnt(" #n ")" ::: "memory")
; #define BAR __builtin_amdgcn_s_barrier()
; #define SCHED __builtin_amdgcn_sched_barrier(0)
; template <class Get, class Epi>
; DI void gemm_stream(LAS unsigned char* lds, const int K, const int ld, Get get, Epi epi) {
;     ...
;             LDB(B1, 1, 1); STAGE(SBo(1, 0), b3);
;             BAR; WAIT_L(0); MMA(0, 1, At, B1); BAR;
;             LDA(At, 1, 1); STAGE(SAo(1, 0), a3);
;             BAR; WAIT_L(0); MMA(1, 0, At, B0); BAR; SCHED;
;             STAGE(SBo(1, 1), b3 + hstep);
;             WAIT_V(6); BAR; MMA(1, 1, At, B1); BAR;
;         }
;         epi(acc, cur);
; DI void phase_inproj1(const P& p, char* shm) {
;     ...
;     auto epi = [&](const Acc& acc, const Unit& u) {
;         const int brow = u.pm * 256, pn = u.pn;
;         const int b = u.pm / 17, pt = u.pm % 17;
;         const size_t latrow0 = (size_t)b * SEQ + (pt - 1) * 256;
;         if (pn < 8) epi_rope256(acc, p, brow, (bf16_t*)(p.ws + O_Q1), latrow0, pn * 256, 1.f);
;         else if (pn < 16) epi_rope256(acc, p, brow, (bf16_t*)(p.ws + O_K1), (size_t)brow, (pn - 8) * 256, 0.0625f);
;         else if (pn < 32) epi_T<32>(acc, (pn - 16) * 256, brow, (bf16_t*)(p.ws + O_V1T), 4096, nullptr);
;         else epi_plain(acc, 0, (bf16_t*)(p.ws + O_G1) + latrow0 * 4096, 4096, (pn - 32) * 256, nullptr);
	s_waitcnt lgkmcnt(0)
	v_mfma_f32_16x16x32_bf16 v[60:63], v[128:131], v[160:163], v[60:63]
	v_mfma_f32_16x16x32_bf16 v[52:55], v[136:139], v[160:163], v[52:55]
	v_mfma_f32_16x16x32_bf16 v[44:47], v[128:131], v[168:171], v[44:47]
	v_mfma_f32_16x16x32_bf16 v[36:39], v[136:139], v[168:171], v[36:39]
	v_mfma_f32_16x16x32_bf16 v[28:31], v[128:131], v[176:179], v[28:31]
	v_mfma_f32_16x16x32_bf16 v[20:23], v[136:139], v[176:179], v[20:23]
	v_mfma_f32_16x16x32_bf16 v[12:15], v[128:131], v[184:187], v[12:15]
	v_mfma_f32_16x16x32_bf16 v[4:7], v[136:139], v[184:187], v[4:7]
	v_mfma_f32_16x16x32_bf16 v[60:63], v[132:135], v[164:167], v[60:63]
	v_mfma_f32_16x16x32_bf16 v[52:55], v[156:159], v[164:167], v[52:55]
	v_mfma_f32_16x16x32_bf16 v[44:47], v[132:135], v[172:175], v[44:47]
	v_mfma_f32_16x16x32_bf16 v[36:39], v[156:159], v[172:175], v[36:39]
	v_mfma_f32_16x16x32_bf16 v[28:31], v[132:135], v[180:183], v[28:31]
	v_mfma_f32_16x16x32_bf16 v[20:23], v[156:159], v[180:183], v[20:23]
	v_mfma_f32_16x16x32_bf16 v[12:15], v[132:135], v[188:191], v[12:15]
	v_mfma_f32_16x16x32_bf16 v[4:7], v[156:159], v[188:191], v[4:7]
	s_barrier
	s_add_u32 s28, s74, 0x80080
	s_addc_u32 s29, s75, 0
	s_add_i32 s57, s63, s21
	s_mov_b32 m0, s57
	s_nop 0
	global_load_lds_dwordx4 v142, s[28:29]
	s_add_i32 m0, s57, 0x2000
	s_nop 0
	global_load_lds_dwordx4 v144, s[28:29]
	s_add_i32 s7, s7, 2
	s_add_u32 s64, s64, 0x100
	s_addc_u32 s65, s65, 0
	s_add_u32 s2, s2, 0x100
	s_addc_u32 s3, s3, 0
	s_cmp_gt_u32 s7, 29
	s_waitcnt vmcnt(6)
	s_barrier
	v_mfma_f32_16x16x32_bf16 v[56:59], v[192:195], v[160:163], v[56:59]
	v_mfma_f32_16x16x32_bf16 v[48:51], v[200:203], v[160:163], v[48:51]
	v_mfma_f32_16x16x32_bf16 v[40:43], v[192:195], v[168:171], v[40:43]
	v_mfma_f32_16x16x32_bf16 v[32:35], v[200:203], v[168:171], v[32:35]
	v_mfma_f32_16x16x32_bf16 v[24:27], v[192:195], v[176:179], v[24:27]
	v_mfma_f32_16x16x32_bf16 v[16:19], v[200:203], v[176:179], v[16:19]
	v_mfma_f32_16x16x32_bf16 v[8:11], v[192:195], v[184:187], v[8:11]
	v_mfma_f32_16x16x32_bf16 v[0:3], v[200:203], v[184:187], v[0:3]
	v_mfma_f32_16x16x32_bf16 v[56:59], v[196:199], v[164:167], v[56:59]
	v_mfma_f32_16x16x32_bf16 v[48:51], v[212:215], v[164:167], v[48:51]
	v_mfma_f32_16x16x32_bf16 v[40:43], v[196:199], v[172:175], v[40:43]
	v_mfma_f32_16x16x32_bf16 v[32:35], v[212:215], v[172:175], v[32:35]
	v_mfma_f32_16x16x32_bf16 v[24:27], v[196:199], v[180:183], v[24:27]
	v_mfma_f32_16x16x32_bf16 v[16:19], v[212:215], v[180:183], v[16:19]
	v_mfma_f32_16x16x32_bf16 v[8:11], v[196:199], v[188:191], v[8:11]
	v_mfma_f32_16x16x32_bf16 v[0:3], v[212:215], v[188:191], v[0:3]
	s_barrier
	s_cbranch_scc0 .LBB0_2102
	s_mul_hi_i32 s2, s6, 0x78787879
	s_lshr_b32 s3, s2, 31
	s_ashr_i32 s2, s2, 3
	s_add_i32 s76, s2, s3
	s_mul_i32 s2, s76, 17
	s_lshl_b32 s74, s6, 8
	s_sub_i32 s6, s6, s2
	s_lshl_b32 s6, s6, 8
	s_ashr_i32 s77, s76, 31
	s_addk_i32 s6, 0xff00
	s_lshl_b64 s[2:3], s[76:77], 12
	s_ashr_i32 s7, s6, 31
	s_add_u32 s64, s2, s6
	s_addc_u32 s65, s3, s7
	s_cmp_gt_i32 s62, 7
	s_mov_b64 s[6:7], -1
	s_cbranch_scc0 .LBB0_2145
	s_cmp_gt_u32 s62, 15
	s_cbranch_scc0 .LBB0_2110
	s_cmp_gt_u32 s62, 31
	v_cvt_pk_bf16_f32 v204, v124, v125
	v_cvt_pk_bf16_f32 v205, v126, v127
	v_cvt_pk_bf16_f32 v202, v116, v117
	v_cvt_pk_bf16_f32 v203, v118, v119
	v_cvt_pk_bf16_f32 v200, v120, v121
	v_cvt_pk_bf16_f32 v201, v122, v123
	v_cvt_pk_bf16_f32 v198, v112, v113
	v_cvt_pk_bf16_f32 v199, v114, v115
	v_cvt_pk_bf16_f32 v196, v108, v109
	v_cvt_pk_bf16_f32 v197, v110, v111
	v_cvt_pk_bf16_f32 v194, v100, v101
	v_cvt_pk_bf16_f32 v195, v102, v103
	v_cvt_pk_bf16_f32 v192, v104, v105
	v_cvt_pk_bf16_f32 v193, v106, v107
	v_cvt_pk_bf16_f32 v190, v96, v97
	v_cvt_pk_bf16_f32 v191, v98, v99
	v_cvt_pk_bf16_f32 v188, v92, v93
	v_cvt_pk_bf16_f32 v189, v94, v95
	v_cvt_pk_bf16_f32 v186, v84, v85
	v_cvt_pk_bf16_f32 v187, v86, v87
	v_cvt_pk_bf16_f32 v184, v88, v89
	v_cvt_pk_bf16_f32 v185, v90, v91
	v_cvt_pk_bf16_f32 v182, v80, v81
	v_cvt_pk_bf16_f32 v183, v82, v83
	v_cvt_pk_bf16_f32 v180, v76, v77
	v_cvt_pk_bf16_f32 v181, v78, v79
	v_cvt_pk_bf16_f32 v178, v68, v69
	v_cvt_pk_bf16_f32 v179, v70, v71
	v_cvt_pk_bf16_f32 v176, v72, v73
	v_cvt_pk_bf16_f32 v177, v74, v75
	v_cvt_pk_bf16_f32 v174, v64, v65
	v_cvt_pk_bf16_f32 v175, v66, v67
	v_cvt_pk_bf16_f32 v172, v60, v61
	v_cvt_pk_bf16_f32 v173, v62, v63
	v_cvt_pk_bf16_f32 v170, v52, v53
	v_cvt_pk_bf16_f32 v171, v54, v55
	v_cvt_pk_bf16_f32 v168, v56, v57
	v_cvt_pk_bf16_f32 v169, v58, v59
	v_cvt_pk_bf16_f32 v166, v48, v49
	v_cvt_pk_bf16_f32 v167, v50, v51
	v_cvt_pk_bf16_f32 v164, v44, v45
	v_cvt_pk_bf16_f32 v165, v46, v47
	v_cvt_pk_bf16_f32 v162, v36, v37
	v_cvt_pk_bf16_f32 v163, v38, v39
	v_cvt_pk_bf16_f32 v160, v40, v41
	v_cvt_pk_bf16_f32 v161, v42, v43
	v_cvt_pk_bf16_f32 v158, v32, v33
	v_cvt_pk_bf16_f32 v159, v34, v35
	v_cvt_pk_bf16_f32 v156, v28, v29
	v_cvt_pk_bf16_f32 v157, v30, v31
	v_cvt_pk_bf16_f32 v140, v20, v21
	v_cvt_pk_bf16_f32 v141, v22, v23
	v_cvt_pk_bf16_f32 v138, v24, v25
	v_cvt_pk_bf16_f32 v139, v26, v27
	v_cvt_pk_bf16_f32 v136, v16, v17
	v_cvt_pk_bf16_f32 v137, v18, v19
	v_cvt_pk_bf16_f32 v134, v12, v13
	v_cvt_pk_bf16_f32 v135, v14, v15
	v_cvt_pk_bf16_f32 v132, v4, v5
	v_cvt_pk_bf16_f32 v133, v6, v7
	v_cvt_pk_bf16_f32 v130, v8, v9
	v_cvt_pk_bf16_f32 v131, v10, v11
	v_cvt_pk_bf16_f32 v128, v0, v1
	v_cvt_pk_bf16_f32 v129, v2, v3
	s_cbranch_scc0 .LBB0_2107
; DI void epi_plain(const Acc& acc, int brow, bf16_t* dst, int ld, int coff, const float* rs) {
;     EPI_IDX
; #pragma unroll
;     for (int ai = 0; ai < 2; ++ai)
; #pragma unroll
;         for (int m = 0; m < 4; ++m) {
;             const int lr = ai * 128 + wr * 64 + m * 16 + fr;
;             const float s = rs ? rs[lr] : 1.f;
;             bf16_t* rp = dst + (size_t)(brow + lr) * ld + coff + wc * 32 + fq * 4;
; #pragma unroll
;             for (int bj = 0; bj < 2; ++bj)
; #pragma unroll
;                 for (int n = 0; n < 2; ++n) { const f32x4 v = acc[ai][bj][m][n]; st4(rp + bj * 128 + n * 16, v[0] * s, v[1] * s, v[2] * s, v[3] * s); }
;         }
	s_lshl_b64 s[2:3], s[64:65], 13
	s_add_u32 s2, s26, s2
	s_addc_u32 s3, s27, s3
	v_mov_b32_e32 v146, v206
	s_lshl_b32 s6, s62, 9
	s_add_u32 s2, s2, s6
	v_and_b32_e32 v212, 15, v146
	v_ashrrev_i32_e32 v213, 2, v146
	v_and_or_b32 v212, v213, s92, v212
	s_addc_u32 s3, s3, 0
	v_lshrrev_b32_e32 v213, 1, v146
	v_and_b32_e32 v146, 0xc0, v146
	v_lshl_add_u64 v[214:215], s[2:3], 0, v[146:147]
	v_and_b32_e32 v146, 24, v213
	v_or_b32_e32 v218, 16, v212
	v_lshl_add_u64 v[214:215], v[214:215], 0, v[146:147]
	s_mov_b64 s[2:3], 0x1a3fc000
	v_ashrrev_i32_e32 v213, 31, v212
	v_ashrrev_i32_e32 v219, 31, v218
	v_lshl_add_u64 v[214:215], v[214:215], 0, s[2:3]
	v_lshlrev_b64 v[216:217], 13, v[212:213]
	v_lshlrev_b64 v[218:219], 13, v[218:219]
	v_lshl_add_u64 v[216:217], v[214:215], 0, v[216:217]
	v_lshl_add_u64 v[218:219], v[214:215], 0, v[218:219]
	global_store_dwordx2 v[216:217], v[204:205], off
	global_store_dwordx2 v[216:217], v[202:203], off offset:32
	global_store_dwordx2 v[216:217], v[200:201], off offset:256
	global_store_dwordx2 v[216:217], v[198:199], off offset:288
	global_store_dwordx2 v[218:219], v[196:197], off
	global_store_dwordx2 v[218:219], v[194:195], off offset:32
	global_store_dwordx2 v[218:219], v[192:193], off offset:256
	global_store_dwordx2 v[218:219], v[190:191], off offset:288
	v_or_b32_e32 v218, 32, v212
	v_or_b32_e32 v212, 48, v212
	v_ashrrev_i32_e32 v219, 31, v218
	v_ashrrev_i32_e32 v213, 31, v212
	v_lshlrev_b64 v[218:219], 13, v[218:219]
	v_lshlrev_b64 v[212:213], 13, v[212:213]
	v_lshl_add_u64 v[218:219], v[214:215], 0, v[218:219]
	v_lshl_add_u64 v[212:213], v[214:215], 0, v[212:213]
	s_mov_b64 s[2:3], 0x100000
	global_store_dwordx2 v[218:219], v[188:189], off
	global_store_dwordx2 v[218:219], v[186:187], off offset:32
	global_store_dwordx2 v[218:219], v[184:185], off offset:256
	global_store_dwordx2 v[218:219], v[182:183], off offset:288
	global_store_dwordx2 v[212:213], v[180:181], off
	global_store_dwordx2 v[212:213], v[178:179], off offset:32
	global_store_dwordx2 v[212:213], v[176:177], off offset:256
	global_store_dwordx2 v[212:213], v[174:175], off offset:288
	v_lshl_add_u64 v[212:213], v[216:217], 0, s[2:3]
	s_mov_b32 s2, 0x100000
	v_add_co_u32_e32 v214, vcc, s2, v216
	s_mov_b64 s[2:3], 0x120000
	s_nop 0
	v_addc_co_u32_e32 v215, vcc, 0, v217, vcc
	global_store_dwordx2 v[214:215], v[172:173], off
	global_store_dwordx2 v[212:213], v[170:171], off offset:32
	global_store_dwordx2 v[212:213], v[168:169], off offset:256
	global_store_dwordx2 v[212:213], v[166:167], off offset:288
	v_add_co_u32_e32 v214, vcc, s93, v216
	v_lshl_add_u64 v[212:213], v[216:217], 0, s[2:3]
	s_nop 0
	v_addc_co_u32_e32 v215, vcc, 0, v217, vcc
	global_store_dwordx2 v[214:215], v[164:165], off
	global_store_dwordx2 v[212:213], v[162:163], off offset:32
	global_store_dwordx2 v[212:213], v[160:161], off offset:256
	global_store_dwordx2 v[212:213], v[158:159], off offset:288
	v_add_co_u32_e32 v214, vcc, s94, v216
	v_lshl_add_u64 v[212:213], v[216:217], 0, s[16:17]
	s_nop 0
	v_addc_co_u32_e32 v215, vcc, 0, v217, vcc
	global_store_dwordx2 v[214:215], v[156:157], off
	global_store_dwordx2 v[212:213], v[140:141], off offset:32
	global_store_dwordx2 v[212:213], v[138:139], off offset:256
	global_store_dwordx2 v[212:213], v[136:137], off offset:288
	v_add_co_u32_e32 v214, vcc, s95, v216
	v_lshl_add_u64 v[212:213], v[216:217], 0, s[18:19]
	s_nop 0
	v_addc_co_u32_e32 v215, vcc, 0, v217, vcc
	global_store_dwordx2 v[214:215], v[134:135], off
	global_store_dwordx2 v[212:213], v[132:133], off offset:32
	global_store_dwordx2 v[212:213], v[130:131], off offset:256
	global_store_dwordx2 v[212:213], v[128:129], off offset:288
	s_mov_b64 s[6:7], 0

; #define WAIT_V(n) asm volatile("s_waitcnt vmcnt(" #n ")" ::: "memory")
; #define WAIT_L(n) asm volatile("s_waitcnt lgkmcnt(" #n ")" ::: "memory")
; #define BAR __builtin_amdgcn_s_barrier()
; #define SCHED __builtin_amdgcn_sched_barrier(0)
; template <class Get, class Epi>
; DI void gemm_stream(LAS unsigned char* lds, const int K, const int ld, Get get, Epi epi) {
;     ...
;             LDB(B0, 0, 0); SCHED; LDA(At, 0, 0); STAGE(SAo(1, 1), a1 + hstep);
;             WAIT_L(8); BAR; WAIT_L(0); MMA(0, 0, At, B0); BAR; SCHED;
;             LDB(B1, 0, 1); STAGE(SBo(0, 0), b2);
;             BAR; WAIT_L(0); MMA(0, 1, At, B1); BAR;
;             LDA(At, 0, 1); STAGE(SAo(0, 0), a2);
;             BAR; WAIT_L(0); MMA(1, 0, At, B0); BAR; SCHED;
;             STAGE(SBo(0, 1), b2 + hstep);
;             WAIT_V(6); BAR; MMA(1, 1, At, B1); BAR;
;             LDB(B0, 1, 0); SCHED; LDA(At, 1, 0); STAGE(SAo(0, 1), a2 + hstep);
;             WAIT_L(8); BAR; WAIT_L(0); MMA(0, 0, At, B0); BAR; SCHED;
;             LDB(B1, 1, 1); STAGE(SBo(1, 0), b3);
;             BAR; WAIT_L(0); MMA(0, 1, At, B1); BAR;
;             LDA(At, 1, 1); STAGE(SAo(1, 0), a3);
;             BAR; WAIT_L(0); MMA(1, 0, At, B0); BAR; SCHED;
;             STAGE(SBo(1, 1), b3 + hstep);
;             WAIT_V(6); BAR; MMA(1, 1, At, B1); BAR;
.LBB0_2670:
	ds_read_b128 v[128:131], v198
	ds_read_b128 v[132:135], v198 offset:1024
	ds_read_b128 v[136:139], v198 offset:2048
	ds_read_b128 v[140:143], v198 offset:3072
	s_add_u32 s8, s6, 0x100
	s_addc_u32 s9, s7, 0
	s_cmp_eq_u32 s16, 60
	s_cselect_b32 s13, s39, s9
	s_cselect_b32 s12, s38, s8
	s_cselect_b32 s11, s41, s15
	s_cselect_b32 s10, s40, s14
	s_mov_b32 m0, s52
	ds_read_b128 v[144:147], v199
	ds_read_b128 v[148:151], v199 offset:1024
	ds_read_b128 v[152:155], v199 offset:2048
	ds_read_b128 v[156:159], v199 offset:3072
	ds_read_b128 v[160:163], v199 offset:4096
	ds_read_b128 v[174:177], v199 offset:5120
	ds_read_b128 v[178:181], v199 offset:6144
	ds_read_b128 v[182:185], v199 offset:7168
	global_load_lds_dwordx4 v168, s[6:7]
	s_mov_b32 m0, s53
	s_nop 0
	global_load_lds_dwordx4 v170, s[6:7]
	s_waitcnt lgkmcnt(8)
	s_barrier
	s_waitcnt lgkmcnt(0)
	v_mfma_f32_16x16x32_bf16 v[124:127], v[128:131], v[144:147], v[124:127]
	v_mfma_f32_16x16x32_bf16 v[92:95], v[136:139], v[144:147], v[92:95]
	v_mfma_f32_16x16x32_bf16 v[120:123], v[128:131], v[152:155], v[120:123]
	v_mfma_f32_16x16x32_bf16 v[88:91], v[136:139], v[152:155], v[88:91]
	v_mfma_f32_16x16x32_bf16 v[116:119], v[128:131], v[160:163], v[116:119]
	v_mfma_f32_16x16x32_bf16 v[84:87], v[136:139], v[160:163], v[84:87]
	v_mfma_f32_16x16x32_bf16 v[112:115], v[128:131], v[178:181], v[112:115]
	v_mfma_f32_16x16x32_bf16 v[80:83], v[136:139], v[178:181], v[80:83]
	v_mfma_f32_16x16x32_bf16 v[124:127], v[132:135], v[148:151], v[124:127]
	v_mfma_f32_16x16x32_bf16 v[92:95], v[140:143], v[148:151], v[92:95]
	v_mfma_f32_16x16x32_bf16 v[120:123], v[132:135], v[156:159], v[120:123]
	v_mfma_f32_16x16x32_bf16 v[88:91], v[140:143], v[156:159], v[88:91]
	v_mfma_f32_16x16x32_bf16 v[116:119], v[132:135], v[174:177], v[116:119]
	v_mfma_f32_16x16x32_bf16 v[84:87], v[140:143], v[174:177], v[84:87]
	v_mfma_f32_16x16x32_bf16 v[112:115], v[132:135], v[182:185], v[112:115]
	v_mfma_f32_16x16x32_bf16 v[80:83], v[140:143], v[182:185], v[80:83]
	s_barrier
	s_mov_b32 m0, s58
	v_lshl_add_u64 v[204:205], s[10:11], 0, v[164:165]
	ds_read_b128 v[186:189], v200
	ds_read_b128 v[190:193], v200 offset:1024
	ds_read_b128 v[194:197], v200 offset:2048
	ds_read_b128 v[208:211], v200 offset:3072
	global_load_lds_dwordx4 v[204:205], off
	v_lshl_add_u64 v[212:213], s[10:11], 0, v[166:167]
	s_mov_b32 m0, s59
	s_nop 0
	global_load_lds_dwordx4 v[212:213], off
	s_barrier
	s_waitcnt lgkmcnt(0)
	v_mfma_f32_16x16x32_bf16 v[60:63], v[186:189], v[144:147], v[60:63]
	v_mfma_f32_16x16x32_bf16 v[28:31], v[194:197], v[144:147], v[28:31]
	v_mfma_f32_16x16x32_bf16 v[56:59], v[186:189], v[152:155], v[56:59]
	v_mfma_f32_16x16x32_bf16 v[24:27], v[194:197], v[152:155], v[24:27]
	v_mfma_f32_16x16x32_bf16 v[52:55], v[186:189], v[160:163], v[52:55]
	v_mfma_f32_16x16x32_bf16 v[20:23], v[194:197], v[160:163], v[20:23]
	v_mfma_f32_16x16x32_bf16 v[48:51], v[186:189], v[178:181], v[48:51]
	v_mfma_f32_16x16x32_bf16 v[16:19], v[194:197], v[178:181], v[16:19]
	v_mfma_f32_16x16x32_bf16 v[60:63], v[190:193], v[148:151], v[60:63]
	v_mfma_f32_16x16x32_bf16 v[28:31], v[208:211], v[148:151], v[28:31]
	v_mfma_f32_16x16x32_bf16 v[56:59], v[190:193], v[156:159], v[56:59]
	v_mfma_f32_16x16x32_bf16 v[24:27], v[208:211], v[156:159], v[24:27]
	v_mfma_f32_16x16x32_bf16 v[52:55], v[190:193], v[174:177], v[52:55]
	v_mfma_f32_16x16x32_bf16 v[20:23], v[208:211], v[174:177], v[20:23]
	v_mfma_f32_16x16x32_bf16 v[48:51], v[190:193], v[182:185], v[48:51]
	v_mfma_f32_16x16x32_bf16 v[16:19], v[208:211], v[182:185], v[16:19]
	s_barrier
	s_mov_b32 m0, s35
	v_lshl_add_u64 v[214:215], s[12:13], 0, v[164:165]
	ds_read_b128 v[144:147], v199 offset:16384
	ds_read_b128 v[148:151], v199 offset:17408
	ds_read_b128 v[152:155], v199 offset:18432
	ds_read_b128 v[156:159], v199 offset:19456
	ds_read_b128 v[160:163], v199 offset:20480
	ds_read_b128 v[174:177], v199 offset:21504
	ds_read_b128 v[178:181], v199 offset:22528
	ds_read_b128 v[182:185], v199 offset:23552
	global_load_lds_dwordx4 v[214:215], off
	v_lshl_add_u64 v[216:217], s[12:13], 0, v[166:167]
	s_mov_b32 m0, s44
	s_nop 0
	global_load_lds_dwordx4 v[216:217], off
	s_barrier
	s_waitcnt lgkmcnt(0)
	v_mfma_f32_16x16x32_bf16 v[108:111], v[128:131], v[144:147], v[108:111]
	v_mfma_f32_16x16x32_bf16 v[76:79], v[136:139], v[144:147], v[76:79]
	v_mfma_f32_16x16x32_bf16 v[104:107], v[128:131], v[152:155], v[104:107]
	v_mfma_f32_16x16x32_bf16 v[72:75], v[136:139], v[152:155], v[72:75]
	v_mfma_f32_16x16x32_bf16 v[100:103], v[128:131], v[160:163], v[100:103]
	v_mfma_f32_16x16x32_bf16 v[68:71], v[136:139], v[160:163], v[68:71]
	v_mfma_f32_16x16x32_bf16 v[96:99], v[128:131], v[178:181], v[96:99]
	v_mfma_f32_16x16x32_bf16 v[64:67], v[136:139], v[178:181], v[64:67]
	v_mfma_f32_16x16x32_bf16 v[108:111], v[132:135], v[148:151], v[108:111]
	v_mfma_f32_16x16x32_bf16 v[76:79], v[140:143], v[148:151], v[76:79]
	v_mfma_f32_16x16x32_bf16 v[104:107], v[132:135], v[156:159], v[104:107]
	v_mfma_f32_16x16x32_bf16 v[72:75], v[140:143], v[156:159], v[72:75]
	v_mfma_f32_16x16x32_bf16 v[100:103], v[132:135], v[174:177], v[100:103]
	v_mfma_f32_16x16x32_bf16 v[68:71], v[140:143], v[174:177], v[68:71]
	v_mfma_f32_16x16x32_bf16 v[96:99], v[132:135], v[182:185], v[96:99]
	v_mfma_f32_16x16x32_bf16 v[64:67], v[140:143], v[182:185], v[64:67]
	s_barrier
	s_add_u32 s6, s10, 0x100000
	s_addc_u32 s7, s11, 0
	s_mov_b32 m0, s60
	v_lshl_add_u64 v[128:129], s[6:7], 0, v[164:165]
	global_load_lds_dwordx4 v[128:129], off
	s_mov_b32 m0, s61
	s_nop 0
	global_load_lds_dwordx4 v166, s[6:7]
	s_waitcnt vmcnt(6)
	s_barrier
; #define WAIT_V(n) asm volatile("s_waitcnt vmcnt(" #n ")" ::: "memory")
; #define WAIT_L(n) asm volatile("s_waitcnt lgkmcnt(" #n ")" ::: "memory")
; #define BAR __builtin_amdgcn_s_barrier()
; #define SCHED __builtin_amdgcn_sched_barrier(0)
; template <class Get, class Epi>
; DI void gemm_stream(LAS unsigned char* lds, const int K, const int ld, Get get, Epi epi) {
;     ...
;             LDB(B0, 0, 0); SCHED; LDA(At, 0, 0); STAGE(SAo(1, 1), a1 + hstep);
;             WAIT_L(8); BAR; WAIT_L(0); MMA(0, 0, At, B0); BAR; SCHED;
;             LDB(B1, 0, 1); STAGE(SBo(0, 0), b2);
;             BAR; WAIT_L(0); MMA(0, 1, At, B1); BAR;
;             LDA(At, 0, 1); STAGE(SAo(0, 0), a2);
;             BAR; WAIT_L(0); MMA(1, 0, At, B0); BAR; SCHED;
;             STAGE(SBo(0, 1), b2 + hstep);
;             WAIT_V(6); BAR; MMA(1, 1, At, B1); BAR;
;             LDB(B0, 1, 0); SCHED; LDA(At, 1, 0); STAGE(SAo(0, 1), a2 + hstep);
;             WAIT_L(8); BAR; WAIT_L(0); MMA(0, 0, At, B0); BAR; SCHED;
;             LDB(B1, 1, 1); STAGE(SBo(1, 0), b3);
;             BAR; WAIT_L(0); MMA(0, 1, At, B1); BAR;
;             LDA(At, 1, 1); STAGE(SAo(1, 0), a3);
;             BAR; WAIT_L(0); MMA(1, 0, At, B0); BAR; SCHED;
;             STAGE(SBo(1, 1), b3 + hstep);
;             WAIT_V(6); BAR; MMA(1, 1, At, B1); BAR;
	v_mfma_f32_16x16x32_bf16 v[44:47], v[186:189], v[144:147], v[44:47]
	v_mfma_f32_16x16x32_bf16 v[12:15], v[194:197], v[144:147], v[12:15]
	v_mfma_f32_16x16x32_bf16 v[40:43], v[186:189], v[152:155], v[40:43]
	v_mfma_f32_16x16x32_bf16 v[8:11], v[194:197], v[152:155], v[8:11]
	v_mfma_f32_16x16x32_bf16 v[36:39], v[186:189], v[160:163], v[36:39]
	v_mfma_f32_16x16x32_bf16 v[4:7], v[194:197], v[160:163], v[4:7]
	v_mfma_f32_16x16x32_bf16 v[32:35], v[186:189], v[178:181], v[32:35]
	v_mfma_f32_16x16x32_bf16 v[0:3], v[194:197], v[178:181], v[0:3]
	v_mfma_f32_16x16x32_bf16 v[44:47], v[190:193], v[148:151], v[44:47]
	v_mfma_f32_16x16x32_bf16 v[12:15], v[208:211], v[148:151], v[12:15]
	v_mfma_f32_16x16x32_bf16 v[40:43], v[190:193], v[156:159], v[40:43]
	v_mfma_f32_16x16x32_bf16 v[8:11], v[208:211], v[156:159], v[8:11]
	v_mfma_f32_16x16x32_bf16 v[36:39], v[190:193], v[174:177], v[36:39]
	v_mfma_f32_16x16x32_bf16 v[4:7], v[208:211], v[174:177], v[4:7]
	v_mfma_f32_16x16x32_bf16 v[32:35], v[190:193], v[182:185], v[32:35]
	v_mfma_f32_16x16x32_bf16 v[0:3], v[208:211], v[182:185], v[0:3]
	s_barrier
	ds_read_b128 v[128:131], v201
	ds_read_b128 v[132:135], v201 offset:1024
	ds_read_b128 v[136:139], v201 offset:2048
	ds_read_b128 v[140:143], v201 offset:3072
	s_add_u32 s6, s12, 0x100000
	s_addc_u32 s7, s13, 0
	s_mov_b32 m0, s45
	ds_read_b128 v[144:147], v199 offset:32768
	ds_read_b128 v[148:151], v199 offset:33792
	ds_read_b128 v[152:155], v199 offset:34816
	ds_read_b128 v[156:159], v199 offset:35840
	ds_read_b128 v[160:163], v199 offset:36864
	ds_read_b128 v[174:177], v199 offset:37888
	ds_read_b128 v[178:181], v199 offset:38912
	ds_read_b128 v[182:185], v199 offset:39936
	global_load_lds_dwordx4 v164, s[6:7]
	s_mov_b32 m0, s46
	s_nop 0
	global_load_lds_dwordx4 v166, s[6:7]
	s_waitcnt lgkmcnt(8)
	s_barrier
	s_waitcnt lgkmcnt(0)
	v_mfma_f32_16x16x32_bf16 v[124:127], v[128:131], v[144:147], v[124:127]
	v_mfma_f32_16x16x32_bf16 v[92:95], v[136:139], v[144:147], v[92:95]
	v_mfma_f32_16x16x32_bf16 v[120:123], v[128:131], v[152:155], v[120:123]
	v_mfma_f32_16x16x32_bf16 v[88:91], v[136:139], v[152:155], v[88:91]
	v_mfma_f32_16x16x32_bf16 v[116:119], v[128:131], v[160:163], v[116:119]
	v_mfma_f32_16x16x32_bf16 v[84:87], v[136:139], v[160:163], v[84:87]
	v_mfma_f32_16x16x32_bf16 v[112:115], v[128:131], v[178:181], v[112:115]
	v_mfma_f32_16x16x32_bf16 v[80:83], v[136:139], v[178:181], v[80:83]
	v_mfma_f32_16x16x32_bf16 v[124:127], v[132:135], v[148:151], v[124:127]
	v_mfma_f32_16x16x32_bf16 v[92:95], v[140:143], v[148:151], v[92:95]
	v_mfma_f32_16x16x32_bf16 v[120:123], v[132:135], v[156:159], v[120:123]
	v_mfma_f32_16x16x32_bf16 v[88:91], v[140:143], v[156:159], v[88:91]
	v_mfma_f32_16x16x32_bf16 v[116:119], v[132:135], v[174:177], v[116:119]
	v_mfma_f32_16x16x32_bf16 v[84:87], v[140:143], v[174:177], v[84:87]
	v_mfma_f32_16x16x32_bf16 v[112:115], v[132:135], v[182:185], v[112:115]
	v_mfma_f32_16x16x32_bf16 v[80:83], v[140:143], v[182:185], v[80:83]
	s_barrier
	s_mov_b32 m0, s64
	v_lshl_add_u64 v[204:205], v[204:205], 0, s[0:1]
	ds_read_b128 v[186:189], v202
	ds_read_b128 v[190:193], v202 offset:1024
	ds_read_b128 v[194:197], v202 offset:2048
	ds_read_b128 v[208:211], v202 offset:3072
	global_load_lds_dwordx4 v[204:205], off
	v_lshl_add_u64 v[204:205], v[212:213], 0, s[0:1]
	s_mov_b32 m0, s65
	s_nop 0
	global_load_lds_dwordx4 v[204:205], off
	s_barrier
	s_waitcnt lgkmcnt(0)
	v_mfma_f32_16x16x32_bf16 v[60:63], v[186:189], v[144:147], v[60:63]
	v_mfma_f32_16x16x32_bf16 v[28:31], v[194:197], v[144:147], v[28:31]
	v_mfma_f32_16x16x32_bf16 v[56:59], v[186:189], v[152:155], v[56:59]
	v_mfma_f32_16x16x32_bf16 v[24:27], v[194:197], v[152:155], v[24:27]
	v_mfma_f32_16x16x32_bf16 v[52:55], v[186:189], v[160:163], v[52:55]
	v_mfma_f32_16x16x32_bf16 v[20:23], v[194:197], v[160:163], v[20:23]
	v_mfma_f32_16x16x32_bf16 v[48:51], v[186:189], v[178:181], v[48:51]
	v_mfma_f32_16x16x32_bf16 v[16:19], v[194:197], v[178:181], v[16:19]
	v_mfma_f32_16x16x32_bf16 v[60:63], v[190:193], v[148:151], v[60:63]
	v_mfma_f32_16x16x32_bf16 v[28:31], v[208:211], v[148:151], v[28:31]
	v_mfma_f32_16x16x32_bf16 v[56:59], v[190:193], v[156:159], v[56:59]
	v_mfma_f32_16x16x32_bf16 v[24:27], v[208:211], v[156:159], v[24:27]
	v_mfma_f32_16x16x32_bf16 v[52:55], v[190:193], v[174:177], v[52:55]
	v_mfma_f32_16x16x32_bf16 v[20:23], v[208:211], v[174:177], v[20:23]
	v_mfma_f32_16x16x32_bf16 v[48:51], v[190:193], v[182:185], v[48:51]
	v_mfma_f32_16x16x32_bf16 v[16:19], v[208:211], v[182:185], v[16:19]
	s_barrier
	s_mov_b32 m0, s47
	v_lshl_add_u64 v[204:205], v[214:215], 0, s[0:1]
	ds_read_b128 v[144:147], v199 offset:49152
	ds_read_b128 v[148:151], v199 offset:50176
	ds_read_b128 v[152:155], v199 offset:51200
	ds_read_b128 v[156:159], v199 offset:52224
	ds_read_b128 v[160:163], v199 offset:53248
	ds_read_b128 v[174:177], v199 offset:54272
	ds_read_b128 v[178:181], v199 offset:55296
	ds_read_b128 v[182:185], v199 offset:56320
	global_load_lds_dwordx4 v[204:205], off
	v_lshl_add_u64 v[204:205], v[216:217], 0, s[0:1]
	s_mov_b32 m0, s48
	s_nop 0
	global_load_lds_dwordx4 v[204:205], off
	s_barrier
; #define WAIT_V(n) asm volatile("s_waitcnt vmcnt(" #n ")" ::: "memory")
; #define WAIT_L(n) asm volatile("s_waitcnt lgkmcnt(" #n ")" ::: "memory")
; #define BAR __builtin_amdgcn_s_barrier()
; #define SCHED __builtin_amdgcn_sched_barrier(0)
; template <class Get, class Epi>
; DI void gemm_stream(LAS unsigned char* lds, const int K, const int ld, Get get, Epi epi) {
;     ...
;             LDB(B1, 1, 1); STAGE(SBo(1, 0), b3);
;             BAR; WAIT_L(0); MMA(0, 1, At, B1); BAR;
;             LDA(At, 1, 1); STAGE(SAo(1, 0), a3);
;             BAR; WAIT_L(0); MMA(1, 0, At, B0); BAR; SCHED;
;             STAGE(SBo(1, 1), b3 + hstep);
;             WAIT_V(6); BAR; MMA(1, 1, At, B1); BAR;
;         }
;         epi(acc, cur);
; DI void epi_resid(const Acc& acc, const P& p, int brow, int bcol, int layer, int gch, bool from_input) {
;     EPI_IDX
;     const float* gate = modv(p, layer, brow, gch);
; #pragma unroll
;     for (int bj = 0; bj < 2; ++bj)
; #pragma unroll
;         for (int n = 0; n < 2; ++n) {
;             const int c0 = bcol + bj * 128 + wc * 32 + n * 16 + fq * 4;
;             const f32x4 g = *(const f32x4*)(gate + c0);
;             f32x4 xv[2][4];
; #pragma unroll
;             for (int ai = 0; ai < 2; ++ai)
; #pragma unroll
;                 for (int m = 0; m < 4; ++m) {
;                     const int r = brow + ai * 128 + wr * 64 + m * 16 + fr;
;                     const float* sp = (from_input ? inrow(p, r) : xrow(p, r)) + c0;
;                     xv[ai][m] = *(const f32x4*)sp;
;                 }
;             __builtin_amdgcn_sched_barrier(0);
; #pragma unroll
;             for (int ai = 0; ai < 2; ++ai)
; #pragma unroll
;                 for (int m = 0; m < 4; ++m) {
;                     const int r = brow + ai * 128 + wr * 64 + m * 16 + fr;
;                     *(f32x4*)(xrow(p, r) + c0) = xv[ai][m] + g * acc[ai][bj][m][n];
;                 }
;             __builtin_amdgcn_sched_barrier(0);
;         }
	s_waitcnt lgkmcnt(0)
	v_mfma_f32_16x16x32_bf16 v[108:111], v[128:131], v[144:147], v[108:111]
	v_mfma_f32_16x16x32_bf16 v[76:79], v[136:139], v[144:147], v[76:79]
	v_mfma_f32_16x16x32_bf16 v[104:107], v[128:131], v[152:155], v[104:107]
	v_mfma_f32_16x16x32_bf16 v[72:75], v[136:139], v[152:155], v[72:75]
	v_mfma_f32_16x16x32_bf16 v[100:103], v[128:131], v[160:163], v[100:103]
	v_mfma_f32_16x16x32_bf16 v[68:71], v[136:139], v[160:163], v[68:71]
	v_mfma_f32_16x16x32_bf16 v[96:99], v[128:131], v[178:181], v[96:99]
	v_mfma_f32_16x16x32_bf16 v[64:67], v[136:139], v[178:181], v[64:67]
	v_mfma_f32_16x16x32_bf16 v[108:111], v[132:135], v[148:151], v[108:111]
	v_mfma_f32_16x16x32_bf16 v[76:79], v[140:143], v[148:151], v[76:79]
	v_mfma_f32_16x16x32_bf16 v[104:107], v[132:135], v[156:159], v[104:107]
	v_mfma_f32_16x16x32_bf16 v[72:75], v[140:143], v[156:159], v[72:75]
	v_mfma_f32_16x16x32_bf16 v[100:103], v[132:135], v[174:177], v[100:103]
	v_mfma_f32_16x16x32_bf16 v[68:71], v[140:143], v[174:177], v[68:71]
	v_mfma_f32_16x16x32_bf16 v[96:99], v[132:135], v[182:185], v[96:99]
	v_mfma_f32_16x16x32_bf16 v[64:67], v[140:143], v[182:185], v[64:67]
	s_barrier
	s_add_u32 s6, s10, 0x100080
	s_addc_u32 s7, s11, 0
	s_mov_b32 m0, s68
	v_lshl_add_u64 v[128:129], s[6:7], 0, v[164:165]
	global_load_lds_dwordx4 v[128:129], off
	s_mov_b32 m0, s69
	s_nop 0
	global_load_lds_dwordx4 v166, s[6:7]
	s_add_i32 s16, s16, 2
	s_add_u32 s14, s14, 0x100
	s_addc_u32 s15, s15, 0
	s_cmp_gt_u32 s16, 61
	s_mov_b64 s[6:7], s[8:9]
	s_waitcnt vmcnt(6)
	s_barrier
	v_mfma_f32_16x16x32_bf16 v[44:47], v[186:189], v[144:147], v[44:47]
	v_mfma_f32_16x16x32_bf16 v[12:15], v[194:197], v[144:147], v[12:15]
	v_mfma_f32_16x16x32_bf16 v[40:43], v[186:189], v[152:155], v[40:43]
	v_mfma_f32_16x16x32_bf16 v[8:11], v[194:197], v[152:155], v[8:11]
	v_mfma_f32_16x16x32_bf16 v[36:39], v[186:189], v[160:163], v[36:39]
	v_mfma_f32_16x16x32_bf16 v[4:7], v[194:197], v[160:163], v[4:7]
	v_mfma_f32_16x16x32_bf16 v[32:35], v[186:189], v[178:181], v[32:35]
	v_mfma_f32_16x16x32_bf16 v[0:3], v[194:197], v[178:181], v[0:3]
	v_mfma_f32_16x16x32_bf16 v[44:47], v[190:193], v[148:151], v[44:47]
	v_mfma_f32_16x16x32_bf16 v[12:15], v[208:211], v[148:151], v[12:15]
	v_mfma_f32_16x16x32_bf16 v[40:43], v[190:193], v[156:159], v[40:43]
	v_mfma_f32_16x16x32_bf16 v[8:11], v[208:211], v[156:159], v[8:11]
	v_mfma_f32_16x16x32_bf16 v[36:39], v[190:193], v[174:177], v[36:39]
	v_mfma_f32_16x16x32_bf16 v[4:7], v[208:211], v[174:177], v[4:7]
	v_mfma_f32_16x16x32_bf16 v[32:35], v[190:193], v[182:185], v[32:35]
	v_mfma_f32_16x16x32_bf16 v[0:3], v[208:211], v[182:185], v[0:3]
	s_barrier
	s_cbranch_scc0 .LBB0_2670
	s_lshl_b32 s12, s3, 21
	s_lshl_b32 s13, s2, 10
	s_lshr_b32 s16, s3, 4
	s_add_u32 s12, s12, s13
	s_mul_i32 s16, s16, 6
	s_add_i32 s16, s16, 32
	s_lshl_b32 s16, s16, 13
	s_add_u32 s16, s16, s13
	s_add_u32 s10, s26, s16
	s_addc_u32 s11, s27, 0
	s_add_u32 s6, s24, s12
	s_addc_u32 s7, s25, 0
	v_lshrrev_b32_e32 v224, 6, v206
	v_and_b32_e32 v225, 3, v224
	v_lshrrev_b32_e32 v224, 2, v224
	v_and_b32_e32 v205, 15, v206
	v_bfe_u32 v226, v206, 4, 2
	v_lshl_add_u32 v225, v225, 3, v226
	v_lshl_add_u32 v224, v224, 6, v205
	v_lshlrev_b32_e32 v205, 4, v225
	v_lshl_add_u32 v203, v224, 13, v205
	v_mov_b32_e32 v204, v203
	global_load_dwordx4 v[128:131], v205, s[10:11] offset:0
	global_load_dwordx4 v[132:135], v205, s[10:11] offset:64
	global_load_dwordx4 v[136:139], v205, s[10:11] offset:512
	global_load_dwordx4 v[140:143], v205, s[10:11] offset:576
	global_load_dwordx4 v[144:147], v203, s[6:7] offset:0
	global_load_dwordx4 v[148:151], v203, s[6:7] offset:64
	global_load_dwordx4 v[152:155], v203, s[6:7] offset:512
	global_load_dwordx4 v[156:159], v203, s[6:7] offset:576
	v_add_u32_e32 v203, 0x20000, v203
	global_load_dwordx4 v[160:163], v203, s[6:7] offset:0
	global_load_dwordx4 v[174:177], v203, s[6:7] offset:64
	global_load_dwordx4 v[178:181], v203, s[6:7] offset:512
	global_load_dwordx4 v[182:185], v203, s[6:7] offset:576
	v_add_u32_e32 v203, 0x20000, v203
	global_load_dwordx4 v[186:189], v203, s[6:7] offset:0
	global_load_dwordx4 v[190:193], v203, s[6:7] offset:64
	global_load_dwordx4 v[194:197], v203, s[6:7] offset:512
	global_load_dwordx4 v[208:211], v203, s[6:7] offset:576
	v_add_u32_e32 v203, 0x20000, v203
	global_load_dwordx4 v[212:215], v203, s[6:7] offset:0
	global_load_dwordx4 v[216:219], v203, s[6:7] offset:64
	global_load_dwordx4 v[220:223], v203, s[6:7] offset:512
	global_load_dwordx4 v[224:227], v203, s[6:7] offset:576
	v_add_u32_e32 v203, 0xa0000, v203
	s_waitcnt vmcnt(12)
	v_pk_fma_f32 v[124:125], v[124:125], v[128:129], v[144:145]
	v_pk_fma_f32 v[126:127], v[126:127], v[130:131], v[146:147]
	v_pk_fma_f32 v[92:93], v[92:93], v[132:133], v[148:149]
	v_pk_fma_f32 v[94:95], v[94:95], v[134:135], v[150:151]
	v_pk_fma_f32 v[60:61], v[60:61], v[136:137], v[152:153]
	v_pk_fma_f32 v[62:63], v[62:63], v[138:139], v[154:155]
	v_pk_fma_f32 v[28:29], v[28:29], v[140:141], v[156:157]
	v_pk_fma_f32 v[30:31], v[30:31], v[142:143], v[158:159]
	global_store_dwordx4 v204, v[124:127], s[6:7] offset:0
	global_store_dwordx4 v204, v[92:95], s[6:7] offset:64
	global_store_dwordx4 v204, v[60:63], s[6:7] offset:512
	global_store_dwordx4 v204, v[28:31], s[6:7] offset:576
	v_add_u32_e32 v204, 0x20000, v204
	global_load_dwordx4 v[144:147], v203, s[6:7] offset:0
	global_load_dwordx4 v[148:151], v203, s[6:7] offset:64
	global_load_dwordx4 v[152:155], v203, s[6:7] offset:512
	global_load_dwordx4 v[156:159], v203, s[6:7] offset:576
	v_add_u32_e32 v203, 0x20000, v203
	s_waitcnt vmcnt(16)
; DI void epi_resid(const Acc& acc, const P& p, int brow, int bcol, int layer, int gch, bool from_input) {
;     ...
;     for (int bj = 0; bj < 2; ++bj)
; #pragma unroll
;         for (int n = 0; n < 2; ++n) {
;             const int c0 = bcol + bj * 128 + wc * 32 + n * 16 + fq * 4;
;             const f32x4 g = *(const f32x4*)(gate + c0);
;             f32x4 xv[2][4];
; #pragma unroll
;             for (int ai = 0; ai < 2; ++ai)
; #pragma unroll
;                 for (int m = 0; m < 4; ++m) {
;                     const int r = brow + ai * 128 + wr * 64 + m * 16 + fr;
;                     const float* sp = (from_input ? inrow(p, r) : xrow(p, r)) + c0;
;                     xv[ai][m] = *(const f32x4*)sp;
;                 }
;             __builtin_amdgcn_sched_barrier(0);
; #pragma unroll
;             for (int ai = 0; ai < 2; ++ai)
; #pragma unroll
;                 for (int m = 0; m < 4; ++m) {
;                     const int r = brow + ai * 128 + wr * 64 + m * 16 + fr;
;                     *(f32x4*)(xrow(p, r) + c0) = xv[ai][m] + g * acc[ai][bj][m][n];
;                 }
;             __builtin_amdgcn_sched_barrier(0);
	v_pk_fma_f32 v[120:121], v[120:121], v[128:129], v[160:161]
	v_pk_fma_f32 v[122:123], v[122:123], v[130:131], v[162:163]
	v_pk_fma_f32 v[88:89], v[88:89], v[132:133], v[174:175]
	v_pk_fma_f32 v[90:91], v[90:91], v[134:135], v[176:177]
	v_pk_fma_f32 v[56:57], v[56:57], v[136:137], v[178:179]
	v_pk_fma_f32 v[58:59], v[58:59], v[138:139], v[180:181]
	v_pk_fma_f32 v[24:25], v[24:25], v[140:141], v[182:183]
	v_pk_fma_f32 v[26:27], v[26:27], v[142:143], v[184:185]
	global_store_dwordx4 v204, v[120:123], s[6:7] offset:0
	global_store_dwordx4 v204, v[88:91], s[6:7] offset:64
	global_store_dwordx4 v204, v[56:59], s[6:7] offset:512
	global_store_dwordx4 v204, v[24:27], s[6:7] offset:576
	v_add_u32_e32 v204, 0x20000, v204
	global_load_dwordx4 v[160:163], v203, s[6:7] offset:0
	global_load_dwordx4 v[174:177], v203, s[6:7] offset:64
	global_load_dwordx4 v[178:181], v203, s[6:7] offset:512
	global_load_dwordx4 v[182:185], v203, s[6:7] offset:576
	v_add_u32_e32 v203, 0x20000, v203
	s_waitcnt vmcnt(20)
	v_pk_fma_f32 v[116:117], v[116:117], v[128:129], v[186:187]
	v_pk_fma_f32 v[118:119], v[118:119], v[130:131], v[188:189]
	v_pk_fma_f32 v[84:85], v[84:85], v[132:133], v[190:191]
	v_pk_fma_f32 v[86:87], v[86:87], v[134:135], v[192:193]
	v_pk_fma_f32 v[52:53], v[52:53], v[136:137], v[194:195]
	v_pk_fma_f32 v[54:55], v[54:55], v[138:139], v[196:197]
	v_pk_fma_f32 v[20:21], v[20:21], v[140:141], v[208:209]
	v_pk_fma_f32 v[22:23], v[22:23], v[142:143], v[210:211]
	global_store_dwordx4 v204, v[116:119], s[6:7] offset:0
	global_store_dwordx4 v204, v[84:87], s[6:7] offset:64
	global_store_dwordx4 v204, v[52:55], s[6:7] offset:512
	global_store_dwordx4 v204, v[20:23], s[6:7] offset:576
	v_add_u32_e32 v204, 0x20000, v204
	global_load_dwordx4 v[186:189], v203, s[6:7] offset:0
	global_load_dwordx4 v[190:193], v203, s[6:7] offset:64
	global_load_dwordx4 v[194:197], v203, s[6:7] offset:512
	global_load_dwordx4 v[208:211], v203, s[6:7] offset:576
	v_add_u32_e32 v203, 0x20000, v203
	s_waitcnt vmcnt(24)
	v_pk_fma_f32 v[112:113], v[112:113], v[128:129], v[212:213]
	v_pk_fma_f32 v[114:115], v[114:115], v[130:131], v[214:215]
	v_pk_fma_f32 v[80:81], v[80:81], v[132:133], v[216:217]
	v_pk_fma_f32 v[82:83], v[82:83], v[134:135], v[218:219]
	v_pk_fma_f32 v[48:49], v[48:49], v[136:137], v[220:221]
	v_pk_fma_f32 v[50:51], v[50:51], v[138:139], v[222:223]
	v_pk_fma_f32 v[16:17], v[16:17], v[140:141], v[224:225]
	v_pk_fma_f32 v[18:19], v[18:19], v[142:143], v[226:227]
	global_store_dwordx4 v204, v[112:115], s[6:7] offset:0
	global_store_dwordx4 v204, v[80:83], s[6:7] offset:64
	global_store_dwordx4 v204, v[48:51], s[6:7] offset:512
	global_store_dwordx4 v204, v[16:19], s[6:7] offset:576
	v_add_u32_e32 v204, 0xa0000, v204
	global_load_dwordx4 v[212:215], v203, s[6:7] offset:0
	global_load_dwordx4 v[216:219], v203, s[6:7] offset:64
	global_load_dwordx4 v[220:223], v203, s[6:7] offset:512
	global_load_dwordx4 v[224:227], v203, s[6:7] offset:576
	s_waitcnt vmcnt(24)
	v_pk_fma_f32 v[108:109], v[108:109], v[128:129], v[144:145]
	v_pk_fma_f32 v[110:111], v[110:111], v[130:131], v[146:147]
	v_pk_fma_f32 v[76:77], v[76:77], v[132:133], v[148:149]
	v_pk_fma_f32 v[78:79], v[78:79], v[134:135], v[150:151]
	v_pk_fma_f32 v[44:45], v[44:45], v[136:137], v[152:153]
	v_pk_fma_f32 v[46:47], v[46:47], v[138:139], v[154:155]
	v_pk_fma_f32 v[12:13], v[12:13], v[140:141], v[156:157]
	v_pk_fma_f32 v[14:15], v[14:15], v[142:143], v[158:159]
	global_store_dwordx4 v204, v[108:111], s[6:7] offset:0
	global_store_dwordx4 v204, v[76:79], s[6:7] offset:64
	global_store_dwordx4 v204, v[44:47], s[6:7] offset:512
	global_store_dwordx4 v204, v[12:15], s[6:7] offset:576
	v_add_u32_e32 v204, 0x20000, v204
	s_waitcnt vmcnt(20)
	v_pk_fma_f32 v[104:105], v[104:105], v[128:129], v[160:161]
	v_pk_fma_f32 v[106:107], v[106:107], v[130:131], v[162:163]
	v_pk_fma_f32 v[72:73], v[72:73], v[132:133], v[174:175]
	v_pk_fma_f32 v[74:75], v[74:75], v[134:135], v[176:177]
	v_pk_fma_f32 v[40:41], v[40:41], v[136:137], v[178:179]
	v_pk_fma_f32 v[42:43], v[42:43], v[138:139], v[180:181]
	v_pk_fma_f32 v[8:9], v[8:9], v[140:141], v[182:183]
	v_pk_fma_f32 v[10:11], v[10:11], v[142:143], v[184:185]
	global_store_dwordx4 v204, v[104:107], s[6:7] offset:0
	global_store_dwordx4 v204, v[72:75], s[6:7] offset:64
	global_store_dwordx4 v204, v[40:43], s[6:7] offset:512
	global_store_dwordx4 v204, v[8:11], s[6:7] offset:576
	v_add_u32_e32 v204, 0x20000, v204
	s_waitcnt vmcnt(16)
	v_pk_fma_f32 v[100:101], v[100:101], v[128:129], v[186:187]
	v_pk_fma_f32 v[102:103], v[102:103], v[130:131], v[188:189]
	v_pk_fma_f32 v[68:69], v[68:69], v[132:133], v[190:191]
	v_pk_fma_f32 v[70:71], v[70:71], v[134:135], v[192:193]
	v_pk_fma_f32 v[36:37], v[36:37], v[136:137], v[194:195]
	v_pk_fma_f32 v[38:39], v[38:39], v[138:139], v[196:197]
	v_pk_fma_f32 v[4:5], v[4:5], v[140:141], v[208:209]
	v_pk_fma_f32 v[6:7], v[6:7], v[142:143], v[210:211]
	global_store_dwordx4 v204, v[100:103], s[6:7] offset:0
	global_store_dwordx4 v204, v[68:71], s[6:7] offset:64
	global_store_dwordx4 v204, v[36:39], s[6:7] offset:512
	global_store_dwordx4 v204, v[4:7], s[6:7] offset:576
	v_add_u32_e32 v204, 0x20000, v204
	s_waitcnt vmcnt(12)
	v_pk_fma_f32 v[96:97], v[96:97], v[128:129], v[212:213]
	v_pk_fma_f32 v[98:99], v[98:99], v[130:131], v[214:215]
	v_pk_fma_f32 v[64:65], v[64:65], v[132:133], v[216:217]
	v_pk_fma_f32 v[66:67], v[66:67], v[134:135], v[218:219]
	v_pk_fma_f32 v[32:33], v[32:33], v[136:137], v[220:221]
	v_pk_fma_f32 v[34:35], v[34:35], v[138:139], v[222:223]
	v_pk_fma_f32 v[0:1], v[0:1], v[140:141], v[224:225]
	v_pk_fma_f32 v[2:3], v[2:3], v[142:143], v[226:227]
	global_store_dwordx4 v204, v[96:99], s[6:7] offset:0
	global_store_dwordx4 v204, v[64:67], s[6:7] offset:64
	global_store_dwordx4 v204, v[32:35], s[6:7] offset:512
	global_store_dwordx4 v204, v[0:3], s[6:7] offset:576
	s_branch .Lresid_latch_wout1

; #define WAIT_V(n) asm volatile("s_waitcnt vmcnt(" #n ")" ::: "memory")
; #define WAIT_L(n) asm volatile("s_waitcnt lgkmcnt(" #n ")" ::: "memory")
; #define BAR __builtin_amdgcn_s_barrier()
; #define SCHED __builtin_amdgcn_sched_barrier(0)
; template <class Get, class Epi>
; DI void gemm_stream(LAS unsigned char* lds, const int K, const int ld, Get get, Epi epi) {
;     ...
;             LDB(B0, 0, 0); SCHED; LDA(At, 0, 0); STAGE(SAo(1, 1), a1 + hstep);
;             WAIT_L(8); BAR; WAIT_L(0); MMA(0, 0, At, B0); BAR; SCHED;
;             LDB(B1, 0, 1); STAGE(SBo(0, 0), b2);
;             BAR; WAIT_L(0); MMA(0, 1, At, B1); BAR;
;             LDA(At, 0, 1); STAGE(SAo(0, 0), a2);
;             BAR; WAIT_L(0); MMA(1, 0, At, B0); BAR; SCHED;
;             STAGE(SBo(0, 1), b2 + hstep);
;             WAIT_V(6); BAR; MMA(1, 1, At, B1); BAR;
;             LDB(B0, 1, 0); SCHED; LDA(At, 1, 0); STAGE(SAo(0, 1), a2 + hstep);
;             WAIT_L(8); BAR; WAIT_L(0); MMA(0, 0, At, B0); BAR; SCHED;
;             LDB(B1, 1, 1); STAGE(SBo(1, 0), b3);
;             BAR; WAIT_L(0); MMA(0, 1, At, B1); BAR;
;             LDA(At, 1, 1); STAGE(SAo(1, 0), a3);
;             BAR; WAIT_L(0); MMA(1, 0, At, B0); BAR; SCHED;
;             STAGE(SBo(1, 1), b3 + hstep);
;             WAIT_V(6); BAR; MMA(1, 1, At, B1); BAR;
.LBB0_3046:
	ds_read_b128 v[148:151], v142
	ds_read_b128 v[152:155], v142 offset:1024
	ds_read_b128 v[156:159], v142 offset:2048
	ds_read_b128 v[160:163], v142 offset:3072
	s_add_u32 s14, s12, 0xfff80080
	s_addc_u32 s15, s13, -1
	s_cmp_eq_u32 s56, 28
	s_cselect_b32 s17, s9, s15
	s_cselect_b32 s16, s8, s14
	s_cselect_b32 s15, s11, s55
	s_cselect_b32 s14, s10, s0
	s_mov_b32 m0, s38
	ds_read_b128 v[164:167], v143
	ds_read_b128 v[168:171], v143 offset:1024
	ds_read_b128 v[172:175], v143 offset:2048
	ds_read_b128 v[176:179], v143 offset:3072
	ds_read_b128 v[180:183], v143 offset:4096
	ds_read_b128 v[184:187], v143 offset:5120
	ds_read_b128 v[188:191], v143 offset:6144
	ds_read_b128 v[192:195], v143 offset:7168
	global_load_lds_dwordx4 v134, s[12:13]
	s_mov_b32 m0, s39
	s_nop 0
	global_load_lds_dwordx4 v136, s[12:13]
	s_waitcnt lgkmcnt(8)
	s_barrier
	s_waitcnt lgkmcnt(0)
	v_mfma_f32_16x16x32_bf16 v[124:127], v[148:151], v[164:167], v[124:127]
	v_mfma_f32_16x16x32_bf16 v[116:119], v[156:159], v[164:167], v[116:119]
	v_mfma_f32_16x16x32_bf16 v[108:111], v[148:151], v[172:175], v[108:111]
	v_mfma_f32_16x16x32_bf16 v[100:103], v[156:159], v[172:175], v[100:103]
	v_mfma_f32_16x16x32_bf16 v[92:95], v[148:151], v[180:183], v[92:95]
	v_mfma_f32_16x16x32_bf16 v[84:87], v[156:159], v[180:183], v[84:87]
	v_mfma_f32_16x16x32_bf16 v[76:79], v[148:151], v[188:191], v[76:79]
	v_mfma_f32_16x16x32_bf16 v[68:71], v[156:159], v[188:191], v[68:71]
	v_mfma_f32_16x16x32_bf16 v[124:127], v[152:155], v[168:171], v[124:127]
	v_mfma_f32_16x16x32_bf16 v[116:119], v[160:163], v[168:171], v[116:119]
	v_mfma_f32_16x16x32_bf16 v[108:111], v[152:155], v[176:179], v[108:111]
	v_mfma_f32_16x16x32_bf16 v[100:103], v[160:163], v[176:179], v[100:103]
	v_mfma_f32_16x16x32_bf16 v[92:95], v[152:155], v[184:187], v[92:95]
	v_mfma_f32_16x16x32_bf16 v[84:87], v[160:163], v[184:187], v[84:87]
	v_mfma_f32_16x16x32_bf16 v[76:79], v[152:155], v[192:195], v[76:79]
	v_mfma_f32_16x16x32_bf16 v[68:71], v[160:163], v[192:195], v[68:71]
	s_barrier
	s_mov_b32 m0, s40
	v_lshl_add_u64 v[140:141], s[14:15], 0, v[130:131]
	ds_read_b128 v[196:199], v144
	ds_read_b128 v[200:203], v144 offset:1024
	ds_read_b128 v[208:211], v144 offset:2048
	ds_read_b128 v[212:215], v144 offset:3072
	global_load_lds_dwordx4 v[140:141], off
	v_lshl_add_u64 v[204:205], s[14:15], 0, v[128:129]
	s_mov_b32 m0, s41
	s_nop 0
	global_load_lds_dwordx4 v[204:205], off
	s_barrier
	s_waitcnt lgkmcnt(0)
	v_mfma_f32_16x16x32_bf16 v[120:123], v[196:199], v[164:167], v[120:123]
	v_mfma_f32_16x16x32_bf16 v[112:115], v[208:211], v[164:167], v[112:115]
	v_mfma_f32_16x16x32_bf16 v[104:107], v[196:199], v[172:175], v[104:107]
	v_mfma_f32_16x16x32_bf16 v[96:99], v[208:211], v[172:175], v[96:99]
	v_mfma_f32_16x16x32_bf16 v[88:91], v[196:199], v[180:183], v[88:91]
	v_mfma_f32_16x16x32_bf16 v[80:83], v[208:211], v[180:183], v[80:83]
	v_mfma_f32_16x16x32_bf16 v[72:75], v[196:199], v[188:191], v[72:75]
	v_mfma_f32_16x16x32_bf16 v[64:67], v[208:211], v[188:191], v[64:67]
	v_mfma_f32_16x16x32_bf16 v[120:123], v[200:203], v[168:171], v[120:123]
	v_mfma_f32_16x16x32_bf16 v[112:115], v[212:215], v[168:171], v[112:115]
	v_mfma_f32_16x16x32_bf16 v[104:107], v[200:203], v[176:179], v[104:107]
	v_mfma_f32_16x16x32_bf16 v[96:99], v[212:215], v[176:179], v[96:99]
	v_mfma_f32_16x16x32_bf16 v[88:91], v[200:203], v[184:187], v[88:91]
	v_mfma_f32_16x16x32_bf16 v[80:83], v[212:215], v[184:187], v[80:83]
	v_mfma_f32_16x16x32_bf16 v[72:75], v[200:203], v[192:195], v[72:75]
	v_mfma_f32_16x16x32_bf16 v[64:67], v[212:215], v[192:195], v[64:67]
	s_barrier
	s_mov_b32 m0, s19
	v_lshl_add_u64 v[216:217], s[16:17], 0, v[130:131]
	ds_read_b128 v[164:167], v143 offset:16384
	ds_read_b128 v[168:171], v143 offset:17408
	ds_read_b128 v[172:175], v143 offset:18432
	ds_read_b128 v[176:179], v143 offset:19456
	ds_read_b128 v[180:183], v143 offset:20480
	ds_read_b128 v[184:187], v143 offset:21504
	ds_read_b128 v[188:191], v143 offset:22528
	ds_read_b128 v[192:195], v143 offset:23552
	global_load_lds_dwordx4 v[216:217], off
	v_lshl_add_u64 v[218:219], s[16:17], 0, v[128:129]
	s_mov_b32 m0, s20
	s_nop 0
	global_load_lds_dwordx4 v[218:219], off
	s_barrier
	s_waitcnt lgkmcnt(0)
	v_mfma_f32_16x16x32_bf16 v[60:63], v[148:151], v[164:167], v[60:63]
	v_mfma_f32_16x16x32_bf16 v[52:55], v[156:159], v[164:167], v[52:55]
	v_mfma_f32_16x16x32_bf16 v[44:47], v[148:151], v[172:175], v[44:47]
	v_mfma_f32_16x16x32_bf16 v[36:39], v[156:159], v[172:175], v[36:39]
	v_mfma_f32_16x16x32_bf16 v[28:31], v[148:151], v[180:183], v[28:31]
	v_mfma_f32_16x16x32_bf16 v[20:23], v[156:159], v[180:183], v[20:23]
	v_mfma_f32_16x16x32_bf16 v[12:15], v[148:151], v[188:191], v[12:15]
	v_mfma_f32_16x16x32_bf16 v[4:7], v[156:159], v[188:191], v[4:7]
	v_mfma_f32_16x16x32_bf16 v[60:63], v[152:155], v[168:171], v[60:63]
	v_mfma_f32_16x16x32_bf16 v[52:55], v[160:163], v[168:171], v[52:55]
	v_mfma_f32_16x16x32_bf16 v[44:47], v[152:155], v[176:179], v[44:47]
	v_mfma_f32_16x16x32_bf16 v[36:39], v[160:163], v[176:179], v[36:39]
	v_mfma_f32_16x16x32_bf16 v[28:31], v[152:155], v[184:187], v[28:31]
	v_mfma_f32_16x16x32_bf16 v[20:23], v[160:163], v[184:187], v[20:23]
	v_mfma_f32_16x16x32_bf16 v[12:15], v[152:155], v[192:195], v[12:15]
	v_mfma_f32_16x16x32_bf16 v[4:7], v[160:163], v[192:195], v[4:7]
	s_barrier
	s_add_u32 s58, s14, 0x80000
	s_addc_u32 s59, s15, 0
	s_mov_b32 m0, s42
	v_lshl_add_u64 v[148:149], s[58:59], 0, v[130:131]
	global_load_lds_dwordx4 v[148:149], off
	s_mov_b32 m0, s43
	s_nop 0
	global_load_lds_dwordx4 v128, s[58:59]
	s_waitcnt vmcnt(6)
	s_barrier
; #define WAIT_V(n) asm volatile("s_waitcnt vmcnt(" #n ")" ::: "memory")
; #define WAIT_L(n) asm volatile("s_waitcnt lgkmcnt(" #n ")" ::: "memory")
; #define BAR __builtin_amdgcn_s_barrier()
; #define SCHED __builtin_amdgcn_sched_barrier(0)
; template <class Get, class Epi>
; DI void gemm_stream(LAS unsigned char* lds, const int K, const int ld, Get get, Epi epi) {
;     ...
;             LDB(B0, 0, 0); SCHED; LDA(At, 0, 0); STAGE(SAo(1, 1), a1 + hstep);
;             WAIT_L(8); BAR; WAIT_L(0); MMA(0, 0, At, B0); BAR; SCHED;
;             LDB(B1, 0, 1); STAGE(SBo(0, 0), b2);
;             BAR; WAIT_L(0); MMA(0, 1, At, B1); BAR;
;             LDA(At, 0, 1); STAGE(SAo(0, 0), a2);
;             BAR; WAIT_L(0); MMA(1, 0, At, B0); BAR; SCHED;
;             STAGE(SBo(0, 1), b2 + hstep);
;             WAIT_V(6); BAR; MMA(1, 1, At, B1); BAR;
;             LDB(B0, 1, 0); SCHED; LDA(At, 1, 0); STAGE(SAo(0, 1), a2 + hstep);
;             WAIT_L(8); BAR; WAIT_L(0); MMA(0, 0, At, B0); BAR; SCHED;
;             LDB(B1, 1, 1); STAGE(SBo(1, 0), b3);
;             BAR; WAIT_L(0); MMA(0, 1, At, B1); BAR;
;             LDA(At, 1, 1); STAGE(SAo(1, 0), a3);
;             BAR; WAIT_L(0); MMA(1, 0, At, B0); BAR; SCHED;
;             STAGE(SBo(1, 1), b3 + hstep);
;             WAIT_V(6); BAR; MMA(1, 1, At, B1); BAR;
	v_mfma_f32_16x16x32_bf16 v[56:59], v[196:199], v[164:167], v[56:59]
	v_mfma_f32_16x16x32_bf16 v[48:51], v[208:211], v[164:167], v[48:51]
	v_mfma_f32_16x16x32_bf16 v[40:43], v[196:199], v[172:175], v[40:43]
	v_mfma_f32_16x16x32_bf16 v[32:35], v[208:211], v[172:175], v[32:35]
	v_mfma_f32_16x16x32_bf16 v[24:27], v[196:199], v[180:183], v[24:27]
	v_mfma_f32_16x16x32_bf16 v[16:19], v[208:211], v[180:183], v[16:19]
	v_mfma_f32_16x16x32_bf16 v[8:11], v[196:199], v[188:191], v[8:11]
	v_mfma_f32_16x16x32_bf16 v[0:3], v[208:211], v[188:191], v[0:3]
	v_mfma_f32_16x16x32_bf16 v[56:59], v[200:203], v[168:171], v[56:59]
	v_mfma_f32_16x16x32_bf16 v[48:51], v[212:215], v[168:171], v[48:51]
	v_mfma_f32_16x16x32_bf16 v[40:43], v[200:203], v[176:179], v[40:43]
	v_mfma_f32_16x16x32_bf16 v[32:35], v[212:215], v[176:179], v[32:35]
	v_mfma_f32_16x16x32_bf16 v[24:27], v[200:203], v[184:187], v[24:27]
	v_mfma_f32_16x16x32_bf16 v[16:19], v[212:215], v[184:187], v[16:19]
	v_mfma_f32_16x16x32_bf16 v[8:11], v[200:203], v[192:195], v[8:11]
	v_mfma_f32_16x16x32_bf16 v[0:3], v[212:215], v[192:195], v[0:3]
	s_barrier
	ds_read_b128 v[148:151], v145
	ds_read_b128 v[152:155], v145 offset:1024
	ds_read_b128 v[156:159], v145 offset:2048
	ds_read_b128 v[160:163], v145 offset:3072
	s_add_u32 s16, s16, 0x80000
	s_addc_u32 s17, s17, 0
	s_mov_b32 m0, s21
	ds_read_b128 v[164:167], v143 offset:32768
	ds_read_b128 v[168:171], v143 offset:33792
	ds_read_b128 v[172:175], v143 offset:34816
	ds_read_b128 v[176:179], v143 offset:35840
	ds_read_b128 v[180:183], v143 offset:36864
	ds_read_b128 v[184:187], v143 offset:37888
	ds_read_b128 v[188:191], v143 offset:38912
	ds_read_b128 v[192:195], v143 offset:39936
	global_load_lds_dwordx4 v130, s[16:17]
	s_mov_b32 m0, s28
	s_nop 0
	global_load_lds_dwordx4 v128, s[16:17]
	s_waitcnt lgkmcnt(8)
	s_barrier
	s_waitcnt lgkmcnt(0)
	v_mfma_f32_16x16x32_bf16 v[124:127], v[148:151], v[164:167], v[124:127]
	v_mfma_f32_16x16x32_bf16 v[116:119], v[156:159], v[164:167], v[116:119]
	v_mfma_f32_16x16x32_bf16 v[108:111], v[148:151], v[172:175], v[108:111]
	v_mfma_f32_16x16x32_bf16 v[100:103], v[156:159], v[172:175], v[100:103]
	v_mfma_f32_16x16x32_bf16 v[92:95], v[148:151], v[180:183], v[92:95]
	v_mfma_f32_16x16x32_bf16 v[84:87], v[156:159], v[180:183], v[84:87]
	v_mfma_f32_16x16x32_bf16 v[76:79], v[148:151], v[188:191], v[76:79]
	v_mfma_f32_16x16x32_bf16 v[68:71], v[156:159], v[188:191], v[68:71]
	v_mfma_f32_16x16x32_bf16 v[124:127], v[152:155], v[168:171], v[124:127]
	v_mfma_f32_16x16x32_bf16 v[116:119], v[160:163], v[168:171], v[116:119]
	v_mfma_f32_16x16x32_bf16 v[108:111], v[152:155], v[176:179], v[108:111]
	v_mfma_f32_16x16x32_bf16 v[100:103], v[160:163], v[176:179], v[100:103]
	v_mfma_f32_16x16x32_bf16 v[92:95], v[152:155], v[184:187], v[92:95]
	v_mfma_f32_16x16x32_bf16 v[84:87], v[160:163], v[184:187], v[84:87]
	v_mfma_f32_16x16x32_bf16 v[76:79], v[152:155], v[192:195], v[76:79]
	v_mfma_f32_16x16x32_bf16 v[68:71], v[160:163], v[192:195], v[68:71]
	s_barrier
	s_mov_b32 m0, s44
	v_lshl_add_u64 v[140:141], v[140:141], 0, s[6:7]
	ds_read_b128 v[196:199], v146
	ds_read_b128 v[200:203], v146 offset:1024
	ds_read_b128 v[208:211], v146 offset:2048
	ds_read_b128 v[212:215], v146 offset:3072
	global_load_lds_dwordx4 v[140:141], off
	v_lshl_add_u64 v[140:141], v[204:205], 0, s[6:7]
	s_mov_b32 m0, s45
	s_nop 0
	global_load_lds_dwordx4 v[140:141], off
	s_barrier
	s_waitcnt lgkmcnt(0)
	v_mfma_f32_16x16x32_bf16 v[120:123], v[196:199], v[164:167], v[120:123]
	v_mfma_f32_16x16x32_bf16 v[112:115], v[208:211], v[164:167], v[112:115]
	v_mfma_f32_16x16x32_bf16 v[104:107], v[196:199], v[172:175], v[104:107]
	v_mfma_f32_16x16x32_bf16 v[96:99], v[208:211], v[172:175], v[96:99]
	v_mfma_f32_16x16x32_bf16 v[88:91], v[196:199], v[180:183], v[88:91]
	v_mfma_f32_16x16x32_bf16 v[80:83], v[208:211], v[180:183], v[80:83]
	v_mfma_f32_16x16x32_bf16 v[72:75], v[196:199], v[188:191], v[72:75]
	v_mfma_f32_16x16x32_bf16 v[64:67], v[208:211], v[188:191], v[64:67]
	v_mfma_f32_16x16x32_bf16 v[120:123], v[200:203], v[168:171], v[120:123]
	v_mfma_f32_16x16x32_bf16 v[112:115], v[212:215], v[168:171], v[112:115]
	v_mfma_f32_16x16x32_bf16 v[104:107], v[200:203], v[176:179], v[104:107]
	v_mfma_f32_16x16x32_bf16 v[96:99], v[212:215], v[176:179], v[96:99]
	v_mfma_f32_16x16x32_bf16 v[88:91], v[200:203], v[184:187], v[88:91]
	v_mfma_f32_16x16x32_bf16 v[80:83], v[212:215], v[184:187], v[80:83]
	v_mfma_f32_16x16x32_bf16 v[72:75], v[200:203], v[192:195], v[72:75]
	v_mfma_f32_16x16x32_bf16 v[64:67], v[212:215], v[192:195], v[64:67]
	s_barrier
	s_mov_b32 m0, s29
	v_lshl_add_u64 v[140:141], v[216:217], 0, s[6:7]
	ds_read_b128 v[164:167], v143 offset:49152
	ds_read_b128 v[168:171], v143 offset:50176
	ds_read_b128 v[172:175], v143 offset:51200
	ds_read_b128 v[176:179], v143 offset:52224
	ds_read_b128 v[180:183], v143 offset:53248
	ds_read_b128 v[184:187], v143 offset:54272
	ds_read_b128 v[188:191], v143 offset:55296
	ds_read_b128 v[192:195], v143 offset:56320
	global_load_lds_dwordx4 v[140:141], off
	v_lshl_add_u64 v[140:141], v[218:219], 0, s[6:7]
	s_mov_b32 m0, s36
	s_nop 0
	global_load_lds_dwordx4 v[140:141], off
	s_barrier
; DI float silu_f(float g) { return g * __builtin_amdgcn_rcpf(1.f + __builtin_amdgcn_exp2f(-LOG2E * g)); }
; #define WAIT_V(n) asm volatile("s_waitcnt vmcnt(" #n ")" ::: "memory")
; #define WAIT_L(n) asm volatile("s_waitcnt lgkmcnt(" #n ")" ::: "memory")
; #define BAR __builtin_amdgcn_s_barrier()
; #define SCHED __builtin_amdgcn_sched_barrier(0)
; template <class Get, class Epi>
; DI void gemm_stream(LAS unsigned char* lds, const int K, const int ld, Get get, Epi epi) {
;     ...
;             LDA(At, 1, 1); STAGE(SAo(1, 0), a3);
;             BAR; WAIT_L(0); MMA(1, 0, At, B0); BAR; SCHED;
;             STAGE(SBo(1, 1), b3 + hstep);
;             WAIT_V(6); BAR; MMA(1, 1, At, B1); BAR;
;         }
;         epi(acc, cur);
;         if (!has_next) break;
;         ZERO_ACC;
;         cur = nxt; cA = nA; cB = nB; ++ui;
;     }
; DI void epi_swiglu(const Acc& acc, int brow, int pn, bf16_t* hid) {
;     EPI_IDX
; #pragma unroll
;     for (int ai = 0; ai < 2; ++ai)
; #pragma unroll
;         for (int m = 0; m < 4; ++m) {
;             const int r = brow + ai * 128 + wr * 64 + m * 16 + fr;
;             bf16_t* rp = hid + (size_t)r * FF + pn * 128 + wc * 32 + fq * 4;
; #pragma unroll
;             for (int n = 0; n < 2; ++n) {
;                 const f32x4 g = acc[ai][0][m][n], u = acc[ai][1][m][n];
;                 float o[4];
; #pragma unroll
;                 for (int j = 0; j < 4; ++j) o[j] = silu_f(g[j]) * u[j];
;                 st4(rp + n * 16, o[0], o[1], o[2], o[3]);
;             }
;         }
	s_waitcnt lgkmcnt(0)
	v_mfma_f32_16x16x32_bf16 v[60:63], v[148:151], v[164:167], v[60:63]
	v_mfma_f32_16x16x32_bf16 v[52:55], v[156:159], v[164:167], v[52:55]
	v_mfma_f32_16x16x32_bf16 v[44:47], v[148:151], v[172:175], v[44:47]
	v_mfma_f32_16x16x32_bf16 v[36:39], v[156:159], v[172:175], v[36:39]
	v_mfma_f32_16x16x32_bf16 v[28:31], v[148:151], v[180:183], v[28:31]
	v_mfma_f32_16x16x32_bf16 v[20:23], v[156:159], v[180:183], v[20:23]
	v_mfma_f32_16x16x32_bf16 v[12:15], v[148:151], v[188:191], v[12:15]
	v_mfma_f32_16x16x32_bf16 v[4:7], v[156:159], v[188:191], v[4:7]
	v_mfma_f32_16x16x32_bf16 v[60:63], v[152:155], v[168:171], v[60:63]
	v_mfma_f32_16x16x32_bf16 v[52:55], v[160:163], v[168:171], v[52:55]
	v_mfma_f32_16x16x32_bf16 v[44:47], v[152:155], v[176:179], v[44:47]
	v_mfma_f32_16x16x32_bf16 v[36:39], v[160:163], v[176:179], v[36:39]
	v_mfma_f32_16x16x32_bf16 v[28:31], v[152:155], v[184:187], v[28:31]
	v_mfma_f32_16x16x32_bf16 v[20:23], v[160:163], v[184:187], v[20:23]
	v_mfma_f32_16x16x32_bf16 v[12:15], v[152:155], v[192:195], v[12:15]
	v_mfma_f32_16x16x32_bf16 v[4:7], v[160:163], v[192:195], v[4:7]
	s_barrier
	s_add_u32 s14, s14, 0x80080
	s_addc_u32 s15, s15, 0
	s_mov_b32 m0, s46
	v_lshl_add_u64 v[140:141], s[14:15], 0, v[130:131]
	global_load_lds_dwordx4 v[140:141], off
	v_lshl_add_u64 v[140:141], s[14:15], 0, v[128:129]
	s_mov_b32 m0, s47
	s_nop 0
	global_load_lds_dwordx4 v[140:141], off
	s_add_i32 s56, s56, 2
	s_add_u32 s12, s12, 0x100
	s_addc_u32 s13, s13, 0
	s_add_u32 s0, s0, 0x100
	s_addc_u32 s55, s55, 0
	s_cmp_gt_u32 s56, 29
	s_waitcnt vmcnt(6)
	s_barrier
	v_mfma_f32_16x16x32_bf16 v[56:59], v[196:199], v[164:167], v[56:59]
	v_mfma_f32_16x16x32_bf16 v[48:51], v[208:211], v[164:167], v[48:51]
	v_mfma_f32_16x16x32_bf16 v[40:43], v[196:199], v[172:175], v[40:43]
	v_mfma_f32_16x16x32_bf16 v[32:35], v[208:211], v[172:175], v[32:35]
	v_mfma_f32_16x16x32_bf16 v[24:27], v[196:199], v[180:183], v[24:27]
	v_mfma_f32_16x16x32_bf16 v[16:19], v[208:211], v[180:183], v[16:19]
	v_mfma_f32_16x16x32_bf16 v[8:11], v[196:199], v[188:191], v[8:11]
	v_mfma_f32_16x16x32_bf16 v[0:3], v[208:211], v[188:191], v[0:3]
	v_mfma_f32_16x16x32_bf16 v[56:59], v[200:203], v[168:171], v[56:59]
	v_mfma_f32_16x16x32_bf16 v[48:51], v[212:215], v[168:171], v[48:51]
	v_mfma_f32_16x16x32_bf16 v[40:43], v[200:203], v[176:179], v[40:43]
	v_mfma_f32_16x16x32_bf16 v[32:35], v[212:215], v[176:179], v[32:35]
	v_mfma_f32_16x16x32_bf16 v[24:27], v[200:203], v[184:187], v[24:27]
	v_mfma_f32_16x16x32_bf16 v[16:19], v[212:215], v[184:187], v[16:19]
	v_mfma_f32_16x16x32_bf16 v[8:11], v[200:203], v[192:195], v[8:11]
	v_mfma_f32_16x16x32_bf16 v[0:3], v[212:215], v[192:195], v[0:3]
	s_barrier
	s_cbranch_scc0 .LBB0_3046
	s_lshr_b32 s0, s53, 4
	s_lshl_b32 s12, s53, 8
	s_mulk_i32 s0, 0x1100
	s_and_b32 s12, s12, 0xf00
	s_add_i32 s0, s0, s12
	s_lshl_b32 s12, s54, 7
	s_ashr_i32 s13, s12, 31
	s_addk_i32 s0, 0x100
	v_mov_b32_e32 v132, v206
	s_lshl_b64 s[12:13], s[12:13], 1
	s_add_u32 s12, s23, s12
	v_ashrrev_i32_e32 v140, 2, v132
	v_and_b32_e32 v140, 0xffffffc0, v140
	v_and_or_b32 v141, v132, 15, s0
	s_addc_u32 s13, s35, s13
	v_lshrrev_b32_e32 v148, 1, v132
	v_and_b32_e32 v132, 0xc0, v132
	v_add_u32_e32 v147, v141, v140
	v_lshl_add_u64 v[140:141], s[12:13], 0, v[132:133]
	v_and_b32_e32 v132, 24, v148
	v_mul_f32_e32 v148, 0xbfb8aa3b, v124
	v_exp_f32_e32 v148, v148
	v_mul_f32_e32 v149, 0xbfb8aa3b, v125
	v_exp_f32_e32 v149, v149
	v_lshl_add_u64 v[140:141], v[140:141], 0, v[132:133]
	v_add_f32_e32 v132, 1.0, v148
	v_rcp_f32_e32 v148, v132
	v_add_f32_e32 v132, 1.0, v149
	v_mul_f32_e32 v149, 0xbfb8aa3b, v126
	v_exp_f32_e32 v150, v149
	v_mul_f32_e32 v149, 0xbfb8aa3b, v127
	v_exp_f32_e32 v151, v149
	v_rcp_f32_e32 v149, v132
	v_add_f32_e32 v132, 1.0, v150
	v_rcp_f32_e32 v150, v132
	v_add_f32_e32 v132, 1.0, v151
	v_rcp_f32_e32 v151, v132
	v_pk_mul_f32 v[124:125], v[124:125], v[148:149]
	v_mad_i64_i32 v[152:153], s[12:13], v147, s37, v[140:141]
	v_pk_mul_f32 v[120:121], v[124:125], v[120:121]
	v_pk_mul_f32 v[124:125], v[126:127], v[150:151]
	v_cvt_pk_bf16_f32 v120, v120, v121
	v_mul_f32_e32 v121, 0xbfb8aa3b, v116
	v_pk_mul_f32 v[122:123], v[124:125], v[122:123]
	v_exp_f32_e32 v124, v121
	v_mul_f32_e32 v121, 0xbfb8aa3b, v117
	v_exp_f32_e32 v125, v121
	v_cvt_pk_bf16_f32 v121, v122, v123
	v_add_f32_e32 v122, 1.0, v124
	v_mul_f32_e32 v124, 0xbfb8aa3b, v118
	v_add_f32_e32 v123, 1.0, v125
	v_mul_f32_e32 v125, 0xbfb8aa3b, v119
	v_exp_f32_e32 v124, v124
	v_exp_f32_e32 v125, v125
	v_rcp_f32_e32 v122, v122
	v_rcp_f32_e32 v123, v123
	v_add_f32_e32 v124, 1.0, v124
	v_add_f32_e32 v125, 1.0, v125
	v_rcp_f32_e32 v124, v124
	v_rcp_f32_e32 v125, v125
	v_pk_mul_f32 v[116:117], v[116:117], v[122:123]
	s_and_b64 vcc, exec, s[4:5]
	v_pk_mul_f32 v[112:113], v[116:117], v[112:113]
	v_pk_mul_f32 v[116:117], v[118:119], v[124:125]
	v_cvt_pk_bf16_f32 v112, v112, v113
	v_pk_mul_f32 v[114:115], v[116:117], v[114:115]
	v_or_b32_e32 v116, 16, v147
	v_cvt_pk_bf16_f32 v113, v114, v115
	global_store_dwordx2 v[152:153], v[112:113], off offset:32
	v_mul_f32_e32 v112, 0xbfb8aa3b, v108
	v_mul_f32_e32 v113, 0xbfb8aa3b, v109
	v_exp_f32_e32 v112, v112
	v_exp_f32_e32 v113, v113
	v_mul_f32_e32 v114, 0xbfb8aa3b, v110
	v_mul_f32_e32 v115, 0xbfb8aa3b, v111
	v_exp_f32_e32 v114, v114
	v_exp_f32_e32 v115, v115
	v_add_f32_e32 v112, 1.0, v112
	v_add_f32_e32 v113, 1.0, v113
	v_rcp_f32_e32 v112, v112
	v_rcp_f32_e32 v113, v113
	v_add_f32_e32 v114, 1.0, v114
	v_add_f32_e32 v115, 1.0, v115
	v_rcp_f32_e32 v114, v114
	v_rcp_f32_e32 v115, v115
	v_pk_mul_f32 v[108:109], v[108:109], v[112:113]
	v_mad_i64_i32 v[116:117], s[12:13], v116, s37, v[140:141]
; DI float silu_f(float g) { return g * __builtin_amdgcn_rcpf(1.f + __builtin_amdgcn_exp2f(-LOG2E * g)); }
; DI void epi_swiglu(const Acc& acc, int brow, int pn, bf16_t* hid) {
;     EPI_IDX
; #pragma unroll
;     for (int ai = 0; ai < 2; ++ai)
; #pragma unroll
;         for (int m = 0; m < 4; ++m) {
;             const int r = brow + ai * 128 + wr * 64 + m * 16 + fr;
;             bf16_t* rp = hid + (size_t)r * FF + pn * 128 + wc * 32 + fq * 4;
; #pragma unroll
;             for (int n = 0; n < 2; ++n) {
;                 const f32x4 g = acc[ai][0][m][n], u = acc[ai][1][m][n];
;                 float o[4];
; #pragma unroll
;                 for (int j = 0; j < 4; ++j) o[j] = silu_f(g[j]) * u[j];
;                 st4(rp + n * 16, o[0], o[1], o[2], o[3]);
;             }
;         }
	v_pk_mul_f32 v[104:105], v[108:109], v[104:105]
	v_pk_mul_f32 v[108:109], v[110:111], v[114:115]
	v_cvt_pk_bf16_f32 v104, v104, v105
	v_mul_f32_e32 v105, 0xbfb8aa3b, v100
	v_pk_mul_f32 v[106:107], v[108:109], v[106:107]
	v_exp_f32_e32 v108, v105
	v_mul_f32_e32 v105, 0xbfb8aa3b, v101
	v_exp_f32_e32 v109, v105
	v_cvt_pk_bf16_f32 v105, v106, v107
	v_add_f32_e32 v106, 1.0, v108
	v_mul_f32_e32 v108, 0xbfb8aa3b, v102
	v_add_f32_e32 v107, 1.0, v109
	v_mul_f32_e32 v109, 0xbfb8aa3b, v103
	v_exp_f32_e32 v108, v108
	v_exp_f32_e32 v109, v109
	v_rcp_f32_e32 v106, v106
	v_rcp_f32_e32 v107, v107
	v_add_f32_e32 v108, 1.0, v108
	v_add_f32_e32 v109, 1.0, v109
	v_rcp_f32_e32 v108, v108
	v_rcp_f32_e32 v109, v109
	v_pk_mul_f32 v[100:101], v[100:101], v[106:107]
	s_mov_b32 s54, s49
	v_pk_mul_f32 v[96:97], v[100:101], v[96:97]
	v_pk_mul_f32 v[100:101], v[102:103], v[108:109]
	v_cvt_pk_bf16_f32 v96, v96, v97
	v_pk_mul_f32 v[98:99], v[100:101], v[98:99]
	v_or_b32_e32 v100, 32, v147
	v_cvt_pk_bf16_f32 v97, v98, v99
	global_store_dwordx2 v[116:117], v[96:97], off offset:32
	v_mul_f32_e32 v96, 0xbfb8aa3b, v92
	v_mul_f32_e32 v97, 0xbfb8aa3b, v93
	v_exp_f32_e32 v96, v96
	v_exp_f32_e32 v97, v97
	v_mul_f32_e32 v98, 0xbfb8aa3b, v94
	v_mul_f32_e32 v99, 0xbfb8aa3b, v95
	v_exp_f32_e32 v98, v98
	v_exp_f32_e32 v99, v99
	v_add_f32_e32 v96, 1.0, v96
	v_add_f32_e32 v97, 1.0, v97
	v_rcp_f32_e32 v96, v96
	v_rcp_f32_e32 v97, v97
	v_add_f32_e32 v98, 1.0, v98
	v_add_f32_e32 v99, 1.0, v99
	v_rcp_f32_e32 v98, v98
	v_rcp_f32_e32 v99, v99
	v_pk_mul_f32 v[92:93], v[92:93], v[96:97]
	v_mad_i64_i32 v[100:101], s[12:13], v100, s37, v[140:141]
	v_pk_mul_f32 v[88:89], v[92:93], v[88:89]
	v_pk_mul_f32 v[92:93], v[94:95], v[98:99]
	v_cvt_pk_bf16_f32 v88, v88, v89
	v_mul_f32_e32 v89, 0xbfb8aa3b, v84
	v_pk_mul_f32 v[90:91], v[92:93], v[90:91]
	v_exp_f32_e32 v92, v89
	v_mul_f32_e32 v89, 0xbfb8aa3b, v85
	v_exp_f32_e32 v93, v89
	v_cvt_pk_bf16_f32 v89, v90, v91
	v_add_f32_e32 v90, 1.0, v92
	v_mul_f32_e32 v92, 0xbfb8aa3b, v86
	v_add_f32_e32 v91, 1.0, v93
	v_mul_f32_e32 v93, 0xbfb8aa3b, v87
	v_exp_f32_e32 v92, v92
	v_exp_f32_e32 v93, v93
	v_rcp_f32_e32 v90, v90
	v_rcp_f32_e32 v91, v91
	v_add_f32_e32 v92, 1.0, v92
	v_add_f32_e32 v93, 1.0, v93
	v_rcp_f32_e32 v92, v92
	v_rcp_f32_e32 v93, v93
	v_pk_mul_f32 v[84:85], v[84:85], v[90:91]
	s_mov_b32 s53, s52
	v_pk_mul_f32 v[80:81], v[84:85], v[80:81]
	v_pk_mul_f32 v[84:85], v[86:87], v[92:93]
	v_cvt_pk_bf16_f32 v80, v80, v81
	v_pk_mul_f32 v[82:83], v[84:85], v[82:83]
	v_or_b32_e32 v84, 48, v147
	v_cvt_pk_bf16_f32 v81, v82, v83
	global_store_dwordx2 v[100:101], v[80:81], off offset:32
	v_mul_f32_e32 v80, 0xbfb8aa3b, v76
	v_mul_f32_e32 v81, 0xbfb8aa3b, v77
	v_exp_f32_e32 v80, v80
	v_exp_f32_e32 v81, v81
	v_mul_f32_e32 v82, 0xbfb8aa3b, v78
	v_mul_f32_e32 v83, 0xbfb8aa3b, v79
	v_exp_f32_e32 v82, v82
	v_exp_f32_e32 v83, v83
	v_add_f32_e32 v80, 1.0, v80
	v_add_f32_e32 v81, 1.0, v81
	v_rcp_f32_e32 v80, v80
	v_rcp_f32_e32 v81, v81
	v_add_f32_e32 v82, 1.0, v82
	v_add_f32_e32 v83, 1.0, v83
	v_rcp_f32_e32 v82, v82
	v_rcp_f32_e32 v83, v83
	v_pk_mul_f32 v[76:77], v[76:77], v[80:81]
	v_mad_i64_i32 v[84:85], s[12:13], v84, s37, v[140:141]
	v_pk_mul_f32 v[72:73], v[76:77], v[72:73]
	v_pk_mul_f32 v[76:77], v[78:79], v[82:83]
	v_cvt_pk_bf16_f32 v72, v72, v73
	v_mul_f32_e32 v73, 0xbfb8aa3b, v68
	v_pk_mul_f32 v[74:75], v[76:77], v[74:75]
	v_exp_f32_e32 v76, v73
	v_mul_f32_e32 v73, 0xbfb8aa3b, v69
	v_exp_f32_e32 v77, v73
	v_cvt_pk_bf16_f32 v73, v74, v75
	v_add_f32_e32 v74, 1.0, v76
	v_mul_f32_e32 v76, 0xbfb8aa3b, v70
	v_add_f32_e32 v75, 1.0, v77
	v_mul_f32_e32 v77, 0xbfb8aa3b, v71
	v_exp_f32_e32 v76, v76
	v_exp_f32_e32 v77, v77
	v_rcp_f32_e32 v74, v74
	v_rcp_f32_e32 v75, v75
	v_add_f32_e32 v76, 1.0, v76
	v_add_f32_e32 v77, 1.0, v77
	v_rcp_f32_e32 v76, v76
	v_rcp_f32_e32 v77, v77
	v_pk_mul_f32 v[68:69], v[68:69], v[74:75]
	s_mov_b64 s[14:15], s[10:11]
	v_pk_mul_f32 v[64:65], v[68:69], v[64:65]
	v_pk_mul_f32 v[68:69], v[70:71], v[76:77]
	v_cvt_pk_bf16_f32 v64, v64, v65
	v_pk_mul_f32 v[66:67], v[68:69], v[66:67]
	v_add_u32_e32 v68, 0x80, v147
	v_cvt_pk_bf16_f32 v65, v66, v67
	global_store_dwordx2 v[84:85], v[64:65], off offset:32
	v_mul_f32_e32 v64, 0xbfb8aa3b, v60
	v_mul_f32_e32 v65, 0xbfb8aa3b, v61
	v_exp_f32_e32 v64, v64
	v_exp_f32_e32 v65, v65
	v_mul_f32_e32 v66, 0xbfb8aa3b, v62
	v_mul_f32_e32 v67, 0xbfb8aa3b, v63
	v_exp_f32_e32 v66, v66
	v_exp_f32_e32 v67, v67
	v_add_f32_e32 v64, 1.0, v64
	v_add_f32_e32 v65, 1.0, v65
	v_rcp_f32_e32 v64, v64
	v_rcp_f32_e32 v65, v65
	v_add_f32_e32 v66, 1.0, v66
	v_add_f32_e32 v67, 1.0, v67
	v_rcp_f32_e32 v66, v66
	v_rcp_f32_e32 v67, v67
	v_pk_mul_f32 v[60:61], v[60:61], v[64:65]
	v_mad_i64_i32 v[68:69], s[12:13], v68, s37, v[140:141]
	v_pk_mul_f32 v[56:57], v[60:61], v[56:57]
	v_pk_mul_f32 v[60:61], v[62:63], v[66:67]
	v_cvt_pk_bf16_f32 v56, v56, v57
	v_mul_f32_e32 v57, 0xbfb8aa3b, v52
	v_pk_mul_f32 v[58:59], v[60:61], v[58:59]
	v_exp_f32_e32 v60, v57
	v_mul_f32_e32 v57, 0xbfb8aa3b, v53
	v_exp_f32_e32 v61, v57
	v_cvt_pk_bf16_f32 v57, v58, v59
	v_add_f32_e32 v58, 1.0, v60
	v_mul_f32_e32 v60, 0xbfb8aa3b, v54
	v_add_f32_e32 v59, 1.0, v61
	v_mul_f32_e32 v61, 0xbfb8aa3b, v55
	v_exp_f32_e32 v60, v60
	v_exp_f32_e32 v61, v61
	v_rcp_f32_e32 v58, v58
	v_rcp_f32_e32 v59, v59
	v_add_f32_e32 v60, 1.0, v60
	v_add_f32_e32 v61, 1.0, v61
	v_rcp_f32_e32 v60, v60
; DI float silu_f(float g) { return g * __builtin_amdgcn_rcpf(1.f + __builtin_amdgcn_exp2f(-LOG2E * g)); }
; #define WAIT_V(n) asm volatile("s_waitcnt vmcnt(" #n ")" ::: "memory")
; #define BAR __builtin_amdgcn_s_barrier()
; template <class Get, class Epi>
; DI void gemm_stream(LAS unsigned char* lds, const int K, const int ld, Get get, Epi epi) {
;     ...
;         epi(acc, cur);
;         if (!has_next) break;
;         ZERO_ACC;
;         cur = nxt; cA = nA; cB = nB; ++ui;
;     }
;     WAIT_V(0);
;     if (wr == 0) BAR;
;     BAR;
; DI void epi_swiglu(const Acc& acc, int brow, int pn, bf16_t* hid) {
;     ...
;     for (int ai = 0; ai < 2; ++ai)
; #pragma unroll
;         for (int m = 0; m < 4; ++m) {
;             const int r = brow + ai * 128 + wr * 64 + m * 16 + fr;
;             bf16_t* rp = hid + (size_t)r * FF + pn * 128 + wc * 32 + fq * 4;
; #pragma unroll
;             for (int n = 0; n < 2; ++n) {
;                 const f32x4 g = acc[ai][0][m][n], u = acc[ai][1][m][n];
;                 float o[4];
; #pragma unroll
;                 for (int j = 0; j < 4; ++j) o[j] = silu_f(g[j]) * u[j];
;                 st4(rp + n * 16, o[0], o[1], o[2], o[3]);
;             }
;         }
	v_rcp_f32_e32 v61, v61
	v_pk_mul_f32 v[52:53], v[52:53], v[58:59]
	global_store_dwordx2 v[152:153], v[120:121], off
	v_pk_mul_f32 v[48:49], v[52:53], v[48:49]
	v_pk_mul_f32 v[52:53], v[54:55], v[60:61]
	v_cvt_pk_bf16_f32 v48, v48, v49
	v_pk_mul_f32 v[50:51], v[52:53], v[50:51]
	v_add_u32_e32 v52, 0x90, v147
	v_cvt_pk_bf16_f32 v49, v50, v51
	global_store_dwordx2 v[68:69], v[48:49], off offset:32
	v_mul_f32_e32 v48, 0xbfb8aa3b, v44
	v_mul_f32_e32 v49, 0xbfb8aa3b, v45
	v_exp_f32_e32 v48, v48
	v_exp_f32_e32 v49, v49
	v_mul_f32_e32 v50, 0xbfb8aa3b, v46
	v_mul_f32_e32 v51, 0xbfb8aa3b, v47
	v_exp_f32_e32 v50, v50
	v_exp_f32_e32 v51, v51
	v_add_f32_e32 v48, 1.0, v48
	v_add_f32_e32 v49, 1.0, v49
	v_rcp_f32_e32 v48, v48
	v_rcp_f32_e32 v49, v49
	v_add_f32_e32 v50, 1.0, v50
	v_add_f32_e32 v51, 1.0, v51
	v_rcp_f32_e32 v50, v50
	v_rcp_f32_e32 v51, v51
	v_pk_mul_f32 v[44:45], v[44:45], v[48:49]
	v_mad_i64_i32 v[52:53], s[12:13], v52, s37, v[140:141]
	v_pk_mul_f32 v[40:41], v[44:45], v[40:41]
	v_pk_mul_f32 v[44:45], v[46:47], v[50:51]
	v_cvt_pk_bf16_f32 v40, v40, v41
	v_mul_f32_e32 v41, 0xbfb8aa3b, v36
	v_pk_mul_f32 v[42:43], v[44:45], v[42:43]
	v_exp_f32_e32 v44, v41
	v_mul_f32_e32 v41, 0xbfb8aa3b, v37
	v_exp_f32_e32 v45, v41
	v_cvt_pk_bf16_f32 v41, v42, v43
	v_add_f32_e32 v42, 1.0, v44
	v_mul_f32_e32 v44, 0xbfb8aa3b, v38
	v_add_f32_e32 v43, 1.0, v45
	v_mul_f32_e32 v45, 0xbfb8aa3b, v39
	v_exp_f32_e32 v44, v44
	v_exp_f32_e32 v45, v45
	v_rcp_f32_e32 v42, v42
	v_rcp_f32_e32 v43, v43
	v_add_f32_e32 v44, 1.0, v44
	v_add_f32_e32 v45, 1.0, v45
	v_rcp_f32_e32 v44, v44
	v_rcp_f32_e32 v45, v45
	v_pk_mul_f32 v[36:37], v[36:37], v[42:43]
	global_store_dwordx2 v[116:117], v[104:105], off
	v_pk_mul_f32 v[32:33], v[36:37], v[32:33]
	v_pk_mul_f32 v[36:37], v[38:39], v[44:45]
	v_cvt_pk_bf16_f32 v32, v32, v33
	v_pk_mul_f32 v[34:35], v[36:37], v[34:35]
	v_add_u32_e32 v36, 0xa0, v147
	v_cvt_pk_bf16_f32 v33, v34, v35
	global_store_dwordx2 v[52:53], v[32:33], off offset:32
	v_mul_f32_e32 v32, 0xbfb8aa3b, v28
	v_mul_f32_e32 v33, 0xbfb8aa3b, v29
	v_exp_f32_e32 v32, v32
	v_exp_f32_e32 v33, v33
	v_mul_f32_e32 v34, 0xbfb8aa3b, v30
	v_mul_f32_e32 v35, 0xbfb8aa3b, v31
	v_exp_f32_e32 v34, v34
	v_exp_f32_e32 v35, v35
	v_add_f32_e32 v32, 1.0, v32
	v_add_f32_e32 v33, 1.0, v33
	v_rcp_f32_e32 v32, v32
	v_rcp_f32_e32 v33, v33
	v_add_f32_e32 v34, 1.0, v34
	v_add_f32_e32 v35, 1.0, v35
	v_rcp_f32_e32 v34, v34
	v_rcp_f32_e32 v35, v35
	v_pk_mul_f32 v[28:29], v[28:29], v[32:33]
	v_mad_i64_i32 v[36:37], s[12:13], v36, s37, v[140:141]
	v_pk_mul_f32 v[24:25], v[28:29], v[24:25]
	v_pk_mul_f32 v[28:29], v[30:31], v[34:35]
	v_cvt_pk_bf16_f32 v24, v24, v25
	v_mul_f32_e32 v25, 0xbfb8aa3b, v20
	v_pk_mul_f32 v[26:27], v[28:29], v[26:27]
	v_exp_f32_e32 v28, v25
	v_mul_f32_e32 v25, 0xbfb8aa3b, v21
	v_exp_f32_e32 v29, v25
	v_cvt_pk_bf16_f32 v25, v26, v27
	v_add_f32_e32 v26, 1.0, v28
	v_mul_f32_e32 v28, 0xbfb8aa3b, v22
	v_add_f32_e32 v27, 1.0, v29
	v_mul_f32_e32 v29, 0xbfb8aa3b, v23
	v_exp_f32_e32 v28, v28
	v_exp_f32_e32 v29, v29
	v_rcp_f32_e32 v26, v26
	v_rcp_f32_e32 v27, v27
	v_add_f32_e32 v28, 1.0, v28
	v_add_f32_e32 v29, 1.0, v29
	v_rcp_f32_e32 v28, v28
	v_rcp_f32_e32 v29, v29
	v_pk_mul_f32 v[20:21], v[20:21], v[26:27]
	global_store_dwordx2 v[100:101], v[88:89], off
	v_pk_mul_f32 v[16:17], v[20:21], v[16:17]
	v_pk_mul_f32 v[20:21], v[22:23], v[28:29]
	v_cvt_pk_bf16_f32 v16, v16, v17
	v_pk_mul_f32 v[18:19], v[20:21], v[18:19]
	v_add_u32_e32 v20, 0xb0, v147
	v_cvt_pk_bf16_f32 v17, v18, v19
	global_store_dwordx2 v[36:37], v[16:17], off offset:32
	v_mul_f32_e32 v16, 0xbfb8aa3b, v12
	v_mul_f32_e32 v17, 0xbfb8aa3b, v13
	v_exp_f32_e32 v16, v16
	v_exp_f32_e32 v17, v17
	v_mul_f32_e32 v18, 0xbfb8aa3b, v14
	v_mul_f32_e32 v19, 0xbfb8aa3b, v15
	v_exp_f32_e32 v18, v18
	v_exp_f32_e32 v19, v19
	v_add_f32_e32 v16, 1.0, v16
	v_add_f32_e32 v17, 1.0, v17
	v_rcp_f32_e32 v16, v16
	v_rcp_f32_e32 v17, v17
	v_add_f32_e32 v18, 1.0, v18
	v_add_f32_e32 v19, 1.0, v19
	v_rcp_f32_e32 v18, v18
	v_rcp_f32_e32 v19, v19
	v_pk_mul_f32 v[12:13], v[12:13], v[16:17]
	v_mad_i64_i32 v[20:21], s[12:13], v20, s37, v[140:141]
	v_pk_mul_f32 v[8:9], v[12:13], v[8:9]
	v_pk_mul_f32 v[12:13], v[14:15], v[18:19]
	v_cvt_pk_bf16_f32 v8, v8, v9
	v_mul_f32_e32 v9, 0xbfb8aa3b, v4
	v_pk_mul_f32 v[10:11], v[12:13], v[10:11]
	v_exp_f32_e32 v12, v9
	v_mul_f32_e32 v9, 0xbfb8aa3b, v5
	v_exp_f32_e32 v13, v9
	v_cvt_pk_bf16_f32 v9, v10, v11
	v_add_f32_e32 v10, 1.0, v12
	v_mul_f32_e32 v12, 0xbfb8aa3b, v6
	v_add_f32_e32 v11, 1.0, v13
	v_mul_f32_e32 v13, 0xbfb8aa3b, v7
	v_exp_f32_e32 v12, v12
	v_exp_f32_e32 v13, v13
	v_rcp_f32_e32 v10, v10
	v_rcp_f32_e32 v11, v11
	v_add_f32_e32 v12, 1.0, v12
	v_add_f32_e32 v13, 1.0, v13
	v_rcp_f32_e32 v12, v12
	v_rcp_f32_e32 v13, v13
	v_pk_mul_f32 v[4:5], v[4:5], v[10:11]
	s_mov_b64 s[12:13], s[8:9]
	v_pk_mul_f32 v[0:1], v[4:5], v[0:1]
	v_pk_mul_f32 v[4:5], v[6:7], v[12:13]
	v_cvt_pk_bf16_f32 v0, v0, v1
	v_pk_mul_f32 v[2:3], v[4:5], v[2:3]
	global_store_dwordx2 v[84:85], v[72:73], off
	v_cvt_pk_bf16_f32 v1, v2, v3
	global_store_dwordx2 v[68:69], v[56:57], off
	global_store_dwordx2 v[52:53], v[40:41], off
	global_store_dwordx2 v[36:37], v[24:25], off
	global_store_dwordx2 v[20:21], v[8:9], off
	global_store_dwordx2 v[20:21], v[0:1], off offset:32
	s_cbranch_vccz .LBB0_3043
	s_waitcnt vmcnt(0)
	s_cmpk_gt_u32 s2, 0xff
	s_cbranch_scc1 .LBB0_3050
	s_barrier

; #define WAIT_V(n) asm volatile("s_waitcnt vmcnt(" #n ")" ::: "memory")
; #define WAIT_L(n) asm volatile("s_waitcnt lgkmcnt(" #n ")" ::: "memory")
; #define BAR __builtin_amdgcn_s_barrier()
; #define SCHED __builtin_amdgcn_sched_barrier(0)
; template <class Get, class Epi>
; DI void gemm_stream(LAS unsigned char* lds, const int K, const int ld, Get get, Epi epi) {
;     ...
;             const bool last = (t == nt - 2);
;             const char* a1 = cA + (size_t)(t + 1) * kstep;
;             const char* a2 = last ? nA : cA + (size_t)(t + 2) * kstep;
;             const char* b2 = last ? nB : cB + (size_t)(t + 2) * kstep;
;             const char* a3 = a2 + kstep;
;             const char* b3 = b2 + kstep;
;             LDB(B0, 0, 0); SCHED; LDA(At, 0, 0); STAGE(SAo(1, 1), a1 + hstep);
;             WAIT_L(8); BAR; WAIT_L(0); MMA(0, 0, At, B0); BAR; SCHED;
;             LDB(B1, 0, 1); STAGE(SBo(0, 0), b2);
;             BAR; WAIT_L(0); MMA(0, 1, At, B1); BAR;
;             LDA(At, 0, 1); STAGE(SAo(0, 0), a2);
;             BAR; WAIT_L(0); MMA(1, 0, At, B0); BAR; SCHED;
;             STAGE(SBo(0, 1), b2 + hstep);
;             WAIT_V(6); BAR; MMA(1, 1, At, B1); BAR;
;             LDB(B0, 1, 0); SCHED; LDA(At, 1, 0); STAGE(SAo(0, 1), a2 + hstep);
;             WAIT_L(8); BAR; WAIT_L(0); MMA(0, 0, At, B0); BAR; SCHED;
;             LDB(B1, 1, 1); STAGE(SBo(1, 0), b3);
;             BAR; WAIT_L(0); MMA(0, 1, At, B1); BAR;
.LBB0_3113:
	ds_read_b128 v[128:131], v199
	ds_read_b128 v[132:135], v199 offset:1024
	ds_read_b128 v[136:139], v199 offset:2048
	ds_read_b128 v[140:143], v199 offset:3072
	s_add_u32 s6, s4, 0x100
	s_addc_u32 s7, s5, 0
	s_cmpk_eq_i32 s16, 0x54
	s_cselect_b32 s11, s37, s7
	s_cselect_b32 s10, s36, s6
	s_cselect_b32 s9, s39, s15
	s_cselect_b32 s8, s38, s14
	s_mov_b32 m0, s54
	ds_read_b128 v[144:147], v200
	ds_read_b128 v[148:151], v200 offset:1024
	ds_read_b128 v[152:155], v200 offset:2048
	ds_read_b128 v[156:159], v200 offset:3072
	ds_read_b128 v[160:163], v200 offset:4096
	ds_read_b128 v[174:177], v200 offset:5120
	ds_read_b128 v[178:181], v200 offset:6144
	ds_read_b128 v[182:185], v200 offset:7168
	global_load_lds_dwordx4 v168, s[4:5]
	s_mov_b32 m0, s55
	s_nop 0
	global_load_lds_dwordx4 v170, s[4:5]
	s_waitcnt lgkmcnt(8)
	s_barrier
	s_waitcnt lgkmcnt(0)
	v_mfma_f32_16x16x32_bf16 v[124:127], v[128:131], v[144:147], v[124:127]
	v_mfma_f32_16x16x32_bf16 v[92:95], v[136:139], v[144:147], v[92:95]
	v_mfma_f32_16x16x32_bf16 v[120:123], v[128:131], v[152:155], v[120:123]
	v_mfma_f32_16x16x32_bf16 v[88:91], v[136:139], v[152:155], v[88:91]
	v_mfma_f32_16x16x32_bf16 v[116:119], v[128:131], v[160:163], v[116:119]
	v_mfma_f32_16x16x32_bf16 v[84:87], v[136:139], v[160:163], v[84:87]
	v_mfma_f32_16x16x32_bf16 v[112:115], v[128:131], v[178:181], v[112:115]
	v_mfma_f32_16x16x32_bf16 v[80:83], v[136:139], v[178:181], v[80:83]
	v_mfma_f32_16x16x32_bf16 v[124:127], v[132:135], v[148:151], v[124:127]
	v_mfma_f32_16x16x32_bf16 v[92:95], v[140:143], v[148:151], v[92:95]
	v_mfma_f32_16x16x32_bf16 v[120:123], v[132:135], v[156:159], v[120:123]
	v_mfma_f32_16x16x32_bf16 v[88:91], v[140:143], v[156:159], v[88:91]
	v_mfma_f32_16x16x32_bf16 v[116:119], v[132:135], v[174:177], v[116:119]
	v_mfma_f32_16x16x32_bf16 v[84:87], v[140:143], v[174:177], v[84:87]
	v_mfma_f32_16x16x32_bf16 v[112:115], v[132:135], v[182:185], v[112:115]
	v_mfma_f32_16x16x32_bf16 v[80:83], v[140:143], v[182:185], v[80:83]
	s_barrier
	s_mov_b32 m0, s56
	v_lshl_add_u64 v[208:209], s[8:9], 0, v[164:165]
	ds_read_b128 v[186:189], v201
	ds_read_b128 v[190:193], v201 offset:1024
	ds_read_b128 v[194:197], v201 offset:2048
	ds_read_b128 v[202:205], v201 offset:3072
	global_load_lds_dwordx4 v[208:209], off
	v_lshl_add_u64 v[210:211], s[8:9], 0, v[166:167]
	s_mov_b32 m0, s57
	s_nop 0
	global_load_lds_dwordx4 v[210:211], off
	s_barrier
	s_waitcnt lgkmcnt(0)
	v_mfma_f32_16x16x32_bf16 v[60:63], v[186:189], v[144:147], v[60:63]
	v_mfma_f32_16x16x32_bf16 v[28:31], v[194:197], v[144:147], v[28:31]
	v_mfma_f32_16x16x32_bf16 v[56:59], v[186:189], v[152:155], v[56:59]
	v_mfma_f32_16x16x32_bf16 v[24:27], v[194:197], v[152:155], v[24:27]
	v_mfma_f32_16x16x32_bf16 v[52:55], v[186:189], v[160:163], v[52:55]
	v_mfma_f32_16x16x32_bf16 v[20:23], v[194:197], v[160:163], v[20:23]
	v_mfma_f32_16x16x32_bf16 v[48:51], v[186:189], v[178:181], v[48:51]
	v_mfma_f32_16x16x32_bf16 v[16:19], v[194:197], v[178:181], v[16:19]
	v_mfma_f32_16x16x32_bf16 v[60:63], v[190:193], v[148:151], v[60:63]
	v_mfma_f32_16x16x32_bf16 v[28:31], v[202:205], v[148:151], v[28:31]
	v_mfma_f32_16x16x32_bf16 v[56:59], v[190:193], v[156:159], v[56:59]
	v_mfma_f32_16x16x32_bf16 v[24:27], v[202:205], v[156:159], v[24:27]
	v_mfma_f32_16x16x32_bf16 v[52:55], v[190:193], v[174:177], v[52:55]
	v_mfma_f32_16x16x32_bf16 v[20:23], v[202:205], v[174:177], v[20:23]
	v_mfma_f32_16x16x32_bf16 v[48:51], v[190:193], v[182:185], v[48:51]
	v_mfma_f32_16x16x32_bf16 v[16:19], v[202:205], v[182:185], v[16:19]
	s_barrier
	s_mov_b32 m0, s33
	v_lshl_add_u64 v[212:213], s[10:11], 0, v[164:165]
	ds_read_b128 v[144:147], v200 offset:16384
	ds_read_b128 v[148:151], v200 offset:17408
	ds_read_b128 v[152:155], v200 offset:18432
	ds_read_b128 v[156:159], v200 offset:19456
	ds_read_b128 v[160:163], v200 offset:20480
	ds_read_b128 v[174:177], v200 offset:21504
	ds_read_b128 v[178:181], v200 offset:22528
	ds_read_b128 v[182:185], v200 offset:23552
	global_load_lds_dwordx4 v[212:213], off
	v_lshl_add_u64 v[214:215], s[10:11], 0, v[166:167]
	s_mov_b32 m0, s42
	s_nop 0
	global_load_lds_dwordx4 v[214:215], off
	s_barrier
	s_waitcnt lgkmcnt(0)
	v_mfma_f32_16x16x32_bf16 v[108:111], v[128:131], v[144:147], v[108:111]
	v_mfma_f32_16x16x32_bf16 v[76:79], v[136:139], v[144:147], v[76:79]
	v_mfma_f32_16x16x32_bf16 v[104:107], v[128:131], v[152:155], v[104:107]
	v_mfma_f32_16x16x32_bf16 v[72:75], v[136:139], v[152:155], v[72:75]
	v_mfma_f32_16x16x32_bf16 v[100:103], v[128:131], v[160:163], v[100:103]
	v_mfma_f32_16x16x32_bf16 v[68:71], v[136:139], v[160:163], v[68:71]
	v_mfma_f32_16x16x32_bf16 v[96:99], v[128:131], v[178:181], v[96:99]
	v_mfma_f32_16x16x32_bf16 v[64:67], v[136:139], v[178:181], v[64:67]
	v_mfma_f32_16x16x32_bf16 v[108:111], v[132:135], v[148:151], v[108:111]
	v_mfma_f32_16x16x32_bf16 v[76:79], v[140:143], v[148:151], v[76:79]
	v_mfma_f32_16x16x32_bf16 v[104:107], v[132:135], v[156:159], v[104:107]
	v_mfma_f32_16x16x32_bf16 v[72:75], v[140:143], v[156:159], v[72:75]
	v_mfma_f32_16x16x32_bf16 v[100:103], v[132:135], v[174:177], v[100:103]
	v_mfma_f32_16x16x32_bf16 v[68:71], v[140:143], v[174:177], v[68:71]
	v_mfma_f32_16x16x32_bf16 v[96:99], v[132:135], v[182:185], v[96:99]
	v_mfma_f32_16x16x32_bf16 v[64:67], v[140:143], v[182:185], v[64:67]
	s_barrier
	s_add_u32 s4, s8, 0x160000
	s_addc_u32 s5, s9, 0
	s_mov_b32 m0, s58
	v_lshl_add_u64 v[128:129], s[4:5], 0, v[164:165]
	global_load_lds_dwordx4 v[128:129], off
	s_mov_b32 m0, s59
	s_nop 0
	global_load_lds_dwordx4 v166, s[4:5]
	s_waitcnt vmcnt(6)
	s_barrier
; #define WAIT_L(n) asm volatile("s_waitcnt lgkmcnt(" #n ")" ::: "memory")
; #define BAR __builtin_amdgcn_s_barrier()
; #define SCHED __builtin_amdgcn_sched_barrier(0)
; template <class Get, class Epi>
; DI void gemm_stream(LAS unsigned char* lds, const int K, const int ld, Get get, Epi epi) {
;     ...
;             LDB(B0, 1, 0); SCHED; LDA(At, 1, 0); STAGE(SAo(0, 1), a2 + hstep);
;             WAIT_L(8); BAR; WAIT_L(0); MMA(0, 0, At, B0); BAR; SCHED;
;             LDB(B1, 1, 1); STAGE(SBo(1, 0), b3);
;             BAR; WAIT_L(0); MMA(0, 1, At, B1); BAR;
;             LDA(At, 1, 1); STAGE(SAo(1, 0), a3);
;             BAR; WAIT_L(0); MMA(1, 0, At, B0); BAR; SCHED;
	v_mfma_f32_16x16x32_bf16 v[44:47], v[186:189], v[144:147], v[44:47]
	v_mfma_f32_16x16x32_bf16 v[12:15], v[194:197], v[144:147], v[12:15]
	v_mfma_f32_16x16x32_bf16 v[40:43], v[186:189], v[152:155], v[40:43]
	v_mfma_f32_16x16x32_bf16 v[8:11], v[194:197], v[152:155], v[8:11]
	v_mfma_f32_16x16x32_bf16 v[36:39], v[186:189], v[160:163], v[36:39]
	v_mfma_f32_16x16x32_bf16 v[4:7], v[194:197], v[160:163], v[4:7]
	v_mfma_f32_16x16x32_bf16 v[32:35], v[186:189], v[178:181], v[32:35]
	v_mfma_f32_16x16x32_bf16 v[0:3], v[194:197], v[178:181], v[0:3]
	v_mfma_f32_16x16x32_bf16 v[44:47], v[190:193], v[148:151], v[44:47]
	v_mfma_f32_16x16x32_bf16 v[12:15], v[202:205], v[148:151], v[12:15]
	v_mfma_f32_16x16x32_bf16 v[40:43], v[190:193], v[156:159], v[40:43]
	v_mfma_f32_16x16x32_bf16 v[8:11], v[202:205], v[156:159], v[8:11]
	v_mfma_f32_16x16x32_bf16 v[36:39], v[190:193], v[174:177], v[36:39]
	v_mfma_f32_16x16x32_bf16 v[4:7], v[202:205], v[174:177], v[4:7]
	v_mfma_f32_16x16x32_bf16 v[32:35], v[190:193], v[182:185], v[32:35]
	v_mfma_f32_16x16x32_bf16 v[0:3], v[202:205], v[182:185], v[0:3]
	s_add_i32 s17, 16, 0x18000
	v_add_u32_e32 v140, s17, v198
	s_barrier
	ds_read_b128 v[128:131], v140
	ds_read_b128 v[132:135], v140 offset:1024
	ds_read_b128 v[136:139], v140 offset:2048
	ds_read_b128 v[140:143], v140 offset:3072
	s_add_u32 s4, s10, 0x160000
	s_addc_u32 s5, s11, 0
	s_mov_b32 m0, s43
	ds_read_b128 v[144:147], v200 offset:32768
	ds_read_b128 v[148:151], v200 offset:33792
	ds_read_b128 v[152:155], v200 offset:34816
	ds_read_b128 v[156:159], v200 offset:35840
	ds_read_b128 v[160:163], v200 offset:36864
	ds_read_b128 v[174:177], v200 offset:37888
	ds_read_b128 v[178:181], v200 offset:38912
	ds_read_b128 v[182:185], v200 offset:39936
	global_load_lds_dwordx4 v164, s[4:5]
	s_mov_b32 m0, s44
	s_nop 0
	global_load_lds_dwordx4 v166, s[4:5]
	s_waitcnt lgkmcnt(8)
	s_barrier
	s_waitcnt lgkmcnt(0)
	v_mfma_f32_16x16x32_bf16 v[124:127], v[128:131], v[144:147], v[124:127]
	v_mfma_f32_16x16x32_bf16 v[92:95], v[136:139], v[144:147], v[92:95]
	v_mfma_f32_16x16x32_bf16 v[120:123], v[128:131], v[152:155], v[120:123]
	v_mfma_f32_16x16x32_bf16 v[88:91], v[136:139], v[152:155], v[88:91]
	v_mfma_f32_16x16x32_bf16 v[116:119], v[128:131], v[160:163], v[116:119]
	v_mfma_f32_16x16x32_bf16 v[84:87], v[136:139], v[160:163], v[84:87]
	v_mfma_f32_16x16x32_bf16 v[112:115], v[128:131], v[178:181], v[112:115]
	v_mfma_f32_16x16x32_bf16 v[80:83], v[136:139], v[178:181], v[80:83]
	v_mfma_f32_16x16x32_bf16 v[124:127], v[132:135], v[148:151], v[124:127]
	v_mfma_f32_16x16x32_bf16 v[92:95], v[140:143], v[148:151], v[92:95]
	v_mfma_f32_16x16x32_bf16 v[120:123], v[132:135], v[156:159], v[120:123]
	v_mfma_f32_16x16x32_bf16 v[88:91], v[140:143], v[156:159], v[88:91]
	v_mfma_f32_16x16x32_bf16 v[116:119], v[132:135], v[174:177], v[116:119]
	v_mfma_f32_16x16x32_bf16 v[84:87], v[140:143], v[174:177], v[84:87]
	v_mfma_f32_16x16x32_bf16 v[112:115], v[132:135], v[182:185], v[112:115]
	v_mfma_f32_16x16x32_bf16 v[80:83], v[140:143], v[182:185], v[80:83]
	s_barrier
	s_add_i32 s10, 16, 0x1c000
	s_add_i32 s4, s17, s21
	v_add_u32_e32 v202, s10, v198
	v_lshl_add_u64 v[208:209], v[208:209], 0, s[0:1]
	s_mov_b32 m0, s4
	ds_read_b128 v[186:189], v202
	ds_read_b128 v[190:193], v202 offset:1024
	ds_read_b128 v[194:197], v202 offset:2048
	ds_read_b128 v[202:205], v202 offset:3072
	global_load_lds_dwordx4 v[208:209], off
	v_lshl_add_u64 v[208:209], v[210:211], 0, s[0:1]
	s_add_i32 m0, s4, 0x2000
	s_nop 0
	global_load_lds_dwordx4 v[208:209], off
	s_barrier
	s_waitcnt lgkmcnt(0)
	v_mfma_f32_16x16x32_bf16 v[60:63], v[186:189], v[144:147], v[60:63]
	v_mfma_f32_16x16x32_bf16 v[28:31], v[194:197], v[144:147], v[28:31]
	v_mfma_f32_16x16x32_bf16 v[56:59], v[186:189], v[152:155], v[56:59]
	v_mfma_f32_16x16x32_bf16 v[24:27], v[194:197], v[152:155], v[24:27]
	v_mfma_f32_16x16x32_bf16 v[52:55], v[186:189], v[160:163], v[52:55]
	v_mfma_f32_16x16x32_bf16 v[20:23], v[194:197], v[160:163], v[20:23]
	v_mfma_f32_16x16x32_bf16 v[48:51], v[186:189], v[178:181], v[48:51]
	v_mfma_f32_16x16x32_bf16 v[16:19], v[194:197], v[178:181], v[16:19]
	v_mfma_f32_16x16x32_bf16 v[60:63], v[190:193], v[148:151], v[60:63]
	v_mfma_f32_16x16x32_bf16 v[28:31], v[202:205], v[148:151], v[28:31]
	v_mfma_f32_16x16x32_bf16 v[56:59], v[190:193], v[156:159], v[56:59]
	v_mfma_f32_16x16x32_bf16 v[24:27], v[202:205], v[156:159], v[24:27]
	v_mfma_f32_16x16x32_bf16 v[52:55], v[190:193], v[174:177], v[52:55]
	v_mfma_f32_16x16x32_bf16 v[20:23], v[202:205], v[174:177], v[20:23]
	v_mfma_f32_16x16x32_bf16 v[48:51], v[190:193], v[182:185], v[48:51]
	v_mfma_f32_16x16x32_bf16 v[16:19], v[202:205], v[182:185], v[16:19]
	s_barrier
	s_mov_b32 m0, s45
	v_lshl_add_u64 v[208:209], v[212:213], 0, s[0:1]
	ds_read_b128 v[144:147], v200 offset:49152
	ds_read_b128 v[148:151], v200 offset:50176
	ds_read_b128 v[152:155], v200 offset:51200
	ds_read_b128 v[156:159], v200 offset:52224
	ds_read_b128 v[160:163], v200 offset:53248
	ds_read_b128 v[174:177], v200 offset:54272
	ds_read_b128 v[178:181], v200 offset:55296
	ds_read_b128 v[182:185], v200 offset:56320
	global_load_lds_dwordx4 v[208:209], off
	v_lshl_add_u64 v[208:209], v[214:215], 0, s[0:1]
	s_mov_b32 m0, s46
	s_nop 0
	global_load_lds_dwordx4 v[208:209], off
	s_barrier
; #define WAIT_V(n) asm volatile("s_waitcnt vmcnt(" #n ")" ::: "memory")
; #define WAIT_L(n) asm volatile("s_waitcnt lgkmcnt(" #n ")" ::: "memory")
; #define BAR __builtin_amdgcn_s_barrier()
; #define SCHED __builtin_amdgcn_sched_barrier(0)
; template <class Get, class Epi>
; DI void gemm_stream(LAS unsigned char* lds, const int K, const int ld, Get get, Epi epi) {
;     ...
;             LDA(At, 1, 1); STAGE(SAo(1, 0), a3);
;             BAR; WAIT_L(0); MMA(1, 0, At, B0); BAR; SCHED;
;             STAGE(SBo(1, 1), b3 + hstep);
;             WAIT_V(6); BAR; MMA(1, 1, At, B1); BAR;
; DI void epi_resid(const Acc& acc, const P& p, int brow, int bcol, int layer, int gch, bool from_input) {
;     EPI_IDX
;     const float* gate = modv(p, layer, brow, gch);
; #pragma unroll
;     for (int bj = 0; bj < 2; ++bj)
; #pragma unroll
;         for (int n = 0; n < 2; ++n) {
;             const int c0 = bcol + bj * 128 + wc * 32 + n * 16 + fq * 4;
;             const f32x4 g = *(const f32x4*)(gate + c0);
;             f32x4 xv[2][4];
; #pragma unroll
;             for (int ai = 0; ai < 2; ++ai)
; #pragma unroll
;                 for (int m = 0; m < 4; ++m) {
;                     const int r = brow + ai * 128 + wr * 64 + m * 16 + fr;
;                     const float* sp = (from_input ? inrow(p, r) : xrow(p, r)) + c0;
;                     xv[ai][m] = *(const f32x4*)sp;
;                 }
;             __builtin_amdgcn_sched_barrier(0);
; #pragma unroll
;             for (int ai = 0; ai < 2; ++ai)
; #pragma unroll
;                 for (int m = 0; m < 4; ++m) {
;                     const int r = brow + ai * 128 + wr * 64 + m * 16 + fr;
;                     *(f32x4*)(xrow(p, r) + c0) = xv[ai][m] + g * acc[ai][bj][m][n];
	s_waitcnt lgkmcnt(0)
	v_mfma_f32_16x16x32_bf16 v[108:111], v[128:131], v[144:147], v[108:111]
	v_mfma_f32_16x16x32_bf16 v[76:79], v[136:139], v[144:147], v[76:79]
	v_mfma_f32_16x16x32_bf16 v[104:107], v[128:131], v[152:155], v[104:107]
	v_mfma_f32_16x16x32_bf16 v[72:75], v[136:139], v[152:155], v[72:75]
	v_mfma_f32_16x16x32_bf16 v[100:103], v[128:131], v[160:163], v[100:103]
	v_mfma_f32_16x16x32_bf16 v[68:71], v[136:139], v[160:163], v[68:71]
	v_mfma_f32_16x16x32_bf16 v[96:99], v[128:131], v[178:181], v[96:99]
	v_mfma_f32_16x16x32_bf16 v[64:67], v[136:139], v[178:181], v[64:67]
	v_mfma_f32_16x16x32_bf16 v[108:111], v[132:135], v[148:151], v[108:111]
	v_mfma_f32_16x16x32_bf16 v[76:79], v[140:143], v[148:151], v[76:79]
	v_mfma_f32_16x16x32_bf16 v[104:107], v[132:135], v[156:159], v[104:107]
	v_mfma_f32_16x16x32_bf16 v[72:75], v[140:143], v[156:159], v[72:75]
	v_mfma_f32_16x16x32_bf16 v[100:103], v[132:135], v[174:177], v[100:103]
	v_mfma_f32_16x16x32_bf16 v[68:71], v[140:143], v[174:177], v[68:71]
	v_mfma_f32_16x16x32_bf16 v[96:99], v[132:135], v[182:185], v[96:99]
	v_mfma_f32_16x16x32_bf16 v[64:67], v[140:143], v[182:185], v[64:67]
	s_barrier
	s_add_u32 s4, s8, 0x160080
	s_addc_u32 s5, s9, 0
	s_add_i32 s8, s10, s21
	s_mov_b32 m0, s8
	s_nop 0
	global_load_lds_dwordx4 v164, s[4:5]
	s_add_i32 m0, s8, 0x2000
	s_nop 0
	global_load_lds_dwordx4 v166, s[4:5]
	s_add_i32 s16, s16, 2
	s_add_u32 s14, s14, 0x100
	s_addc_u32 s15, s15, 0
	s_cmpk_gt_u32 s16, 0x55
	s_mov_b64 s[4:5], s[6:7]
	s_waitcnt vmcnt(6)
	s_barrier
	v_mfma_f32_16x16x32_bf16 v[44:47], v[186:189], v[144:147], v[44:47]
	v_mfma_f32_16x16x32_bf16 v[12:15], v[194:197], v[144:147], v[12:15]
	v_mfma_f32_16x16x32_bf16 v[40:43], v[186:189], v[152:155], v[40:43]
	v_mfma_f32_16x16x32_bf16 v[8:11], v[194:197], v[152:155], v[8:11]
	v_mfma_f32_16x16x32_bf16 v[36:39], v[186:189], v[160:163], v[36:39]
	v_mfma_f32_16x16x32_bf16 v[4:7], v[194:197], v[160:163], v[4:7]
	v_mfma_f32_16x16x32_bf16 v[32:35], v[186:189], v[178:181], v[32:35]
	v_mfma_f32_16x16x32_bf16 v[0:3], v[194:197], v[178:181], v[0:3]
	v_mfma_f32_16x16x32_bf16 v[44:47], v[190:193], v[148:151], v[44:47]
	v_mfma_f32_16x16x32_bf16 v[12:15], v[202:205], v[148:151], v[12:15]
	v_mfma_f32_16x16x32_bf16 v[40:43], v[190:193], v[156:159], v[40:43]
	v_mfma_f32_16x16x32_bf16 v[8:11], v[202:205], v[156:159], v[8:11]
	v_mfma_f32_16x16x32_bf16 v[36:39], v[190:193], v[174:177], v[36:39]
	v_mfma_f32_16x16x32_bf16 v[4:7], v[202:205], v[174:177], v[4:7]
	v_mfma_f32_16x16x32_bf16 v[32:35], v[190:193], v[182:185], v[32:35]
	v_mfma_f32_16x16x32_bf16 v[0:3], v[202:205], v[182:185], v[0:3]
	s_barrier
	s_cbranch_scc0 .LBB0_3113
	s_lshl_b32 s8, s13, 21
	s_lshl_b32 s9, s12, 10
	s_lshr_b32 s16, s13, 4
	s_add_u32 s8, s8, s9
	s_mul_i32 s16, s16, 6
	s_add_i32 s16, s16, 35
	s_lshl_b32 s16, s16, 13
	s_add_u32 s16, s16, s9
	s_add_u32 s10, s26, s16
	s_addc_u32 s11, s27, 0
	s_add_u32 s6, s24, s8
	s_addc_u32 s7, s25, 0
	v_lshrrev_b32_e32 v224, 6, v206
	v_and_b32_e32 v225, 3, v224
	v_lshrrev_b32_e32 v224, 2, v224
	v_and_b32_e32 v205, 15, v206
	v_bfe_u32 v226, v206, 4, 2
	v_lshl_add_u32 v225, v225, 3, v226
	v_lshl_add_u32 v224, v224, 6, v205
	v_lshlrev_b32_e32 v205, 4, v225
	v_lshl_add_u32 v203, v224, 13, v205
	v_mov_b32_e32 v204, v203
	global_load_dwordx4 v[128:131], v205, s[10:11] offset:0
	global_load_dwordx4 v[132:135], v205, s[10:11] offset:64
	global_load_dwordx4 v[136:139], v205, s[10:11] offset:512
	global_load_dwordx4 v[140:143], v205, s[10:11] offset:576
	global_load_dwordx4 v[144:147], v203, s[6:7] offset:0
	global_load_dwordx4 v[148:151], v203, s[6:7] offset:64
	global_load_dwordx4 v[152:155], v203, s[6:7] offset:512
	global_load_dwordx4 v[156:159], v203, s[6:7] offset:576
	v_add_u32_e32 v203, 0x20000, v203
	global_load_dwordx4 v[160:163], v203, s[6:7] offset:0
	global_load_dwordx4 v[174:177], v203, s[6:7] offset:64
	global_load_dwordx4 v[178:181], v203, s[6:7] offset:512
	global_load_dwordx4 v[182:185], v203, s[6:7] offset:576
	v_add_u32_e32 v203, 0x20000, v203
	global_load_dwordx4 v[186:189], v203, s[6:7] offset:0
	global_load_dwordx4 v[190:193], v203, s[6:7] offset:64
	global_load_dwordx4 v[194:197], v203, s[6:7] offset:512
	global_load_dwordx4 v[208:211], v203, s[6:7] offset:576
	v_add_u32_e32 v203, 0x20000, v203
	global_load_dwordx4 v[212:215], v203, s[6:7] offset:0
	global_load_dwordx4 v[216:219], v203, s[6:7] offset:64
	global_load_dwordx4 v[220:223], v203, s[6:7] offset:512
	global_load_dwordx4 v[224:227], v203, s[6:7] offset:576
	v_add_u32_e32 v203, 0xa0000, v203
	s_waitcnt vmcnt(12)
	v_pk_fma_f32 v[124:125], v[124:125], v[128:129], v[144:145]
	v_pk_fma_f32 v[126:127], v[126:127], v[130:131], v[146:147]
	v_pk_fma_f32 v[92:93], v[92:93], v[132:133], v[148:149]
	v_pk_fma_f32 v[94:95], v[94:95], v[134:135], v[150:151]
	v_pk_fma_f32 v[60:61], v[60:61], v[136:137], v[152:153]
	v_pk_fma_f32 v[62:63], v[62:63], v[138:139], v[154:155]
	v_pk_fma_f32 v[28:29], v[28:29], v[140:141], v[156:157]
	v_pk_fma_f32 v[30:31], v[30:31], v[142:143], v[158:159]
	global_store_dwordx4 v204, v[124:127], s[6:7] offset:0
	global_store_dwordx4 v204, v[92:95], s[6:7] offset:64
	global_store_dwordx4 v204, v[60:63], s[6:7] offset:512
	global_store_dwordx4 v204, v[28:31], s[6:7] offset:576
	v_add_u32_e32 v204, 0x20000, v204
	global_load_dwordx4 v[144:147], v203, s[6:7] offset:0
	global_load_dwordx4 v[148:151], v203, s[6:7] offset:64
	global_load_dwordx4 v[152:155], v203, s[6:7] offset:512
	global_load_dwordx4 v[156:159], v203, s[6:7] offset:576
	v_add_u32_e32 v203, 0x20000, v203
	s_waitcnt vmcnt(16)
; DI void epi_resid(const Acc& acc, const P& p, int brow, int bcol, int layer, int gch, bool from_input) {
;     ...
; #pragma unroll
;             for (int ai = 0; ai < 2; ++ai)
; #pragma unroll
;                 for (int m = 0; m < 4; ++m) {
;                     const int r = brow + ai * 128 + wr * 64 + m * 16 + fr;
;                     *(f32x4*)(xrow(p, r) + c0) = xv[ai][m] + g * acc[ai][bj][m][n];
;                 }
;             __builtin_amdgcn_sched_barrier(0);
;         }
	v_pk_fma_f32 v[120:121], v[120:121], v[128:129], v[160:161]
	v_pk_fma_f32 v[122:123], v[122:123], v[130:131], v[162:163]
	v_pk_fma_f32 v[88:89], v[88:89], v[132:133], v[174:175]
	v_pk_fma_f32 v[90:91], v[90:91], v[134:135], v[176:177]
	v_pk_fma_f32 v[56:57], v[56:57], v[136:137], v[178:179]
	v_pk_fma_f32 v[58:59], v[58:59], v[138:139], v[180:181]
	v_pk_fma_f32 v[24:25], v[24:25], v[140:141], v[182:183]
	v_pk_fma_f32 v[26:27], v[26:27], v[142:143], v[184:185]
	global_store_dwordx4 v204, v[120:123], s[6:7] offset:0
	global_store_dwordx4 v204, v[88:91], s[6:7] offset:64
	global_store_dwordx4 v204, v[56:59], s[6:7] offset:512
	global_store_dwordx4 v204, v[24:27], s[6:7] offset:576
	v_add_u32_e32 v204, 0x20000, v204
	global_load_dwordx4 v[160:163], v203, s[6:7] offset:0
	global_load_dwordx4 v[174:177], v203, s[6:7] offset:64
	global_load_dwordx4 v[178:181], v203, s[6:7] offset:512
	global_load_dwordx4 v[182:185], v203, s[6:7] offset:576
	v_add_u32_e32 v203, 0x20000, v203
	s_waitcnt vmcnt(20)
	v_pk_fma_f32 v[116:117], v[116:117], v[128:129], v[186:187]
	v_pk_fma_f32 v[118:119], v[118:119], v[130:131], v[188:189]
	v_pk_fma_f32 v[84:85], v[84:85], v[132:133], v[190:191]
	v_pk_fma_f32 v[86:87], v[86:87], v[134:135], v[192:193]
	v_pk_fma_f32 v[52:53], v[52:53], v[136:137], v[194:195]
	v_pk_fma_f32 v[54:55], v[54:55], v[138:139], v[196:197]
	v_pk_fma_f32 v[20:21], v[20:21], v[140:141], v[208:209]
	v_pk_fma_f32 v[22:23], v[22:23], v[142:143], v[210:211]
	global_store_dwordx4 v204, v[116:119], s[6:7] offset:0
	global_store_dwordx4 v204, v[84:87], s[6:7] offset:64
	global_store_dwordx4 v204, v[52:55], s[6:7] offset:512
	global_store_dwordx4 v204, v[20:23], s[6:7] offset:576
	v_add_u32_e32 v204, 0x20000, v204
	global_load_dwordx4 v[186:189], v203, s[6:7] offset:0
	global_load_dwordx4 v[190:193], v203, s[6:7] offset:64
	global_load_dwordx4 v[194:197], v203, s[6:7] offset:512
	global_load_dwordx4 v[208:211], v203, s[6:7] offset:576
	v_add_u32_e32 v203, 0x20000, v203
	s_waitcnt vmcnt(24)
	v_pk_fma_f32 v[112:113], v[112:113], v[128:129], v[212:213]
	v_pk_fma_f32 v[114:115], v[114:115], v[130:131], v[214:215]
	v_pk_fma_f32 v[80:81], v[80:81], v[132:133], v[216:217]
	v_pk_fma_f32 v[82:83], v[82:83], v[134:135], v[218:219]
	v_pk_fma_f32 v[48:49], v[48:49], v[136:137], v[220:221]
	v_pk_fma_f32 v[50:51], v[50:51], v[138:139], v[222:223]
	v_pk_fma_f32 v[16:17], v[16:17], v[140:141], v[224:225]
	v_pk_fma_f32 v[18:19], v[18:19], v[142:143], v[226:227]
	global_store_dwordx4 v204, v[112:115], s[6:7] offset:0
	global_store_dwordx4 v204, v[80:83], s[6:7] offset:64
	global_store_dwordx4 v204, v[48:51], s[6:7] offset:512
	global_store_dwordx4 v204, v[16:19], s[6:7] offset:576
	v_add_u32_e32 v204, 0xa0000, v204
	global_load_dwordx4 v[212:215], v203, s[6:7] offset:0
	global_load_dwordx4 v[216:219], v203, s[6:7] offset:64
	global_load_dwordx4 v[220:223], v203, s[6:7] offset:512
	global_load_dwordx4 v[224:227], v203, s[6:7] offset:576
	s_waitcnt vmcnt(24)
	v_pk_fma_f32 v[108:109], v[108:109], v[128:129], v[144:145]
	v_pk_fma_f32 v[110:111], v[110:111], v[130:131], v[146:147]
	v_pk_fma_f32 v[76:77], v[76:77], v[132:133], v[148:149]
	v_pk_fma_f32 v[78:79], v[78:79], v[134:135], v[150:151]
	v_pk_fma_f32 v[44:45], v[44:45], v[136:137], v[152:153]
	v_pk_fma_f32 v[46:47], v[46:47], v[138:139], v[154:155]
	v_pk_fma_f32 v[12:13], v[12:13], v[140:141], v[156:157]
	v_pk_fma_f32 v[14:15], v[14:15], v[142:143], v[158:159]
	global_store_dwordx4 v204, v[108:111], s[6:7] offset:0
	global_store_dwordx4 v204, v[76:79], s[6:7] offset:64
	global_store_dwordx4 v204, v[44:47], s[6:7] offset:512
	global_store_dwordx4 v204, v[12:15], s[6:7] offset:576
	v_add_u32_e32 v204, 0x20000, v204
	s_waitcnt vmcnt(20)
	v_pk_fma_f32 v[104:105], v[104:105], v[128:129], v[160:161]
	v_pk_fma_f32 v[106:107], v[106:107], v[130:131], v[162:163]
	v_pk_fma_f32 v[72:73], v[72:73], v[132:133], v[174:175]
	v_pk_fma_f32 v[74:75], v[74:75], v[134:135], v[176:177]
	v_pk_fma_f32 v[40:41], v[40:41], v[136:137], v[178:179]
	v_pk_fma_f32 v[42:43], v[42:43], v[138:139], v[180:181]
	v_pk_fma_f32 v[8:9], v[8:9], v[140:141], v[182:183]
	v_pk_fma_f32 v[10:11], v[10:11], v[142:143], v[184:185]
	global_store_dwordx4 v204, v[104:107], s[6:7] offset:0
	global_store_dwordx4 v204, v[72:75], s[6:7] offset:64
	global_store_dwordx4 v204, v[40:43], s[6:7] offset:512
	global_store_dwordx4 v204, v[8:11], s[6:7] offset:576
	v_add_u32_e32 v204, 0x20000, v204
	s_waitcnt vmcnt(16)
	v_pk_fma_f32 v[100:101], v[100:101], v[128:129], v[186:187]
	v_pk_fma_f32 v[102:103], v[102:103], v[130:131], v[188:189]
	v_pk_fma_f32 v[68:69], v[68:69], v[132:133], v[190:191]
	v_pk_fma_f32 v[70:71], v[70:71], v[134:135], v[192:193]
	v_pk_fma_f32 v[36:37], v[36:37], v[136:137], v[194:195]
	v_pk_fma_f32 v[38:39], v[38:39], v[138:139], v[196:197]
	v_pk_fma_f32 v[4:5], v[4:5], v[140:141], v[208:209]
	v_pk_fma_f32 v[6:7], v[6:7], v[142:143], v[210:211]
	global_store_dwordx4 v204, v[100:103], s[6:7] offset:0
	global_store_dwordx4 v204, v[68:71], s[6:7] offset:64
	global_store_dwordx4 v204, v[36:39], s[6:7] offset:512
	global_store_dwordx4 v204, v[4:7], s[6:7] offset:576
	v_add_u32_e32 v204, 0x20000, v204
	s_waitcnt vmcnt(12)
	v_pk_fma_f32 v[96:97], v[96:97], v[128:129], v[212:213]
	v_pk_fma_f32 v[98:99], v[98:99], v[130:131], v[214:215]
	v_pk_fma_f32 v[64:65], v[64:65], v[132:133], v[216:217]
	v_pk_fma_f32 v[66:67], v[66:67], v[134:135], v[218:219]
	v_pk_fma_f32 v[32:33], v[32:33], v[136:137], v[220:221]
	v_pk_fma_f32 v[34:35], v[34:35], v[138:139], v[222:223]
	v_pk_fma_f32 v[0:1], v[0:1], v[140:141], v[224:225]
	v_pk_fma_f32 v[2:3], v[2:3], v[142:143], v[226:227]
	global_store_dwordx4 v204, v[96:99], s[6:7] offset:0
	global_store_dwordx4 v204, v[64:67], s[6:7] offset:64
	global_store_dwordx4 v204, v[32:35], s[6:7] offset:512
	global_store_dwordx4 v204, v[0:3], s[6:7] offset:576
	s_branch .Lresid_latch_ffndL1
